# pc_phase: next item's 91 input loads software-prefetched during the current item's t-loop (in-place for rows -1..8, shadow regs for rows 9..15 + constants); first vmcnt(0) of item prologue removed
# baseline (speedup 1.0000x reference)
; __device__ __forceinline__ void pc_phase(LAS unsigned char* lds, const bf16* Pp_, const bf16* LO, const float* mu, const float* w0, const float* a0, const float* k_k, const float* k_a, const float* r_k, ...
;     ...
;         for (int t = 0; t < 16; ++t) {
;             const float r0 = bf2f(sr_[t + 1]), k0 = bf2f(sk_[t + 1]), v0 = bf2f(sv_[t + 1]);
;             const float r = r0 + (r1 - r0) * mu_r, k = k0 + (k1 - k0) * mu_k, v = v0 + (v1 - v0) * mu_v; r1 = r0; k1 = k0; v1 = v0;
;             const float z = -(w0c + bf2f(slw[t])); const float sp = fmaxf(z, 0.f) + flog(1.0f + fexp(-fabsf(z))); const float w = -sp - 0.5f;
;             const float dec = fexp(-fexp(w)); const float a = fsigmoid(a0c + bf2f(sla[t]));
;             float kk = k * kkc; const float n2 = wsum_dpp(kk * kk); kk = kk / fmaxf(sqrtf(n2), 1e-12f);
;             const float kp = bf2f(f2bf(k * (1.0f + (a - 1.0f) * kac))), bb = bf2f(f2bf(kk * a)), rr = bf2f(f2bf(r)); kk = bf2f(f2bf(kk));
;             const float coef = wsum_dpp(rr * kp * rkc);
;             SV[(ib + t) * 64 + lane] = f2bf(v);
;             if (lane == 0) COEF[(size_t)(m0 + t) * 16 + h] = coef;
;             const float Pp = P; P *= dec; const float inv = 1.0f / P;
;             XKK[t * 72 + lane] = f2bf(kk * Pp); XR[t * 72 + lane] = f2bf(rr * P); XK[t * 72 + lane] = f2bf(kp * inv); XB[t * 72 + lane] = f2bf(bb * inv); }
;         PCL[lane] = P;
;         PC_FENCE();
;         { f32x4 akb = zero, akk = zero, ark = zero, arb = zero;
; #pragma unroll
;           for (int ks = 0; ks < 2; ++ks) { const int o = m * 72 + 32 * ks + 8 * g;
;               const bf16x8 fkk = *(const LAS bf16x8*)(XKK + o), fr = *(const LAS bf16x8*)(XR + o), fk = *(const LAS bf16x8*)(XK + o), fb = *(const LAS bf16x8*)(XB + o);
;               akb = __builtin_amdgcn_mfma_f32_16x16x32_bf16(fkk, fb, akb, 0, 0, 0); akk = __builtin_amdgcn_mfma_f32_16x16x32_bf16(fkk, fk, akk, 0, 0, 0);
;               ark = __builtin_amdgcn_mfma_f32_16x16x32_bf16(fr, fk, ark, 0, 0, 0); arb = __builtin_amdgcn_mfma_f32_16x16x32_bf16(fr, fb, arb, 0, 0, 0); }
; #pragma unroll
;           for (int r = 0; r < 4; ++r) { const int i = 4 * g + r, j = m;
;               AKB[i * 20 + j] = (j < i) ? akb[r] : 0.f; AKK[i * 17 + j] = (j < i) ? akk[r] : 0.f; ARK[i * 17 + j] = (j <= i) ? ark[r] : 0.f; ARB[i * 17 + j] = (j <= i) ? arb[r] : 0.f; } }
;         PC_FENCE();
.LBB0_280:
	s_or_b64 exec, exec, s[4:5]
	s_add_i32 s0, s11, s16
	s_cmpk_gt_i32 s0, 0x3fff
	s_cbranch_scc1 .Lpcpf_skip_15
	s_movk_i32 s0, 0x3400
	s_mov_b32 s1, 0
	v_lshl_add_u64 v[146:147], v[146:147], 0, s[0:1]
	s_movk_i32 s0, 0x1800
	v_lshl_add_u64 v[148:149], v[148:149], 0, s[0:1]
	global_load_ushort v204, v[146:147], off offset:-2048
	global_load_ushort v205, v[146:147], off
	global_load_ushort v208, v[146:147], off offset:2048
	global_load_ushort v209, v[148:149], off
	global_load_ushort v210, v[148:149], off offset:2048
.Lpcpf_skip_15:
	v_lshlrev_b32_e32 v6, 16, v16
	v_add_f32_e32 v6, v8, v6
	v_mul_f32_e64 v7, |v6|, s19
	v_exp_f32_e32 v7, v7
	v_mov_b32_e32 v8, s9
	v_mov_b32_e32 v11, s8
	v_add_f32_e32 v8, s7, v8
	v_add_f32_e32 v7, 1.0, v7
	v_log_f32_e32 v7, v7
	v_add_f32_e32 v11, s6, v11
	v_max_f32_e64 v6, -v6, 0
	v_add_f32_e32 v8, v8, v11
	v_fmac_f32_e32 v6, 0x3f317218, v7
	v_cmp_gt_f32_e32 vcc, s33, v8
	v_mul_f32_e32 v7, 0x4f800000, v8
	v_sub_f32_e32 v6, -0.5, v6
	v_cndmask_b32_e32 v7, v8, v7, vcc
	v_sqrt_f32_e32 v8, v7
	v_mul_f32_e32 v6, 0x3fb8aa3b, v6
	v_exp_f32_e32 v6, v6
	v_mov_b32_e32 v76, s28
	v_add_u32_e32 v11, -1, v8
	v_fma_f32 v13, -v11, v8, v7
	v_cmp_ge_f32_e64 s[56:57], 0, v13
	v_add_u32_e32 v13, 1, v8
	v_mul_f32_e32 v6, 0xbfb8aa3b, v6
	v_cndmask_b32_e64 v11, v8, v11, s[56:57]
	v_fma_f32 v8, -v13, v8, v7
	v_cmp_lt_f32_e64 s[56:57], 0, v8
	v_exp_f32_e32 v6, v6
	s_add_i32 s11, s11, s16
	v_cndmask_b32_e64 v8, v11, v13, s[56:57]
	v_mul_f32_e32 v11, 0x37800000, v8
	v_cndmask_b32_e32 v8, v8, v11, vcc
	v_cmp_class_f32_e32 vcc, v7, v219
	v_mul_f32_e32 v61, v21, v6
	s_cmpk_gt_i32 s11, 0x3fff
	v_cndmask_b32_e32 v7, v8, v7, vcc
	v_max_f32_e32 v7, 0x2b8cbccc, v7
	v_div_scale_f32 v8, s[0:1], v7, v7, v14
	v_rcp_f32_e32 v11, v8
	s_nop 0
	v_fma_f32 v13, -v8, v11, 1.0
	v_fmac_f32_e32 v11, v13, v11
	v_div_scale_f32 v13, vcc, v14, v7, v14
	v_mul_f32_e32 v15, v13, v11
	v_fma_f32 v16, -v8, v15, v13
	v_fmac_f32_e32 v15, v16, v11
	v_fma_f32 v8, -v8, v15, v13
	v_div_fmas_f32 v8, v8, v11, v15
	v_div_fixup_f32 v7, v8, v7, v14
	v_mul_f32_e32 v8, v12, v7
	v_cvt_pk_bf16_f32 v8, v8, s0
	v_div_scale_f32 v6, s[0:1], v61, v61, 1.0
	v_rcp_f32_e32 v11, v6
	s_nop 0
	v_cvt_pk_bf16_f32 v7, v7, s0
	v_lshlrev_b32_e32 v7, 16, v7
	v_mul_f32_e32 v7, v21, v7
	v_fma_f32 v12, -v6, v11, 1.0
	v_fmac_f32_e32 v11, v12, v11
	v_div_scale_f32 v12, vcc, 1.0, v61, 1.0
	v_mul_f32_e32 v13, v12, v11
	v_fma_f32 v14, -v6, v13, v12
	v_fmac_f32_e32 v13, v14, v11
	v_fma_f32 v6, -v6, v13, v12
	v_cvt_pk_bf16_f32 v7, v7, s0
	v_div_fmas_f32 v6, v6, v11, v13
	ds_write_b16 v27, v7 offset:2160
	v_mul_f32_e32 v7, v61, v10
	v_lshlrev_b32_e32 v8, 16, v8
	v_div_fixup_f32 v6, v6, v61, 1.0
	v_cvt_pk_bf16_f32 v7, v7, s0
	ds_write_b16 v27, v7 offset:4464
	v_mul_f32_e32 v7, v6, v9
	v_mul_f32_e32 v6, v6, v8
	v_cvt_pk_bf16_f32 v7, v7, s0
	v_cvt_pk_bf16_f32 v6, v6, s0
	ds_write_b16 v27, v7 offset:6768
	ds_write_b16 v27, v6 offset:9072
	ds_write_b32 v22, v61 offset:15936
	s_waitcnt lgkmcnt(0)
	ds_read_b128 v[6:9], v28
	ds_read_b128 v[10:13], v28 offset:6912
	ds_read_b128 v[62:65], v28 offset:2304
	ds_read_b128 v[66:69], v28 offset:64
	ds_read_b128 v[18:21], v28 offset:4608
	ds_read_b128 v[70:73], v28 offset:4672
	s_waitcnt lgkmcnt(0)
	v_mfma_f32_16x16x32_bf16 v[14:17], v[6:9], v[10:13], 0
	v_readlane_b32 s0, v255, 28
	v_readlane_b32 s1, v255, 29
	v_mfma_f32_16x16x32_bf16 v[6:9], v[6:9], v[18:21], 0
	v_mfma_f32_16x16x32_bf16 v[18:21], v[62:65], v[18:21], 0
	v_mfma_f32_16x16x32_bf16 v[10:13], v[62:65], v[10:13], 0
	ds_read_b128 v[62:65], v28 offset:6976
	s_waitcnt lgkmcnt(0)
	v_mfma_f32_16x16x32_bf16 v[14:17], v[66:69], v[62:65], v[14:17]
	v_mfma_f32_16x16x32_bf16 v[6:9], v[66:69], v[70:73], v[6:9]
	ds_read_b128 v[66:69], v28 offset:2368
	s_nop 5
	v_cndmask_b32_e64 v14, 0, v14, s[0:1]
	ds_write_b32 v59, v14 offset:9216
	s_waitcnt lgkmcnt(0)
	v_mfma_f32_16x16x32_bf16 v[18:21], v[66:69], v[70:73], v[18:21]
	v_cndmask_b32_e64 v6, 0, v6, s[0:1]
	ds_write_b32 v30, v6 offset:10496
	v_readlane_b32 s0, v255, 30
	v_mfma_f32_16x16x32_bf16 v[10:13], v[66:69], v[62:65], v[10:13]
	s_nop 3
	v_cndmask_b32_e64 v6, v18, 0, s[42:43]
	ds_write_b32 v30, v6 offset:11584
	v_readlane_b32 s1, v255, 31
	s_nop 0
	v_cndmask_b32_e64 v6, v10, 0, s[42:43]
	ds_write_b32 v30, v6 offset:12672
	v_cndmask_b32_e64 v6, v15, 0, s[42:43]
	ds_write_b32 v60, v6 offset:9216
	v_cndmask_b32_e64 v6, v7, 0, s[42:43]
	ds_write_b32 v31, v6 offset:10496
	v_cndmask_b32_e64 v6, v19, 0, s[0:1]
	ds_write_b32 v31, v6 offset:11584
	v_cndmask_b32_e64 v6, v11, 0, s[0:1]
	v_readlane_b32 s0, v255, 32
	v_readlane_b32 s1, v255, 33
	ds_write_b32 v31, v6 offset:12672
	s_nop 0
	v_cndmask_b32_e64 v6, 0, v16, s[0:1]
	ds_write_b32 v60, v6 offset:9296
	v_cndmask_b32_e64 v6, 0, v8, s[0:1]
	v_readlane_b32 s0, v255, 34
	v_readlane_b32 s1, v255, 35
	ds_write_b32 v32, v6 offset:10496
	s_nop 0
	v_cndmask_b32_e64 v6, v20, 0, s[0:1]
	ds_write_b32 v32, v6 offset:11584
	v_cndmask_b32_e64 v6, v12, 0, s[0:1]
	v_readlane_b32 s0, v255, 36
	v_readlane_b32 s1, v255, 37
	ds_write_b32 v32, v6 offset:12672
	s_nop 0
	v_cndmask_b32_e64 v6, 0, v17, s[0:1]
	ds_write_b32 v60, v6 offset:9376
	v_cndmask_b32_e64 v6, 0, v9, s[0:1]
	s_mov_b64 s[0:1], s[46:47]
	ds_write_b32 v33, v6 offset:10496
	v_cndmask_b32_e64 v6, v21, 0, s[0:1]
	ds_write_b32 v33, v6 offset:11584
	v_cndmask_b32_e64 v6, v13, 0, s[0:1]
	ds_write_b32 v33, v6 offset:12672
	s_waitcnt lgkmcnt(0)
	ds_read_b128 v[6:9], v76 offset:9296
	s_waitcnt lgkmcnt(0)
	ds_read_b128 v[8:11], v76 offset:9376
	s_waitcnt lgkmcnt(0)
; #define LAS __attribute__((address_space(3)))
; __device__ __forceinline__ void pc_phase(LAS unsigned char* lds, const bf16* Pp_, const bf16* LO, const float* mu, const float* w0, const float* a0, const float* k_k, const float* k_a, const float* r_k, ...
;     ...
;         { const int j = m; float Tc[16]; f32x4 Lc[4], Ln[4];
; #pragma unroll
;           for (int c4 = 0; c4 < 4; ++c4) Lc[c4] = *(const LAS f32x4*)(AKB + 20 + 4 * c4);
;           Tc[0] = (j == 0) ? 1.0f : 0.0f;
; #pragma unroll
;           for (int i = 1; i < 16; ++i) {
;               if (i + 1 < 16) {
; #pragma unroll
;                   for (int c4 = 0; c4 < 4; ++c4) Ln[c4] = *(const LAS f32x4*)(AKB + (i + 1) * 20 + 4 * c4); }
;               float a4[4] = {0.f, 0.f, 0.f, 0.f};
; #pragma unroll
;               for (int mm = 0; mm < i; ++mm) a4[mm & 3] += Lc[mm >> 2][mm & 3] * Tc[mm];
;               Tc[i] = ((i == j) ? 1.0f : 0.0f) - ((a4[0] + a4[1]) + (a4[2] + a4[3]));
; #pragma unroll
;               for (int c4 = 0; c4 < 4; ++c4) Lc[c4] = Ln[c4]; }
	ds_read_b128 v[10:13], v76 offset:9456
	s_mov_b32 s0, 0x27600000
	v_fma_f32 v6, v24, v6, 0
	v_sub_f32_e32 v78, v34, v6
	v_fma_f32 v6, v24, v8, 0
	v_fma_f32 v7, v9, v78, 0
	v_add_f32_e32 v6, v6, v7
	v_sub_f32_e32 v79, v35, v6
	ds_read_b128 v[6:9], v76 offset:9536
	s_waitcnt lgkmcnt(0)
	v_fma_f32 v10, v24, v10, 0
	v_fma_f32 v11, v11, v78, 0
	v_fma_f32 v12, v12, v79, 0
	v_add_f32_e32 v10, v10, v11
	v_add_f32_e32 v10, v10, v12
	v_sub_f32_e32 v80, v36, v10
	ds_read_b128 v[10:13], v76 offset:9616
	ds_read_b128 v[14:17], v76 offset:9632
	v_fma_f32 v6, v24, v6, 0
	v_fma_f32 v7, v78, v7, 0
	v_fma_f32 v8, v8, v79, 0
	v_fma_f32 v9, v9, v80, 0
	v_add_f32_e32 v6, v6, v7
	v_add_f32_e32 v7, v8, v9
	v_add_f32_e32 v6, v6, v7
	v_sub_f32_e32 v81, v37, v6
	ds_read_b128 v[6:9], v76 offset:9696
	s_waitcnt lgkmcnt(0)
	ds_read_b128 v[16:19], v76 offset:9712
	v_fma_f32 v10, v24, v10, 0
	v_fma_f32 v11, v78, v11, 0
	v_fma_f32 v12, v12, v79, 0
	v_fma_f32 v13, v13, v80, 0
	v_fmac_f32_e32 v10, v14, v81
	v_add_f32_e32 v10, v11, v10
	v_add_f32_e32 v11, v12, v13
	v_add_f32_e32 v10, v11, v10
	v_sub_f32_e32 v82, v38, v10
	ds_read_b128 v[10:13], v76 offset:9776
	s_waitcnt lgkmcnt(0)
	ds_read_b128 v[18:21], v76 offset:9792
	v_fma_f32 v6, v24, v6, 0
	v_fma_f32 v7, v78, v7, 0
	v_fma_f32 v8, v8, v79, 0
	v_fma_f32 v9, v9, v80, 0
	v_fmac_f32_e32 v6, v16, v81
	v_fmac_f32_e32 v7, v17, v82
	v_add_f32_e32 v6, v6, v7
	v_add_f32_e32 v7, v8, v9
	v_add_f32_e32 v6, v7, v6
	v_sub_f32_e32 v83, v39, v6
	ds_read_b128 v[6:9], v76 offset:9856
	ds_read_b128 v[14:17], v76 offset:9872
	v_fma_f32 v10, v24, v10, 0
	v_fma_f32 v11, v78, v11, 0
	v_fma_f32 v12, v79, v12, 0
	v_fma_f32 v13, v13, v80, 0
	s_waitcnt lgkmcnt(0)
	v_fmac_f32_e32 v10, v18, v81
	v_fmac_f32_e32 v11, v19, v82
	v_fmac_f32_e32 v12, v20, v83
	v_add_f32_e32 v10, v10, v11
	v_add_f32_e32 v11, v13, v12
	v_add_f32_e32 v10, v10, v11
	v_sub_f32_e32 v84, v40, v10
	ds_read_b128 v[10:13], v76 offset:9936
	ds_read_b128 v[18:21], v76 offset:9952
	ds_read_b128 v[62:65], v76 offset:9968
	v_fma_f32 v6, v24, v6, 0
	v_fma_f32 v7, v78, v7, 0
	v_fma_f32 v8, v79, v8, 0
	v_fma_f32 v9, v9, v80, 0
	v_fmac_f32_e32 v6, v14, v81
	v_fmac_f32_e32 v7, v15, v82
	v_fmac_f32_e32 v8, v16, v83
	v_fmac_f32_e32 v9, v17, v84
	v_add_f32_e32 v6, v6, v7
	v_add_f32_e32 v7, v8, v9
	v_add_f32_e32 v6, v6, v7
	s_waitcnt lgkmcnt(0)
	v_fma_f32 v10, v24, v10, 0
	v_sub_f32_e32 v85, v41, v6
	ds_read_b128 v[6:9], v76 offset:10016
	ds_read_b128 v[14:17], v76 offset:10032
	ds_read_b128 v[64:67], v76 offset:10048
	v_fma_f32 v11, v78, v11, 0
	v_fma_f32 v12, v79, v12, 0
	v_fma_f32 v13, v80, v13, 0
	v_fmac_f32_e32 v10, v18, v81
	v_fmac_f32_e32 v11, v19, v82
	v_fmac_f32_e32 v12, v20, v83
	v_fmac_f32_e32 v13, v21, v84
	v_fmac_f32_e32 v10, v62, v85
	v_add_f32_e32 v10, v11, v10
	v_add_f32_e32 v11, v12, v13
	v_add_f32_e32 v10, v11, v10
	s_waitcnt lgkmcnt(0)
	v_fma_f32 v6, v24, v6, 0
	v_fma_f32 v7, v78, v7, 0
	v_sub_f32_e32 v86, v42, v10
	ds_read_b128 v[10:13], v76 offset:10096
	ds_read_b128 v[18:21], v76 offset:10112
	ds_read_b128 v[66:69], v76 offset:10128
	v_fma_f32 v8, v79, v8, 0
	v_fma_f32 v9, v80, v9, 0
	v_fmac_f32_e32 v6, v81, v14
	v_fmac_f32_e32 v7, v15, v82
	v_fmac_f32_e32 v8, v16, v83
	v_fmac_f32_e32 v9, v17, v84
	v_fmac_f32_e32 v6, v64, v85
	v_fmac_f32_e32 v7, v65, v86
	v_add_f32_e32 v6, v6, v7
	v_add_f32_e32 v7, v8, v9
	v_add_f32_e32 v6, v7, v6
	s_waitcnt lgkmcnt(0)
	v_fma_f32 v10, v24, v10, 0
	v_fma_f32 v11, v78, v11, 0
	v_fma_f32 v12, v79, v12, 0
	v_sub_f32_e32 v87, v43, v6
	ds_read_b128 v[6:9], v76 offset:10176
	ds_read_b128 v[14:17], v76 offset:10192
	ds_read_b128 v[62:65], v76 offset:10208
	v_fma_f32 v13, v80, v13, 0
	v_fmac_f32_e32 v10, v81, v18
	v_fmac_f32_e32 v11, v19, v82
	v_fmac_f32_e32 v12, v20, v83
	v_fmac_f32_e32 v13, v21, v84
	v_fmac_f32_e32 v10, v66, v85
	v_fmac_f32_e32 v11, v67, v86
	v_fmac_f32_e32 v12, v68, v87
	v_add_f32_e32 v10, v10, v11
	v_add_f32_e32 v11, v13, v12
	v_add_f32_e32 v10, v10, v11
	s_waitcnt lgkmcnt(0)
	v_fma_f32 v6, v24, v6, 0
	v_fma_f32 v7, v78, v7, 0
	v_fma_f32 v8, v79, v8, 0
	v_fma_f32 v9, v80, v9, 0
	v_sub_f32_e32 v88, v44, v10
	ds_read_b128 v[10:13], v76 offset:10256
	ds_read_b128 v[18:21], v76 offset:10272
	ds_read_b128 v[66:69], v76 offset:10288
	ds_read_b128 v[70:73], v76 offset:10304
	v_fmac_f32_e32 v6, v81, v14
	v_fmac_f32_e32 v7, v82, v15
	v_fmac_f32_e32 v8, v16, v83
	v_fmac_f32_e32 v9, v17, v84
	v_fmac_f32_e32 v6, v62, v85
	v_fmac_f32_e32 v7, v63, v86
	v_fmac_f32_e32 v8, v64, v87
	v_fmac_f32_e32 v9, v65, v88
	v_add_f32_e32 v6, v6, v7
	v_add_f32_e32 v7, v8, v9
	s_waitcnt lgkmcnt(0)
	v_fma_f32 v10, v24, v10, 0
	v_add_f32_e32 v6, v6, v7
	v_fma_f32 v11, v78, v11, 0
	v_fma_f32 v12, v79, v12, 0
	v_fma_f32 v13, v80, v13, 0
	v_fmac_f32_e32 v10, v81, v18
	v_sub_f32_e32 v71, v45, v6
	ds_read_b128 v[6:9], v76 offset:10336
	ds_read_b128 v[14:17], v76 offset:10352
	ds_read_b128 v[62:65], v76 offset:10368
	ds_read_b128 v[72:75], v76 offset:10384
	v_fmac_f32_e32 v11, v82, v19
	v_fmac_f32_e32 v12, v20, v83
	v_fmac_f32_e32 v13, v21, v84
	v_fmac_f32_e32 v10, v66, v85
	v_fmac_f32_e32 v11, v67, v86
	v_fmac_f32_e32 v12, v68, v87
	v_fmac_f32_e32 v13, v69, v88
	v_fmac_f32_e32 v10, v70, v71
	v_add_f32_e32 v10, v11, v10
	v_add_f32_e32 v11, v12, v13
	s_waitcnt lgkmcnt(0)
	v_fma_f32 v6, v24, v6, 0
	v_fma_f32 v7, v78, v7, 0
	v_add_f32_e32 v10, v11, v10
	v_fmac_f32_e32 v6, v81, v14
	v_fmac_f32_e32 v7, v82, v15
	v_sub_f32_e32 v70, v46, v10
	v_fmac_f32_e32 v6, v62, v85
	v_fmac_f32_e32 v7, v63, v86
	v_fmac_f32_e32 v6, v72, v71
	v_fmac_f32_e32 v7, v73, v70
	v_add_f32_e32 v6, v6, v7
	v_fma_f32 v7, v79, v8, 0
	v_fma_f32 v8, v80, v9, 0
	v_fmac_f32_e32 v7, v83, v16
	v_fmac_f32_e32 v8, v17, v84
	ds_read_b128 v[10:13], v76 offset:10416
	ds_read_b128 v[18:21], v76 offset:10432
	ds_read_b128 v[66:69], v76 offset:10448
	ds_read_b128 v[74:77], v76 offset:10464
	v_fmac_f32_e32 v7, v64, v87
	v_fmac_f32_e32 v8, v65, v88
	v_add_f32_e32 v7, v7, v8
	v_add_f32_e32 v6, v7, v6
	s_waitcnt lgkmcnt(0)
; #define PC_FENCE() asm volatile("s_waitcnt lgkmcnt(0)" ::: "memory")
; __device__ __forceinline__ void pc_phase(LAS unsigned char* lds, const bf16* Pp_, const bf16* LO, const float* mu, const float* w0, const float* a0, const float* k_k, const float* k_a, const float* r_k, ...
;     ...
;               for (int mm = 0; mm < i; ++mm) a4[mm & 3] += Lc[mm >> 2][mm & 3] * Tc[mm];
;               Tc[i] = ((i == j) ? 1.0f : 0.0f) - ((a4[0] + a4[1]) + (a4[2] + a4[3]));
; #pragma unroll
;               for (int c4 = 0; c4 < 4; ++c4) Lc[c4] = Ln[c4]; }
; #pragma unroll
;           for (int i = 0; i < 16; ++i) TT[i * 17 + j] = Tc[i]; }
;         PC_FENCE();
; #pragma unroll
;         for (int q = 0; q < 4; ++q) { const int i = g + 4 * q, j = m; float acc = 0.f;
; #pragma unroll
;             for (int mm = 0; mm < 16; ++mm) acc += TT[i * 17 + mm] * AKK[mm * 17 + j];
;             M1[i * 17 + j] = acc; }
	v_fma_f32 v7, v24, v10, 0
	v_fma_f32 v8, v78, v11, 0
	v_fma_f32 v9, v79, v12, 0
	v_fma_f32 v10, v80, v13, 0
	v_fmac_f32_e32 v7, v81, v18
	v_fmac_f32_e32 v8, v82, v19
	v_fmac_f32_e32 v9, v83, v20
	v_sub_f32_e32 v6, v26, v6
	v_fmac_f32_e32 v10, v84, v21
	v_fmac_f32_e32 v7, v66, v85
	v_fmac_f32_e32 v8, v67, v86
	v_fmac_f32_e32 v9, v68, v87
	v_fmac_f32_e32 v10, v69, v88
	v_fmac_f32_e32 v7, v74, v71
	v_fmac_f32_e32 v8, v75, v70
	v_fmac_f32_e32 v9, v76, v6
	v_add_f32_e32 v7, v7, v8
	v_add_f32_e32 v8, v10, v9
	v_add_f32_e32 v7, v7, v8
	v_add_u32_e32 v8, 0x3400, v23
	ds_write2_b32 v8, v24, v78 offset0:112 offset1:129
	ds_write2_b32 v8, v79, v80 offset0:146 offset1:163
	ds_write2_b32 v8, v81, v82 offset0:180 offset1:197
	ds_write2_b32 v8, v83, v84 offset0:214 offset1:231
	v_add_u32_e32 v8, 0x3600, v23
	ds_write2_b32 v8, v85, v86 offset0:120 offset1:137
	v_add_u32_e32 v8, 0x3800, v23
	v_sub_f32_e32 v7, v47, v7
	ds_write2_b32 v8, v87, v88 offset0:26 offset1:43
	ds_write2_b32 v8, v71, v70 offset0:60 offset1:77
	ds_write2_b32 v8, v6, v7 offset0:94 offset1:111
	v_add_u32_e32 v62, s28, v29
	s_waitcnt lgkmcnt(0)
	v_add_u32_e32 v6, 0x35c0, v62
	v_add_u32_e32 v63, 0x2800, v23
	ds_read2_b32 v[6:7], v6 offset1:1
	ds_read2_b32 v[10:11], v63 offset0:64 offset1:81
	v_add_u32_e32 v8, 0x35c8, v62
	ds_read2_b32 v[8:9], v8 offset1:1
	ds_read2_b32 v[16:17], v63 offset0:98 offset1:115
	v_add_u32_e32 v12, 0x35d8, v62
	v_add_u32_e32 v18, 0x35e0, v62
	s_waitcnt lgkmcnt(0)
	v_fma_f32 v70, v6, v10, 0
	v_fmac_f32_e32 v70, v7, v11
	v_fmac_f32_e32 v70, v8, v16
	v_add_u32_e32 v6, 0x35d0, v62
	v_fmac_f32_e32 v70, v9, v17
	ds_read2_b32 v[8:9], v6 offset1:1
	ds_read2_b32 v[6:7], v63 offset0:132 offset1:149
	ds_read2_b32 v[12:13], v12 offset1:1
	ds_read2_b32 v[14:15], v63 offset0:166 offset1:183
	ds_read2_b32 v[20:21], v18 offset1:1
	ds_read2_b32 v[18:19], v63 offset0:200 offset1:217
	s_waitcnt lgkmcnt(0)
	v_fmac_f32_e32 v70, v8, v6
	v_fmac_f32_e32 v70, v9, v7
	v_add_u32_e32 v8, 0x35e8, v62
	v_fmac_f32_e32 v70, v12, v14
	ds_read2_b32 v[64:65], v8 offset1:1
	ds_read2_b32 v[8:9], v63 offset0:234 offset1:251
	v_fmac_f32_e32 v70, v13, v15
	v_fmac_f32_e32 v70, v20, v18
	v_add_u32_e32 v12, 0x35f0, v62
	v_add_u32_e32 v20, 0x2c00, v23
	ds_read2_b32 v[66:67], v12 offset1:1
	ds_read2_b32 v[12:13], v20 offset0:12 offset1:29
	v_fmac_f32_e32 v70, v21, v19
	v_add_u32_e32 v21, 0x35f8, v62
	s_waitcnt lgkmcnt(0)
	v_fmac_f32_e32 v70, v64, v8
	v_add_u32_e32 v63, 0x36d0, v62
	ds_read2_b32 v[68:69], v21 offset1:1
	ds_read2_b32 v[20:21], v20 offset0:46 offset1:63
	v_fmac_f32_e32 v70, v65, v9
	ds_read2_b32 v[64:65], v63 offset1:1
	v_fmac_f32_e32 v70, v66, v12
	v_add_u32_e32 v66, 0x36d8, v62
	v_fmac_f32_e32 v70, v67, v13
	ds_read2_b32 v[66:67], v66 offset1:1
	s_waitcnt lgkmcnt(0)
	v_fmac_f32_e32 v70, v68, v20
	v_fma_f32 v68, v10, v64, 0
	v_add_u32_e32 v64, 0x36e0, v62
	v_fmac_f32_e32 v68, v11, v65
	ds_read2_b32 v[64:65], v64 offset1:1
	v_fmac_f32_e32 v68, v16, v66
	v_add_u32_e32 v66, 0x36e8, v62
	v_fmac_f32_e32 v68, v17, v67
	ds_read2_b32 v[66:67], v66 offset1:1
	s_waitcnt lgkmcnt(0)
	v_fmac_f32_e32 v68, v6, v64
	v_add_u32_e32 v64, 0x36f0, v62
	v_fmac_f32_e32 v68, v7, v65
	ds_read2_b32 v[64:65], v64 offset1:1
	v_fmac_f32_e32 v68, v14, v66
	v_add_u32_e32 v66, 0x36f8, v62
	v_fmac_f32_e32 v68, v15, v67
	ds_read2_b32 v[66:67], v66 offset1:1
	s_waitcnt lgkmcnt(0)
	v_fmac_f32_e32 v68, v18, v64
	v_add_u32_e32 v64, 0x3700, v62
	v_fmac_f32_e32 v68, v19, v65
	ds_read2_b32 v[64:65], v64 offset1:1
	v_fmac_f32_e32 v68, v8, v66
	v_add_u32_e32 v66, 0x3708, v62
	v_fmac_f32_e32 v68, v9, v67
	ds_read2_b32 v[66:67], v66 offset1:1
	s_waitcnt lgkmcnt(0)
	v_fmac_f32_e32 v68, v12, v64
	v_add_u32_e32 v64, 0x37e0, v62
	v_fmac_f32_e32 v68, v13, v65
	ds_read2_b32 v[64:65], v64 offset1:1
	v_add_u32_e32 v63, v23, v29
	v_fmac_f32_e32 v68, v20, v66
	v_fmac_f32_e32 v70, v69, v21
	v_fmac_f32_e32 v68, v21, v67
	v_add_u32_e32 v66, 0x3800, v63
	ds_write2_b32 v66, v70, v68 offset0:128 offset1:196
	v_add_u32_e32 v66, 0x37f0, v62
	ds_read2_b32 v[66:67], v66 offset1:1
	s_waitcnt lgkmcnt(0)
	v_fma_f32 v70, v10, v64, 0
	v_add_u32_e32 v64, 0x37e8, v62
	v_fmac_f32_e32 v70, v11, v65
	ds_read2_b32 v[64:65], v64 offset1:1
	v_add_u32_e32 v68, 0x37f8, v62
	ds_read2_b32 v[68:69], v68 offset1:1
	s_waitcnt lgkmcnt(0)
	v_fmac_f32_e32 v70, v16, v64
	v_add_u32_e32 v64, 0x3800, v62
	v_fmac_f32_e32 v70, v17, v65
	ds_read2_b32 v[64:65], v64 offset1:1
	v_fmac_f32_e32 v70, v6, v66
	v_add_u32_e32 v66, 0x3808, v62
	v_fmac_f32_e32 v70, v7, v67
	ds_read2_b32 v[66:67], v66 offset1:1
	v_fmac_f32_e32 v70, v14, v68
	v_add_u32_e32 v68, 0x3810, v62
	v_fmac_f32_e32 v70, v15, v69
	ds_read2_b32 v[68:69], v68 offset1:1
	s_waitcnt lgkmcnt(0)
	v_fmac_f32_e32 v70, v18, v64
	v_fmac_f32_e32 v70, v19, v65
	v_fmac_f32_e32 v70, v8, v66
	v_add_u32_e32 v66, 0x38f0, v62
	v_fmac_f32_e32 v70, v9, v67
	ds_read2_b32 v[66:67], v66 offset1:1
	v_fmac_f32_e32 v70, v12, v68
	v_add_u32_e32 v68, 0x38f8, v62
	v_fmac_f32_e32 v70, v13, v69
	ds_read2_b32 v[68:69], v68 offset1:1
	s_waitcnt lgkmcnt(0)
	v_fma_f32 v66, v10, v66, 0
	v_add_u32_e32 v10, 0x3900, v62
	v_fmac_f32_e32 v66, v11, v67
	ds_read2_b32 v[10:11], v10 offset1:1
	v_fmac_f32_e32 v66, v16, v68
	v_add_u32_e32 v16, 0x3908, v62
	v_add_u32_e32 v64, 0x3818, v62
	v_fmac_f32_e32 v66, v17, v69
	ds_read2_b32 v[16:17], v16 offset1:1
	ds_read2_b32 v[64:65], v64 offset1:1
	s_waitcnt lgkmcnt(0)
	v_fmac_f32_e32 v66, v6, v10
	v_fmac_f32_e32 v66, v7, v11
	v_add_u32_e32 v6, 0x3918, v62
	v_fmac_f32_e32 v66, v14, v16
	v_add_u32_e32 v10, 0x3920, v62
	v_add_u32_e32 v14, 0x3928, v62
	v_fmac_f32_e32 v66, v15, v17
	ds_read2_b32 v[6:7], v6 offset1:1
	ds_read2_b32 v[10:11], v10 offset1:1
	ds_read2_b32 v[14:15], v14 offset1:1
	v_fmac_f32_e32 v70, v20, v64
	v_add_u32_e32 v64, 0x3910, v62
	v_fmac_f32_e32 v70, v21, v65
	ds_read2_b32 v[64:65], v64 offset1:1
	v_add_u32_e32 v16, 0x3188, v49
	s_waitcnt lgkmcnt(0)
; #define LAS __attribute__((address_space(3)))
; __device__ __forceinline__ float bf2f(bf16 b) { return __uint_as_float((unsigned)b << 16); }
; __device__ __forceinline__ u32x4 pack8v(f32x4 lo, f32x4 hi) { u32x4 w; w.x = pk_bf16(lo.x, lo.y); w.y = pk_bf16(lo.z, lo.w); w.z = pk_bf16(hi.x, hi.y); w.w = pk_bf16(hi.z, hi.w); return w; }
; __device__ __forceinline__ void pc_phase(LAS unsigned char* lds, const bf16* Pp_, const bf16* LO, const float* mu, const float* w0, const float* a0, const float* k_k, const float* k_a, const float* r_k, ...
;     ...
;         { unsigned char* ob = OPS + (size_t)item * PCI_BYTES;
; #pragma unroll
;           for (int ks = 0; ks < 2; ++ks) { u32x4 w; const LAS u32x2* p0 = (const LAS u32x2*)(XKK + m * 72 + 32 * ks + 4 * g); const LAS u32x2* p1 = (const LAS u32x2*)(XKK + m * 72 + 32 * ks + 16 + 4 * g);
;               u32x2 a = *p0, b = *p1; w.x = a.x; w.y = a.y; w.z = b.x; w.w = b.y; *(u32x4*)(ob + ks * 1024 + lane * 16) = w;
;               p0 = (const LAS u32x2*)(XR + m * 72 + 32 * ks + 4 * g); p1 = (const LAS u32x2*)(XR + m * 72 + 32 * ks + 16 + 4 * g);
;               a = *p0; b = *p1; w.x = a.x; w.y = a.y; w.z = b.x; w.w = b.y; *(u32x4*)(ob + (2 + ks) * 1024 + lane * 16) = w; }
;           { f32x4 lo, hi;
; #pragma unroll
;             for (int j = 0; j < 4; ++j) { lo[j] = TT[m * 17 + 4 * g + j]; hi[j] = M1[m * 17 + 4 * g + j]; }
;             *(u32x4*)(ob + 4 * 1024 + lane * 16) = pack8v(lo, hi);
; #pragma unroll
;             for (int j = 0; j < 4; ++j) { lo[j] = ARK[m * 17 + 4 * g + j]; hi[j] = -ARB[m * 17 + 4 * g + j]; }
;             *(u32x4*)(ob + 5 * 1024 + lane * 16) = pack8v(lo, hi); }
; #pragma unroll
;           for (int kt = 0; kt < 4; ++kt) { const int kcol = 16 * kt + m; const float pc = PCL[kcol]; f32x4 lo, hi;
; #pragma unroll
;               for (int j = 0; j < 4; ++j) { lo[j] = bf2f(XK[(4 * g + j) * 72 + kcol]) * pc; hi[j] = -bf2f(XB[(4 * g + j) * 72 + kcol]) * pc; }
;               *(u32x4*)(ob + (6 + kt) * 1024 + lane * 16) = pack8v(lo, hi); }
;           *(float*)(ob + 10240 + lane * 4) = P; }
	v_fmac_f32_e32 v66, v18, v64
	v_fmac_f32_e32 v66, v19, v65
	v_fmac_f32_e32 v66, v8, v6
	v_fmac_f32_e32 v66, v9, v7
	v_fmac_f32_e32 v66, v12, v10
	v_fmac_f32_e32 v66, v13, v11
	v_fmac_f32_e32 v66, v20, v14
	v_fmac_f32_e32 v66, v21, v15
	v_add_u32_e32 v6, 0x3c00, v63
	ds_write2_b32 v6, v70, v66 offset0:8 offset1:76
	s_waitcnt lgkmcnt(0)
	ds_read2_b64 v[8:11], v48 offset1:4
	v_lshl_add_u64 v[6:7], s[88:89], 0, v[2:3]
	v_add_co_u32_e32 v12, vcc, s0, v6
	v_add_u32_e32 v14, 0x800, v48
	s_nop 0
	v_addc_co_u32_e32 v13, vcc, 0, v7, vcc
	s_waitcnt lgkmcnt(0)
	global_store_dwordx4 v[12:13], v[8:11], off
	ds_read2_b64 v[8:11], v14 offset0:32 offset1:36
	s_mov_b32 s0, 0x27601000
	s_waitcnt lgkmcnt(0)
	global_store_dwordx4 v[12:13], v[8:11], off offset:2048
	ds_read2_b64 v[8:11], v48 offset0:8 offset1:12
	s_waitcnt lgkmcnt(0)
	global_store_dwordx4 v[12:13], v[8:11], off offset:1024
	ds_read2_b64 v[8:11], v14 offset0:40 offset1:44
	v_add_u32_e32 v14, 0x3a08, v49
	s_waitcnt lgkmcnt(0)
	global_store_dwordx4 v[12:13], v[8:11], off offset:3072
	s_nop 1
	v_add_u32_e32 v8, 0x35c0, v49
	v_add_u32_e32 v10, 0x3a00, v49
	v_add_u32_e32 v12, 0x35c8, v49
	ds_read2_b32 v[8:9], v8 offset1:1
	ds_read2_b32 v[10:11], v10 offset1:1
	ds_read2_b32 v[12:13], v12 offset1:1
	ds_read2_b32 v[14:15], v14 offset1:1
	s_waitcnt lgkmcnt(0)
	v_cvt_pk_bf16_f32 v8, v8, v9
	v_cvt_pk_bf16_f32 v10, v10, v11
	v_cvt_pk_bf16_f32 v9, v12, v13
	v_add_co_u32_e32 v12, vcc, s0, v6
	v_cvt_pk_bf16_f32 v11, v14, v15
	s_nop 0
	v_addc_co_u32_e32 v13, vcc, 0, v7, vcc
	global_store_dwordx4 v[12:13], v[8:11], off
	v_add_u32_e32 v14, 0x3180, v49
	s_mov_b32 s0, 0x27602000
	v_add_u32_e32 v8, 0x2d40, v49
	v_add_u32_e32 v10, 0x2d48, v49
	ds_read2_b32 v[8:9], v8 offset1:1
	ds_read2_b32 v[10:11], v10 offset1:1
	ds_read2_b32 v[14:15], v14 offset1:1
	ds_read2_b32 v[16:17], v16 offset1:1
	s_waitcnt lgkmcnt(0)
	v_cvt_pk_bf16_f32 v8, v8, v9
	v_cvt_pk_bf16_f32 v9, v10, v11
	v_pk_add_f32 v[10:11], v[14:15], 0 neg_lo:[1,1] neg_hi:[1,1]
	v_pk_add_f32 v[14:15], v[16:17], 0 neg_lo:[1,1] neg_hi:[1,1]
	v_cvt_pk_bf16_f32 v10, v10, v11
	v_cvt_pk_bf16_f32 v11, v14, v15
	global_store_dwordx4 v[12:13], v[8:11], off offset:1024
	ds_read_u16 v9, v51 offset:4608
	ds_read_u16 v10, v50 offset:4608
	ds_read_b32 v8, v23 offset:15936
	ds_read_u16 v14, v51 offset:6912
	ds_read_u16 v16, v50 offset:6912
	s_waitcnt lgkmcnt(0)
	v_lshlrev_b32_e32 v11, 16, v9
	v_lshlrev_b32_e32 v10, 16, v10
	v_pk_mul_f32 v[10:11], v[8:9], v[10:11] op_sel_hi:[0,1]
	v_lshlrev_b32_e32 v15, 16, v14
	v_lshlrev_b32_e32 v14, 16, v16
	ds_read_u16 v9, v53 offset:4608
	ds_read_u16 v16, v52 offset:4608
	ds_read_u16 v18, v53 offset:6912
	ds_read_u16 v20, v52 offset:6912
	s_waitcnt lgkmcnt(0)
	v_lshlrev_b32_e32 v17, 16, v9
	v_lshlrev_b32_e32 v16, 16, v16
	v_lshlrev_b32_e32 v19, 16, v18
	v_lshlrev_b32_e32 v18, 16, v20
	v_pk_mul_f32 v[14:15], v[8:9], v[14:15] op_sel_hi:[0,1] neg_lo:[0,1] neg_hi:[0,1]
	v_pk_mul_f32 v[16:17], v[8:9], v[16:17] op_sel_hi:[0,1]
	v_pk_mul_f32 v[18:19], v[8:9], v[18:19] op_sel_hi:[0,1] neg_lo:[0,1] neg_hi:[0,1]
	v_cvt_pk_bf16_f32 v8, v10, v11
	v_cvt_pk_bf16_f32 v9, v16, v17
	v_cvt_pk_bf16_f32 v10, v14, v15
	v_cvt_pk_bf16_f32 v11, v18, v19
	global_store_dwordx4 v[12:13], v[8:11], off offset:2048
	ds_read_u16 v9, v51 offset:4640
	ds_read_u16 v10, v50 offset:4640
	ds_read_b32 v8, v23 offset:16000
	ds_read_u16 v14, v51 offset:6944
	ds_read_u16 v16, v50 offset:6944
	s_waitcnt lgkmcnt(0)
	v_lshlrev_b32_e32 v11, 16, v9
	v_lshlrev_b32_e32 v10, 16, v10
	v_pk_mul_f32 v[10:11], v[8:9], v[10:11] op_sel_hi:[0,1]
	v_lshlrev_b32_e32 v15, 16, v14
	v_lshlrev_b32_e32 v14, 16, v16
	ds_read_u16 v9, v53 offset:4640
	ds_read_u16 v16, v54 offset:4640
	ds_read_u16 v18, v53 offset:6944
	ds_read_u16 v20, v54 offset:6944
	s_waitcnt lgkmcnt(0)
	v_lshlrev_b32_e32 v17, 16, v9
	v_lshlrev_b32_e32 v16, 16, v16
	v_lshlrev_b32_e32 v19, 16, v18
	v_lshlrev_b32_e32 v18, 16, v20
	v_pk_mul_f32 v[14:15], v[8:9], v[14:15] op_sel_hi:[0,1] neg_lo:[0,1] neg_hi:[0,1]
	v_pk_mul_f32 v[16:17], v[8:9], v[16:17] op_sel_hi:[0,1]
	v_pk_mul_f32 v[18:19], v[8:9], v[18:19] op_sel_hi:[0,1] neg_lo:[0,1] neg_hi:[0,1]
	v_cvt_pk_bf16_f32 v8, v10, v11
	v_cvt_pk_bf16_f32 v9, v16, v17
	v_cvt_pk_bf16_f32 v10, v14, v15
	v_cvt_pk_bf16_f32 v11, v18, v19
	global_store_dwordx4 v[12:13], v[8:11], off offset:3072
	ds_read_u16 v9, v51 offset:4672
	ds_read_u16 v10, v50 offset:4672
	ds_read_b32 v8, v23 offset:16064
	ds_read_u16 v12, v51 offset:6976
	ds_read_u16 v14, v50 offset:6976
	s_waitcnt lgkmcnt(0)
	v_lshlrev_b32_e32 v11, 16, v9
	v_lshlrev_b32_e32 v10, 16, v10
	v_pk_mul_f32 v[10:11], v[8:9], v[10:11] op_sel_hi:[0,1]
	v_lshlrev_b32_e32 v13, 16, v12
	v_lshlrev_b32_e32 v12, 16, v14
	ds_read_u16 v9, v53 offset:4672
	ds_read_u16 v14, v54 offset:4672
	ds_read_u16 v16, v53 offset:6976
	ds_read_u16 v18, v54 offset:6976
	s_waitcnt lgkmcnt(0)
	v_pk_mul_f32 v[12:13], v[8:9], v[12:13] op_sel_hi:[0,1] neg_lo:[0,1] neg_hi:[0,1]
	v_lshlrev_b32_e32 v15, 16, v9
	v_lshlrev_b32_e32 v14, 16, v14
	v_lshlrev_b32_e32 v17, 16, v16
	v_lshlrev_b32_e32 v16, 16, v18
	v_pk_mul_f32 v[14:15], v[8:9], v[14:15] op_sel_hi:[0,1]
	v_pk_mul_f32 v[16:17], v[8:9], v[16:17] op_sel_hi:[0,1] neg_lo:[0,1] neg_hi:[0,1]
	v_cvt_pk_bf16_f32 v8, v10, v11
	v_cvt_pk_bf16_f32 v10, v12, v13
	v_add_co_u32_e32 v12, vcc, s0, v6
	v_cvt_pk_bf16_f32 v9, v14, v15
	v_cvt_pk_bf16_f32 v11, v16, v17
	v_addc_co_u32_e32 v13, vcc, 0, v7, vcc
	global_store_dwordx4 v[12:13], v[8:11], off
	ds_read_u16 v7, v56 offset:4608
	ds_read_u16 v8, v25 offset:4608
	ds_read_b32 v6, v55 offset:15936
	ds_read_u16 v10, v56 offset:6912
	ds_read_u16 v14, v25 offset:6912
	s_waitcnt lgkmcnt(0)
	v_lshlrev_b32_e32 v9, 16, v7
	v_lshlrev_b32_e32 v8, 16, v8
	v_pk_mul_f32 v[8:9], v[6:7], v[8:9] op_sel_hi:[0,1]
	v_lshlrev_b32_e32 v11, 16, v10
	v_lshlrev_b32_e32 v10, 16, v14
	ds_read_u16 v7, v58 offset:4608
	ds_read_u16 v14, v57 offset:4608
	ds_read_u16 v16, v58 offset:6912
	ds_read_u16 v18, v57 offset:6912
	v_readlane_b32 s0, v254, 9
	v_readlane_b32 s1, v254, 10
	s_waitcnt lgkmcnt(0)
	v_lshlrev_b32_e32 v15, 16, v7
	v_lshlrev_b32_e32 v14, 16, v14
	v_lshlrev_b32_e32 v17, 16, v16
	v_lshlrev_b32_e32 v16, 16, v18
	v_pk_mul_f32 v[10:11], v[6:7], v[10:11] op_sel_hi:[0,1] neg_lo:[0,1] neg_hi:[0,1]
	v_pk_mul_f32 v[14:15], v[6:7], v[14:15] op_sel_hi:[0,1]
	v_pk_mul_f32 v[16:17], v[6:7], v[16:17] op_sel_hi:[0,1] neg_lo:[0,1] neg_hi:[0,1]
	v_cvt_pk_bf16_f32 v6, v8, v9
	v_cvt_pk_bf16_f32 v7, v14, v15
	v_cvt_pk_bf16_f32 v8, v10, v11
	v_cvt_pk_bf16_f32 v9, v16, v17
	global_store_dwordx4 v[12:13], v[6:9], off offset:1024
	v_lshl_add_u64 v[2:3], v[2:3], 0, s[0:1]
	s_nop 0
	v_lshl_add_u64 v[6:7], s[88:89], 0, v[0:1]
	global_store_dword v[6:7], v61, off
	s_waitcnt lgkmcnt(0)
	v_lshl_add_u64 v[0:1], v[0:1], 0, s[0:1]
	v_readlane_b32 s0, v254, 42
	v_readlane_b32 s1, v254, 43
	s_nop 1
	v_lshl_add_u64 v[4:5], v[4:5], 0, s[0:1]
	s_cbranch_scc1 .LBB0_313
; __device__ __forceinline__ float bf2f(bf16 b) { return __uint_as_float((unsigned)b << 16); }
; __device__ __forceinline__ void pc_phase(LAS unsigned char* lds, const bf16* Pp_, const bf16* LO, const float* mu, const float* w0, const float* a0, const float* k_k, const float* k_a, const float* r_k, ...
;     ...
;     for (int item = bid * NWAVES + wave; item < 16384; item += G * NWAVES) {
;         const size_t ib = (size_t)item * 16;
;         const int bh = item >> 8, c = item & 255, b = bh >> 4, h = bh & 15, ch = h * 64 + lane; const int m0 = b * SEQ + c * 16;
;         const float mu_r = mu[ch], mu_k = mu[1024 + ch], mu_v = mu[2048 + ch], w0c = w0[ch], a0c = a0[ch], kkc = k_k[ch], kac = k_a[ch], rkc = r_k[ch];
;         unsigned short sr_[17], sk_[17], sv_[17], slw[16], sla[16];
;         { const bf16* pp = Pp_ + (size_t)(c > 0 ? m0 - 1 : m0) * EV_IN_P + 3072 + ch; sr_[0] = pp[0]; sk_[0] = pp[1024]; sv_[0] = pp[2048]; }
; #pragma unroll
;         for (int t = 0; t < 16; ++t) { const bf16* pr = Pp_ + (size_t)(m0 + t) * EV_IN_P + 3072 + ch; sr_[t + 1] = pr[0]; sk_[t + 1] = pr[1024]; sv_[t + 1] = pr[2048];
;             const bf16* lo = LO + (size_t)(m0 + t) * LORA_N + ch; slw[t] = lo[0]; sla[t] = lo[1024]; }
;         const float z1 = (c > 0) ? 1.0f : 0.0f;
;         float P = 1.0f, r1 = bf2f(sr_[0]) * z1, k1 = bf2f(sk_[0]) * z1, v1 = bf2f(sv_[0]) * z1;
	s_and_b32 s1, s11, 0xff
	s_bfe_u32 s0, s11, 0x40008
	s_and_b32 s2, s11, 0xfffff000
	s_lshl_b32 s4, s1, 4
	s_or_b32 s56, s4, s2
	s_cmp_eq_u32 s1, 0
	s_cselect_b64 s[94:95], -1, 0
	s_or_b32 s86, s56, 1
	s_or_b32 s34, s56, 2
	s_or_b32 s40, s56, 3
	s_or_b32 s72, s56, 4
	s_or_b32 s68, s56, 5
	s_or_b32 s66, s56, 6
	s_or_b32 s64, s56, 7
	s_or_b32 s62, s56, 8
	s_or_b32 s36, s56, 9
	s_or_b32 s84, s56, 10
	s_or_b32 s82, s56, 11
	s_or_b32 s80, s56, 12
	s_or_b32 s78, s56, 13
	s_or_b32 s76, s56, 14
	s_or_b32 s74, s56, 15
	v_cndmask_b32_e64 v96, 1.0, 0, s[94:95]
	s_lshl_b32 s0, s0, 2
	v_lshl_add_u64 v[6:7], s[88:89], 0, v[4:5]
	s_add_u32 s2, s49, s0
	s_addc_u32 s14, s35, 0
	s_waitcnt vmcnt(0) lgkmcnt(0)
	v_mov_b32_e32 v8, v159
	v_mov_b32_e32 v9, v157
	v_mov_b32_e32 v10, v156
	v_mov_b32_e32 v11, v163
	v_mov_b32_e32 v12, v158
	v_mov_b32_e32 v13, v162
	v_mov_b32_e32 v14, v161
	v_mov_b32_e32 v15, v160
	v_mov_b32_e32 v16, v209
	v_mov_b32_e32 v17, v210
	v_mov_b32_e32 v18, v204
	v_mov_b32_e32 v19, v205
	v_mov_b32_e32 v20, v208
	v_mov_b32_e32 v21, v202
	v_mov_b32_e32 v61, v203
	v_mov_b32_e32 v62, v191
	v_mov_b32_e32 v63, v192
	v_mov_b32_e32 v64, v193
	v_mov_b32_e32 v65, v189
	v_mov_b32_e32 v66, v184
	v_mov_b32_e32 v67, v187
	v_mov_b32_e32 v68, v188
	v_mov_b32_e32 v69, v190
	v_mov_b32_e32 v70, v182
	v_mov_b32_e32 v71, v183
	v_mov_b32_e32 v72, v179
	v_mov_b32_e32 v73, v180
	v_mov_b32_e32 v74, v181
	v_mov_b32_e32 v75, v177
	v_mov_b32_e32 v76, v178
	v_mov_b32_e32 v77, v174
	v_mov_b32_e32 v78, v175
	v_mov_b32_e32 v79, v176
	v_mov_b32_e32 v80, v172
	v_mov_b32_e32 v81, v173
	v_mov_b32_e32 v82, v169
	v_mov_b32_e32 v83, v170
	v_mov_b32_e32 v84, v171
	v_mov_b32_e32 v85, v167
	v_mov_b32_e32 v86, v168
	v_mov_b32_e32 v87, v164
	v_mov_b32_e32 v88, v165
	v_mov_b32_e32 v89, v166
	s_branch .Lpc_join
.LBB0_281:
	s_and_b32 s1, s11, 0xff
	s_bfe_u32 s0, s11, 0x40008
	s_and_b32 s2, s11, 0xfffff000
	s_lshl_b32 s4, s1, 4
	v_lshl_or_b32 v16, s0, 6, v185
	s_or_b32 s56, s4, s2
	v_readlane_b32 s4, v255, 13
	v_lshlrev_b32_e32 v96, 2, v16
	v_readlane_b32 s5, v255, 14
	s_add_i32 s6, s56, -1
	s_cmp_eq_u32 s1, 0
	v_lshl_add_u64 v[6:7], s[4:5], 0, v[96:97]
	v_add_co_u32_e32 v8, vcc, 0x1000, v6
	global_load_dword v10, v[6:7], off
	s_nop 0
	v_addc_co_u32_e32 v9, vcc, 0, v7, vcc
	global_load_dword v9, v[8:9], off
	v_add_co_u32_e32 v6, vcc, 0x2000, v6
	v_readlane_b32 s4, v255, 15
	s_nop 0
	v_addc_co_u32_e32 v7, vcc, 0, v7, vcc
	v_readlane_b32 s5, v255, 16
	global_load_dword v12, v[6:7], off
	s_cselect_b64 s[94:95], -1, 0
	v_lshl_add_u64 v[6:7], s[4:5], 0, v[96:97]
	v_readlane_b32 s4, v255, 20
	v_readlane_b32 s5, v255, 21
	global_load_dword v8, v[6:7], off
	v_readlane_b32 s8, v254, 63
	v_lshl_add_u64 v[6:7], s[4:5], 0, v[96:97]
	v_readlane_b32 s4, v255, 22
	v_readlane_b32 s5, v255, 23
	global_load_dword v15, v[6:7], off
	v_readlane_b32 s9, v255, 0
	v_lshl_add_u64 v[6:7], s[4:5], 0, v[96:97]
	v_readlane_b32 s4, v255, 24
	v_readlane_b32 s5, v255, 25
	global_load_dword v14, v[6:7], off
	s_nop 0
	v_lshl_add_u64 v[6:7], s[4:5], 0, v[96:97]
	v_readlane_b32 s4, v255, 26
	v_readlane_b32 s5, v255, 27
	global_load_dword v13, v[6:7], off
	s_nop 0
	v_lshl_add_u64 v[6:7], s[4:5], 0, v[96:97]
	s_and_b64 s[4:5], s[94:95], exec
	s_cselect_b32 s1, s2, s6
	s_mul_hi_i32 s2, s1, 0x3400
	s_mulk_i32 s1, 0x3400
	s_add_u32 s4, s8, s1
	s_addc_u32 s5, s9, s2
	v_lshlrev_b32_e32 v96, 1, v16
	v_lshl_add_u64 v[16:17], s[4:5], 0, v[96:97]
	v_readlane_b32 s4, v255, 1
	v_readlane_b32 s5, v255, 2
	s_mul_i32 s2, s56, 0x3400
	global_load_dword v11, v[6:7], off
	v_lshl_add_u64 v[6:7], s[4:5], 0, v[96:97]
	s_mul_hi_i32 s1, s56, 0x3400
	s_add_u32 s4, s8, s2
	s_addc_u32 s5, s9, s1
	s_or_b32 s86, s56, 1
	v_lshl_add_u64 v[20:21], s[4:5], 0, v[96:97]
	v_mad_i64_i32 v[140:141], s[4:5], s56, v226, v[6:7]
	s_mul_i32 s2, s86, 0x3400
	s_mul_hi_i32 s1, s86, 0x3400
	s_add_u32 s4, s8, s2
	s_addc_u32 s5, s9, s1
	v_lshl_add_u64 v[64:65], s[4:5], 0, v[96:97]
	v_add_co_u32_e32 v68, vcc, s55, v64
	s_mov_b64 s[6:7], 0x1800
	s_nop 0
	v_addc_co_u32_e32 v69, vcc, 0, v65, vcc
	v_lshl_add_u64 v[66:67], v[64:65], 0, s[6:7]
	v_add_co_u32_e32 v64, vcc, s13, v64
	s_or_b32 s34, s56, 2
	s_nop 0
	v_addc_co_u32_e32 v65, vcc, 0, v65, vcc
	global_load_ushort v132, v[140:141], off
	global_load_ushort v129, v[68:69], off offset:2048
	global_load_ushort v130, v[66:67], off offset:2048
	global_load_ushort v131, v[64:65], off offset:2048
	v_mad_i64_i32 v[64:65], s[4:5], s86, v226, v[6:7]
	s_mul_i32 s2, s34, 0x3400
	s_mul_hi_i32 s1, s34, 0x3400
	s_add_u32 s4, s8, s2
	s_addc_u32 s5, s9, s1
	global_load_ushort v127, v[64:65], off
	global_load_ushort v128, v[64:65], off offset:2048
	v_lshl_add_u64 v[64:65], s[4:5], 0, v[96:97]
	v_add_co_u32_e32 v68, vcc, s55, v64
	v_lshl_add_u64 v[66:67], v[64:65], 0, s[6:7]
	s_nop 0
	v_addc_co_u32_e32 v69, vcc, 0, v65, vcc
	v_add_co_u32_e32 v64, vcc, s13, v64
	s_or_b32 s40, s56, 3
	s_nop 0
	v_addc_co_u32_e32 v65, vcc, 0, v65, vcc
	global_load_ushort v124, v[68:69], off offset:2048
	global_load_ushort v125, v[66:67], off offset:2048
	global_load_ushort v126, v[64:65], off offset:2048
	v_mad_i64_i32 v[64:65], s[4:5], s34, v226, v[6:7]
	s_mul_i32 s2, s40, 0x3400
	s_mul_hi_i32 s1, s40, 0x3400
	s_add_u32 s4, s8, s2
	s_addc_u32 s5, s9, s1
	global_load_ushort v122, v[64:65], off
	global_load_ushort v123, v[64:65], off offset:2048
	v_lshl_add_u64 v[64:65], s[4:5], 0, v[96:97]
	v_add_co_u32_e32 v68, vcc, s55, v64
	v_lshl_add_u64 v[66:67], v[64:65], 0, s[6:7]
	s_nop 0
	v_addc_co_u32_e32 v69, vcc, 0, v65, vcc
	v_add_co_u32_e32 v64, vcc, s13, v64
	s_or_b32 s72, s56, 4
	s_nop 0
	v_addc_co_u32_e32 v65, vcc, 0, v65, vcc
	global_load_ushort v119, v[68:69], off offset:2048
; __device__ __forceinline__ void pc_phase(LAS unsigned char* lds, const bf16* Pp_, const bf16* LO, const float* mu, const float* w0, const float* a0, const float* k_k, const float* k_a, const float* r_k, ...
;     ...
;         { const bf16* pp = Pp_ + (size_t)(c > 0 ? m0 - 1 : m0) * EV_IN_P + 3072 + ch; sr_[0] = pp[0]; sk_[0] = pp[1024]; sv_[0] = pp[2048]; }
; #pragma unroll
;         for (int t = 0; t < 16; ++t) { const bf16* pr = Pp_ + (size_t)(m0 + t) * EV_IN_P + 3072 + ch; sr_[t + 1] = pr[0]; sk_[t + 1] = pr[1024]; sv_[t + 1] = pr[2048];
;             const bf16* lo = LO + (size_t)(m0 + t) * LORA_N + ch; slw[t] = lo[0]; sla[t] = lo[1024]; }
	global_load_ushort v120, v[66:67], off offset:2048
	global_load_ushort v121, v[64:65], off offset:2048
	v_mad_i64_i32 v[64:65], s[4:5], s40, v226, v[6:7]
	s_mul_i32 s2, s72, 0x3400
	s_mul_hi_i32 s1, s72, 0x3400
	s_add_u32 s4, s8, s2
	s_addc_u32 s5, s9, s1
	global_load_ushort v117, v[64:65], off
	global_load_ushort v118, v[64:65], off offset:2048
	v_lshl_add_u64 v[64:65], s[4:5], 0, v[96:97]
	v_add_co_u32_e32 v68, vcc, s55, v64
	v_lshl_add_u64 v[66:67], v[64:65], 0, s[6:7]
	s_nop 0
	v_addc_co_u32_e32 v69, vcc, 0, v65, vcc
	v_add_co_u32_e32 v64, vcc, s13, v64
	s_or_b32 s68, s56, 5
	s_nop 0
	v_addc_co_u32_e32 v65, vcc, 0, v65, vcc
	global_load_ushort v114, v[68:69], off offset:2048
	global_load_ushort v115, v[66:67], off offset:2048
	global_load_ushort v116, v[64:65], off offset:2048
	v_mad_i64_i32 v[64:65], s[4:5], s72, v226, v[6:7]
	s_mul_i32 s2, s68, 0x3400
	s_mul_hi_i32 s1, s68, 0x3400
	s_add_u32 s4, s8, s2
	s_addc_u32 s5, s9, s1
	global_load_ushort v112, v[64:65], off
	global_load_ushort v113, v[64:65], off offset:2048
	v_lshl_add_u64 v[64:65], s[4:5], 0, v[96:97]
	v_add_co_u32_e32 v68, vcc, s55, v64
	v_lshl_add_u64 v[66:67], v[64:65], 0, s[6:7]
	s_nop 0
	v_addc_co_u32_e32 v69, vcc, 0, v65, vcc
	v_add_co_u32_e32 v64, vcc, s13, v64
	s_or_b32 s66, s56, 6
	s_nop 0
	v_addc_co_u32_e32 v65, vcc, 0, v65, vcc
	global_load_ushort v109, v[68:69], off offset:2048
	global_load_ushort v110, v[66:67], off offset:2048
	global_load_ushort v111, v[64:65], off offset:2048
	v_mad_i64_i32 v[64:65], s[4:5], s68, v226, v[6:7]
	s_mul_i32 s2, s66, 0x3400
	s_mul_hi_i32 s1, s66, 0x3400
	s_add_u32 s4, s8, s2
	s_addc_u32 s5, s9, s1
	global_load_ushort v107, v[64:65], off
	global_load_ushort v108, v[64:65], off offset:2048
	v_lshl_add_u64 v[64:65], s[4:5], 0, v[96:97]
	v_add_co_u32_e32 v68, vcc, s55, v64
	v_lshl_add_u64 v[66:67], v[64:65], 0, s[6:7]
	s_nop 0
	v_addc_co_u32_e32 v69, vcc, 0, v65, vcc
	v_add_co_u32_e32 v64, vcc, s13, v64
	s_or_b32 s64, s56, 7
	s_nop 0
	v_addc_co_u32_e32 v65, vcc, 0, v65, vcc
	global_load_ushort v104, v[68:69], off offset:2048
	global_load_ushort v105, v[66:67], off offset:2048
	global_load_ushort v106, v[64:65], off offset:2048
	v_mad_i64_i32 v[64:65], s[4:5], s66, v226, v[6:7]
	s_mul_i32 s2, s64, 0x3400
	s_mul_hi_i32 s1, s64, 0x3400
	s_add_u32 s4, s8, s2
	s_addc_u32 s5, s9, s1
	global_load_ushort v102, v[64:65], off
	global_load_ushort v103, v[64:65], off offset:2048
	v_lshl_add_u64 v[64:65], s[4:5], 0, v[96:97]
	v_add_co_u32_e32 v68, vcc, s55, v64
	v_lshl_add_u64 v[66:67], v[64:65], 0, s[6:7]
	s_nop 0
	v_addc_co_u32_e32 v69, vcc, 0, v65, vcc
	v_add_co_u32_e32 v64, vcc, s13, v64
	s_or_b32 s62, s56, 8
	s_nop 0
	v_addc_co_u32_e32 v65, vcc, 0, v65, vcc
	global_load_ushort v99, v[68:69], off offset:2048
	global_load_ushort v100, v[66:67], off offset:2048
	global_load_ushort v101, v[64:65], off offset:2048
	v_mad_i64_i32 v[64:65], s[4:5], s64, v226, v[6:7]
	s_mul_i32 s2, s62, 0x3400
	s_mul_hi_i32 s1, s62, 0x3400
	s_add_u32 s4, s8, s2
	s_addc_u32 s5, s9, s1
	global_load_ushort v95, v[64:65], off
	global_load_ushort v98, v[64:65], off offset:2048
	v_lshl_add_u64 v[64:65], s[4:5], 0, v[96:97]
	v_add_co_u32_e32 v68, vcc, s55, v64
	v_lshl_add_u64 v[66:67], v[64:65], 0, s[6:7]
	s_nop 0
	v_addc_co_u32_e32 v69, vcc, 0, v65, vcc
	v_add_co_u32_e32 v64, vcc, s13, v64
	s_or_b32 s36, s56, 9
	s_nop 0
	v_addc_co_u32_e32 v65, vcc, 0, v65, vcc
	global_load_ushort v92, v[68:69], off offset:2048
	global_load_ushort v93, v[66:67], off offset:2048
	global_load_ushort v94, v[64:65], off offset:2048
	v_mad_i64_i32 v[64:65], s[4:5], s62, v226, v[6:7]
	s_mul_i32 s2, s36, 0x3400
	s_mul_hi_i32 s1, s36, 0x3400
	s_add_u32 s4, s8, s2
	s_addc_u32 s5, s9, s1
	global_load_ushort v90, v[64:65], off
	global_load_ushort v91, v[64:65], off offset:2048
	v_lshl_add_u64 v[64:65], s[4:5], 0, v[96:97]
	v_add_co_u32_e32 v68, vcc, s55, v64
	v_lshl_add_u64 v[66:67], v[64:65], 0, s[6:7]
	s_nop 0
	v_addc_co_u32_e32 v69, vcc, 0, v65, vcc
	v_add_co_u32_e32 v64, vcc, s13, v64
	s_or_b32 s84, s56, 10
	s_nop 0
	v_addc_co_u32_e32 v65, vcc, 0, v65, vcc
	global_load_ushort v87, v[68:69], off offset:2048
	global_load_ushort v88, v[66:67], off offset:2048
	global_load_ushort v89, v[64:65], off offset:2048
	v_mad_i64_i32 v[64:65], s[4:5], s36, v226, v[6:7]
	s_mul_i32 s2, s84, 0x3400
	s_mul_hi_i32 s1, s84, 0x3400
	s_add_u32 s4, s8, s2
	s_addc_u32 s5, s9, s1
	global_load_ushort v85, v[64:65], off
	global_load_ushort v86, v[64:65], off offset:2048
	v_lshl_add_u64 v[64:65], s[4:5], 0, v[96:97]
	v_add_co_u32_e32 v68, vcc, s55, v64
	v_lshl_add_u64 v[66:67], v[64:65], 0, s[6:7]
	s_nop 0
	v_addc_co_u32_e32 v69, vcc, 0, v65, vcc
	v_add_co_u32_e32 v64, vcc, s13, v64
	s_or_b32 s82, s56, 11
	s_nop 0
	v_addc_co_u32_e32 v65, vcc, 0, v65, vcc
	global_load_ushort v82, v[68:69], off offset:2048
	global_load_ushort v83, v[66:67], off offset:2048
	global_load_ushort v84, v[64:65], off offset:2048
	v_mad_i64_i32 v[64:65], s[4:5], s84, v226, v[6:7]
	s_mul_i32 s2, s82, 0x3400
	s_mul_hi_i32 s1, s82, 0x3400
	s_add_u32 s4, s8, s2
	s_addc_u32 s5, s9, s1
	global_load_ushort v80, v[64:65], off
	global_load_ushort v81, v[64:65], off offset:2048
	v_lshl_add_u64 v[64:65], s[4:5], 0, v[96:97]
	v_add_co_u32_e32 v68, vcc, s55, v64
	v_lshl_add_u64 v[66:67], v[64:65], 0, s[6:7]
	s_nop 0
	v_addc_co_u32_e32 v69, vcc, 0, v65, vcc
	v_add_co_u32_e32 v64, vcc, s13, v64
	s_or_b32 s80, s56, 12
	s_nop 0
	v_addc_co_u32_e32 v65, vcc, 0, v65, vcc
	global_load_ushort v77, v[68:69], off offset:2048
	global_load_ushort v78, v[66:67], off offset:2048
	global_load_ushort v79, v[64:65], off offset:2048
	v_mad_i64_i32 v[64:65], s[4:5], s82, v226, v[6:7]
; __device__ __forceinline__ float bf2f(bf16 b) { return __uint_as_float((unsigned)b << 16); }
; __device__ __forceinline__ bf16 f2bf(float f) { return (bf16)(pk_bf16(f, 0.f) & 0xffffu); }
; __device__ __forceinline__ float fexp(float x) { return __builtin_amdgcn_exp2f(x * 1.4426950408889634f); }
; __device__ __forceinline__ float flog(float x) { return __builtin_amdgcn_logf(x) * 0.6931471805599453f; }
; __device__ __forceinline__ float fsigmoid(float x) { return __builtin_amdgcn_rcpf(1.0f + fexp(-x)); }
; __device__ __forceinline__ void pc_phase(LAS unsigned char* lds, const bf16* Pp_, const bf16* LO, const float* mu, const float* w0, const float* a0, const float* k_k, const float* k_a, const float* r_k, ...
;     ...
;         for (int t = 0; t < 16; ++t) { const bf16* pr = Pp_ + (size_t)(m0 + t) * EV_IN_P + 3072 + ch; sr_[t + 1] = pr[0]; sk_[t + 1] = pr[1024]; sv_[t + 1] = pr[2048];
;             const bf16* lo = LO + (size_t)(m0 + t) * LORA_N + ch; slw[t] = lo[0]; sla[t] = lo[1024]; }
;         const float z1 = (c > 0) ? 1.0f : 0.0f;
;         float P = 1.0f, r1 = bf2f(sr_[0]) * z1, k1 = bf2f(sk_[0]) * z1, v1 = bf2f(sv_[0]) * z1;
; #pragma unroll
;         for (int t = 0; t < 16; ++t) {
;             const float r0 = bf2f(sr_[t + 1]), k0 = bf2f(sk_[t + 1]), v0 = bf2f(sv_[t + 1]);
;             const float r = r0 + (r1 - r0) * mu_r, k = k0 + (k1 - k0) * mu_k, v = v0 + (v1 - v0) * mu_v; r1 = r0; k1 = k0; v1 = v0;
;             const float z = -(w0c + bf2f(slw[t])); const float sp = fmaxf(z, 0.f) + flog(1.0f + fexp(-fabsf(z))); const float w = -sp - 0.5f;
;             const float dec = fexp(-fexp(w)); const float a = fsigmoid(a0c + bf2f(sla[t]));
;             float kk = k * kkc; const float n2 = wsum_dpp(kk * kk); kk = kk / fmaxf(sqrtf(n2), 1e-12f);
;             const float kp = bf2f(f2bf(k * (1.0f + (a - 1.0f) * kac))), bb = bf2f(f2bf(kk * a)), rr = bf2f(f2bf(r)); kk = bf2f(f2bf(kk));
;             const float coef = wsum_dpp(rr * kp * rkc);
;             SV[(ib + t) * 64 + lane] = f2bf(v);
;             if (lane == 0) COEF[(size_t)(m0 + t) * 16 + h] = coef;
	s_mul_i32 s2, s80, 0x3400
	s_mul_hi_i32 s1, s80, 0x3400
	s_add_u32 s4, s8, s2
	s_addc_u32 s5, s9, s1
	global_load_ushort v75, v[64:65], off
	global_load_ushort v76, v[64:65], off offset:2048
	v_lshl_add_u64 v[64:65], s[4:5], 0, v[96:97]
	v_add_co_u32_e32 v68, vcc, s55, v64
	v_lshl_add_u64 v[66:67], v[64:65], 0, s[6:7]
	s_nop 0
	v_addc_co_u32_e32 v69, vcc, 0, v65, vcc
	v_add_co_u32_e32 v64, vcc, s13, v64
	s_or_b32 s78, s56, 13
	s_nop 0
	v_addc_co_u32_e32 v65, vcc, 0, v65, vcc
	global_load_ushort v72, v[68:69], off offset:2048
	global_load_ushort v73, v[66:67], off offset:2048
	global_load_ushort v74, v[64:65], off offset:2048
	v_mad_i64_i32 v[64:65], s[4:5], s80, v226, v[6:7]
	s_mul_i32 s2, s78, 0x3400
	s_mul_hi_i32 s1, s78, 0x3400
	s_add_u32 s4, s8, s2
	s_addc_u32 s5, s9, s1
	global_load_ushort v70, v[64:65], off
	global_load_ushort v71, v[64:65], off offset:2048
	v_lshl_add_u64 v[64:65], s[4:5], 0, v[96:97]
	v_add_co_u32_e32 v66, vcc, s55, v64
	v_lshl_add_u64 v[68:69], v[64:65], 0, s[6:7]
	s_nop 0
	v_addc_co_u32_e32 v67, vcc, 0, v65, vcc
	v_add_co_u32_e32 v64, vcc, s13, v64
	global_load_ushort v66, v[66:67], off offset:2048
	s_nop 0
	global_load_ushort v67, v[68:69], off offset:2048
	v_addc_co_u32_e32 v65, vcc, 0, v65, vcc
	global_load_ushort v68, v[64:65], off offset:2048
	v_add_co_u32_e32 v64, vcc, s55, v16
	v_lshl_add_u64 v[18:19], v[16:17], 0, s[6:7]
	s_nop 0
	v_addc_co_u32_e32 v65, vcc, 0, v17, vcc
	v_add_co_u32_e32 v16, vcc, s13, v16
	global_load_ushort v134, v[64:65], off offset:2048
	global_load_ushort v135, v[18:19], off offset:2048
	v_addc_co_u32_e32 v17, vcc, 0, v17, vcc
	global_load_ushort v138, v[16:17], off offset:2048
	v_add_co_u32_e32 v16, vcc, s55, v20
	v_lshl_add_u64 v[62:63], v[20:21], 0, s[6:7]
	s_nop 0
	v_addc_co_u32_e32 v17, vcc, 0, v21, vcc
	global_load_ushort v136, v[16:17], off offset:2048
	global_load_ushort v137, v[62:63], off offset:2048
	v_add_co_u32_e32 v16, vcc, s13, v20
	s_or_b32 s76, s56, 14
	s_nop 0
	v_addc_co_u32_e32 v17, vcc, 0, v21, vcc
	global_load_ushort v139, v[16:17], off offset:2048
	v_mad_i64_i32 v[16:17], s[4:5], s78, v226, v[6:7]
	global_load_ushort v65, v[16:17], off
	global_load_ushort v133, v[140:141], off offset:2048
	global_load_ushort v69, v[16:17], off offset:2048
	s_mul_i32 s2, s76, 0x3400
	s_mul_hi_i32 s1, s76, 0x3400
	s_add_u32 s4, s8, s2
	s_addc_u32 s5, s9, s1
	v_lshl_add_u64 v[16:17], s[4:5], 0, v[96:97]
	v_add_co_u32_e32 v20, vcc, s55, v16
	v_lshl_add_u64 v[18:19], v[16:17], 0, s[6:7]
	s_nop 0
	v_addc_co_u32_e32 v21, vcc, 0, v17, vcc
	v_add_co_u32_e32 v16, vcc, s13, v16
	s_or_b32 s74, s56, 15
	s_nop 0
	v_addc_co_u32_e32 v17, vcc, 0, v17, vcc
	global_load_ushort v62, v[20:21], off offset:2048
	global_load_ushort v63, v[18:19], off offset:2048
	global_load_ushort v64, v[16:17], off offset:2048
	v_mad_i64_i32 v[16:17], s[4:5], s76, v226, v[6:7]
	s_mul_i32 s2, s74, 0x3400
	s_mul_hi_i32 s1, s74, 0x3400
	s_add_u32 s4, s8, s2
	s_addc_u32 s5, s9, s1
	global_load_ushort v21, v[16:17], off
	global_load_ushort v61, v[16:17], off offset:2048
	v_lshl_add_u64 v[16:17], s[4:5], 0, v[96:97]
	v_add_co_u32_e32 v18, vcc, s55, v16
	v_lshl_add_u64 v[140:141], v[16:17], 0, s[6:7]
	s_nop 0
	v_addc_co_u32_e32 v19, vcc, 0, v17, vcc
	v_add_co_u32_e32 v16, vcc, s13, v16
	v_mad_i64_i32 v[6:7], s[4:5], s74, v226, v[6:7]
	s_nop 0
	v_addc_co_u32_e32 v17, vcc, 0, v17, vcc
	global_load_ushort v18, v[18:19], off offset:2048
	s_nop 0
	global_load_ushort v19, v[140:141], off offset:2048
	global_load_ushort v20, v[16:17], off offset:2048
	s_nop 0
	global_load_ushort v16, v[6:7], off
	global_load_ushort v17, v[6:7], off offset:2048
	v_cndmask_b32_e64 v96, 1.0, 0, s[94:95]
	s_lshl_b32 s0, s0, 2
	v_lshl_add_u64 v[6:7], s[88:89], 0, v[4:5]
	s_add_u32 s2, s49, s0
	s_addc_u32 s14, s35, 0
	s_waitcnt vmcnt(0) lgkmcnt(0)
.Lpc_join:
	v_lshlrev_b32_e32 v140, 16, v134
	v_lshlrev_b32_e32 v141, 16, v135
	v_lshlrev_b32_e32 v138, 16, v138
	v_lshlrev_b32_e32 v136, 16, v136
	v_lshlrev_b32_e32 v135, 16, v137
	v_fma_f32 v137, v96, v140, -v136
	v_fma_f32 v137, v10, v137, v136
	v_cvt_pk_bf16_f32 v137, v137, s0
	v_lshlrev_b32_e32 v137, 16, v137
	v_lshlrev_b32_e32 v134, 16, v139
	v_fma_f32 v139, v96, v141, -v135
	v_lshlrev_b32_e32 v133, 16, v133
	v_add_f32_e32 v133, v15, v133
	v_mul_f32_e32 v133, 0xbfb8aa3b, v133
	v_exp_f32_e32 v133, v133
	v_fma_f32 v140, v9, v139, v135
	v_mul_f32_e32 v139, v14, v140
	v_fma_f32 v96, v96, v138, -v134
	v_add_f32_e32 v133, 1.0, v133
	v_rcp_f32_e32 v138, v133
	v_mul_f32_e32 v133, v139, v139
	v_fma_f32 v96, v12, v96, v134
	s_nop 0
	v_mov_b32_dpp v133, v133 quad_perm:[1,0,3,2] row_mask:0xf bank_mask:0xf bound_ctrl:1
	v_fmac_f32_e32 v133, v139, v139
	s_nop 1
	v_add_f32_dpp v133, v133, v133 quad_perm:[2,3,0,1] row_mask:0xf bank_mask:0xf bound_ctrl:1
	s_nop 1
	v_add_f32_dpp v133, v133, v133 row_ror:4 row_mask:0xf bank_mask:0xf bound_ctrl:1
	s_nop 1
	v_add_f32_dpp v133, v133, v133 row_ror:8 row_mask:0xf bank_mask:0xf bound_ctrl:1
	s_nop 0
	v_readlane_b32 s7, v133, 0
	v_readlane_b32 s8, v133, 16
	v_readlane_b32 s6, v133, 32
	v_readlane_b32 s9, v133, 48
	v_add_f32_e32 v133, -1.0, v138
	v_fma_f32 v133, v13, v133, 1.0
	v_mul_f32_e32 v133, v140, v133
	v_cvt_pk_bf16_f32 v133, v133, s0
	v_lshlrev_b32_e32 v133, 16, v133
	v_mul_f32_e32 v140, v137, v133
	v_mul_f32_e32 v141, v11, v140
	s_nop 1
	v_mov_b32_dpp v141, v141 quad_perm:[1,0,3,2] row_mask:0xf bank_mask:0xf bound_ctrl:1
	v_fmac_f32_e32 v141, v11, v140
	s_nop 1
	v_add_f32_dpp v140, v141, v141 quad_perm:[2,3,0,1] row_mask:0xf bank_mask:0xf bound_ctrl:1
	s_nop 1
	v_add_f32_dpp v140, v140, v140 row_ror:4 row_mask:0xf bank_mask:0xf bound_ctrl:1
	s_nop 1
	v_add_f32_dpp v140, v140, v140 row_ror:8 row_mask:0xf bank_mask:0xf bound_ctrl:1
	s_nop 0
	v_readlane_b32 s0, v140, 0
	v_readlane_b32 s15, v140, 16
	v_readlane_b32 s1, v140, 32
	v_readlane_b32 s17, v140, 48
	v_add_co_u32_e32 v140, vcc, 0x33600000, v6
	v_cvt_pk_bf16_f32 v96, v96, s0
	s_nop 0
	v_addc_co_u32_e32 v141, vcc, 0, v7, vcc
	global_store_short v[140:141], v96, off
	s_and_saveexec_b64 s[4:5], s[38:39]
	s_cbranch_execz .LBB0_283
	s_ashr_i32 s57, s56, 31
	s_lshl_b64 s[30:31], s[56:57], 6
	s_add_u32 s30, s2, s30
	v_mov_b32_e32 v140, s15
	v_mov_b32_e32 v141, s17
	s_addc_u32 s31, s14, s31
	v_pk_add_f32 v[140:141], s[0:1], v[140:141]
	s_nop 0
	v_add_f32_e32 v96, v140, v141
	v_mov_b64_e32 v[140:141], s[30:31]
	global_store_dword v[140:141], v96, off

; __device__ __forceinline__ float bf2f(bf16 b) { return __uint_as_float((unsigned)b << 16); }
; __device__ __forceinline__ bf16 f2bf(float f) { return (bf16)(pk_bf16(f, 0.f) & 0xffffu); }
; __device__ __forceinline__ float fexp(float x) { return __builtin_amdgcn_exp2f(x * 1.4426950408889634f); }
; __device__ __forceinline__ float flog(float x) { return __builtin_amdgcn_logf(x) * 0.6931471805599453f; }
; __device__ __forceinline__ float fsigmoid(float x) { return __builtin_amdgcn_rcpf(1.0f + fexp(-x)); }
; __device__ __forceinline__ void pc_phase(LAS unsigned char* lds, const bf16* Pp_, const bf16* LO, const float* mu, const float* w0, const float* a0, const float* k_k, const float* k_a, const float* r_k, ...
;     ...
; #pragma unroll
;         for (int t = 0; t < 16; ++t) { const bf16* pr = Pp_ + (size_t)(m0 + t) * EV_IN_P + 3072 + ch; sr_[t + 1] = pr[0]; sk_[t + 1] = pr[1024]; sv_[t + 1] = pr[2048];
;             const bf16* lo = LO + (size_t)(m0 + t) * LORA_N + ch; slw[t] = lo[0]; sla[t] = lo[1024]; }
;         const float z1 = (c > 0) ? 1.0f : 0.0f;
;         float P = 1.0f, r1 = bf2f(sr_[0]) * z1, k1 = bf2f(sk_[0]) * z1, v1 = bf2f(sv_[0]) * z1;
;     ...
;         for (int t = 0; t < 16; ++t) {
;             const float r0 = bf2f(sr_[t + 1]), k0 = bf2f(sk_[t + 1]), v0 = bf2f(sv_[t + 1]);
;             const float r = r0 + (r1 - r0) * mu_r, k = k0 + (k1 - k0) * mu_k, v = v0 + (v1 - v0) * mu_v; r1 = r0; k1 = k0; v1 = v0;
;             const float z = -(w0c + bf2f(slw[t])); const float sp = fmaxf(z, 0.f) + flog(1.0f + fexp(-fabsf(z))); const float w = -sp - 0.5f;
;             const float dec = fexp(-fexp(w)); const float a = fsigmoid(a0c + bf2f(sla[t]));
;             float kk = k * kkc; const float n2 = wsum_dpp(kk * kk); kk = kk / fmaxf(sqrtf(n2), 1e-12f);
;             const float kp = bf2f(f2bf(k * (1.0f + (a - 1.0f) * kac))), bb = bf2f(f2bf(kk * a)), rr = bf2f(f2bf(r)); kk = bf2f(f2bf(kk));
;             const float coef = wsum_dpp(rr * kp * rkc);
;             SV[(ib + t) * 64 + lane] = f2bf(v);
;             if (lane == 0) COEF[(size_t)(m0 + t) * 16 + h] = coef;
;             const float Pp = P; P *= dec; const float inv = 1.0f / P;
;             XKK[t * 72 + lane] = f2bf(kk * Pp); XR[t * 72 + lane] = f2bf(rr * P); XK[t * 72 + lane] = f2bf(kp * inv); XB[t * 72 + lane] = f2bf(bb * inv); }
.LBB0_289:
	s_or_b64 exec, exec, s[4:5]
	s_add_i32 s0, s11, s16
	s_cmpk_gt_i32 s0, 0x3fff
	s_cbranch_scc1 .Lpcpf_skip_3
	s_bfe_u32 s1, s0, 0x40008
	v_lshl_or_b32 v152, s1, 6, v185
	s_and_b32 s1, s0, 0xff
	s_and_b32 s0, s0, 0xfffff000
	s_lshl_b32 s1, s1, 4
	s_or_b32 s0, s0, s1
	v_lshlrev_b32_e32 v154, 2, v152
	v_lshlrev_b32_e32 v152, 1, v152
	v_mov_b32_e32 v153, 0
	v_mov_b32_e32 v155, 0
	v_readlane_b32 vcc_lo, v255, 13
	v_readlane_b32 vcc_hi, v255, 14
	s_nop 1
	s_add_u32 vcc_lo, vcc_lo, 0x1000
	s_addc_u32 vcc_hi, vcc_hi, 0
	v_lshl_add_u64 v[150:151], vcc, 0, v[154:155]
	global_load_dword v156, v[150:151], off offset:-4096
	global_load_dword v157, v[150:151], off
	s_add_u32 vcc_lo, vcc_lo, 0x1000
	s_addc_u32 vcc_hi, vcc_hi, 0
	v_lshl_add_u64 v[150:151], vcc, 0, v[154:155]
	global_load_dword v158, v[150:151], off
	v_readlane_b32 vcc_lo, v255, 15
	v_readlane_b32 vcc_hi, v255, 16
	s_nop 1
	v_lshl_add_u64 v[150:151], vcc, 0, v[154:155]
	global_load_dword v159, v[150:151], off
	v_readlane_b32 vcc_lo, v255, 20
	v_readlane_b32 vcc_hi, v255, 21
	s_nop 1
	v_lshl_add_u64 v[150:151], vcc, 0, v[154:155]
	global_load_dword v160, v[150:151], off
	v_readlane_b32 vcc_lo, v255, 22
	v_readlane_b32 vcc_hi, v255, 23
	s_nop 1
	v_lshl_add_u64 v[150:151], vcc, 0, v[154:155]
	global_load_dword v161, v[150:151], off
	v_readlane_b32 vcc_lo, v255, 24
	v_readlane_b32 vcc_hi, v255, 25
	s_nop 1
	v_lshl_add_u64 v[150:151], vcc, 0, v[154:155]
	global_load_dword v162, v[150:151], off
	v_readlane_b32 vcc_lo, v255, 26
	v_readlane_b32 vcc_hi, v255, 27
	s_nop 1
	v_lshl_add_u64 v[150:151], vcc, 0, v[154:155]
	global_load_dword v163, v[150:151], off
	v_readlane_b32 vcc_lo, v254, 63
	v_readlane_b32 vcc_hi, v255, 0
	s_mul_i32 s1, s0, 0x3400
	s_add_u32 vcc_lo, vcc_lo, s1
	s_addc_u32 vcc_hi, vcc_hi, 0
	s_add_u32 vcc_lo, vcc_lo, 0x2000
	s_addc_u32 vcc_hi, vcc_hi, 0
	v_lshl_add_u64 v[146:147], vcc, 0, v[152:153]
	s_and_b32 s1, s0, 0xff0
	s_cmp_eq_u32 s1, 0
	s_cselect_b32 s1, 0, 0x3400
	s_sub_u32 vcc_lo, vcc_lo, s1
	s_subb_u32 vcc_hi, vcc_hi, 0
	v_lshl_add_u64 v[150:151], vcc, 0, v[152:153]
	global_load_ushort v134, v[150:151], off offset:-2048
	global_load_ushort v135, v[150:151], off
	global_load_ushort v138, v[150:151], off offset:2048
	v_readlane_b32 vcc_lo, v255, 1
	v_readlane_b32 vcc_hi, v255, 2
	s_mul_i32 s1, s0, 0x1800
	s_add_u32 vcc_lo, vcc_lo, s1
	s_addc_u32 vcc_hi, vcc_hi, 0
	v_lshl_add_u64 v[148:149], vcc, 0, v[152:153]
	global_load_ushort v132, v[148:149], off
	global_load_ushort v136, v[146:147], off offset:-2048
	global_load_ushort v137, v[146:147], off
	global_load_ushort v139, v[146:147], off offset:2048
	global_load_ushort v133, v[148:149], off offset:2048
.Lpcpf_skip_3:
	v_lshlrev_b32_e32 v117, 16, v117
	v_add_f32_e32 v117, v8, v117
	v_mul_f32_e64 v125, |v117|, s19
	v_exp_f32_e32 v125, v125
	v_mov_b32_e32 v126, s8
	v_mov_b32_e32 v127, s9
	v_add_f32_e32 v126, s7, v126
	v_add_f32_e32 v125, 1.0, v125
	v_log_f32_e32 v125, v125
	v_add_f32_e32 v127, s6, v127
	v_max_f32_e64 v117, -v117, 0
	v_add_f32_e32 v126, v126, v127
	v_fmac_f32_e32 v117, 0x3f317218, v125
	v_mul_f32_e32 v125, 0x4f800000, v126
	v_cmp_gt_f32_e32 vcc, s33, v126
	v_sub_f32_e32 v117, -0.5, v117
	v_mul_f32_e32 v117, 0x3fb8aa3b, v117
	v_cndmask_b32_e32 v125, v126, v125, vcc
	v_sqrt_f32_e32 v126, v125
	v_exp_f32_e32 v117, v117
	v_lshlrev_b32_e32 v113, 16, v113
	v_add_f32_e32 v113, v15, v113
	v_add_u32_e32 v127, -1, v126
	v_fma_f32 v128, -v127, v126, v125
	v_cmp_ge_f32_e64 s[56:57], 0, v128
	v_add_u32_e32 v128, 1, v126
	v_mul_f32_e32 v117, 0xbfb8aa3b, v117
	v_cndmask_b32_e64 v127, v126, v127, s[56:57]
	v_fma_f32 v126, -v128, v126, v125
	v_cmp_lt_f32_e64 s[56:57], 0, v126
	v_exp_f32_e32 v117, v117
	v_mul_f32_e32 v113, 0xbfb8aa3b, v113
	v_cndmask_b32_e64 v126, v127, v128, s[56:57]
	v_mul_f32_e32 v127, 0x37800000, v126
	v_cndmask_b32_e32 v126, v126, v127, vcc
	v_cmp_class_f32_e32 vcc, v125, v219
	v_mul_f32_e32 v117, v96, v117
	v_lshlrev_b32_e32 v115, 16, v115
	v_cndmask_b32_e32 v125, v126, v125, vcc
	v_max_f32_e32 v125, 0x2b8cbccc, v125
	v_div_scale_f32 v126, s[0:1], v125, v125, v124
	v_rcp_f32_e32 v127, v126
	v_exp_f32_e32 v113, v113
	v_fma_f32 v128, -v126, v127, 1.0
	v_fmac_f32_e32 v127, v128, v127
	v_div_scale_f32 v128, vcc, v124, v125, v124
	v_mul_f32_e32 v129, v128, v127
	v_fma_f32 v130, -v126, v129, v128
	v_fmac_f32_e32 v129, v130, v127
	v_fma_f32 v126, -v126, v129, v128
	v_div_fmas_f32 v126, v126, v127, v129
	v_div_fixup_f32 v124, v126, v125, v124
	v_mul_f32_e32 v123, v123, v124
	v_cvt_pk_bf16_f32 v123, v123, s0
	v_div_scale_f32 v125, s[0:1], v117, v117, 1.0
	v_rcp_f32_e32 v126, v125
	s_nop 0
	v_cvt_pk_bf16_f32 v124, v124, s0
	v_lshlrev_b32_e32 v124, 16, v124
	v_mul_f32_e32 v96, v96, v124
	v_fma_f32 v127, -v125, v126, 1.0
	v_fmac_f32_e32 v126, v127, v126
	v_div_scale_f32 v127, vcc, 1.0, v117, 1.0
	v_mul_f32_e32 v128, v127, v126
	v_fma_f32 v129, -v125, v128, v127
	v_fmac_f32_e32 v128, v129, v126
	v_fma_f32 v125, -v125, v128, v127
	v_cvt_pk_bf16_f32 v96, v96, s0
	v_div_fmas_f32 v125, v125, v126, v128
	ds_write_b16 v27, v96 offset:432
	v_mul_f32_e32 v96, v117, v121
	v_div_fixup_f32 v125, v125, v117, 1.0
	v_cvt_pk_bf16_f32 v96, v96, s0
	ds_write_b16 v27, v96 offset:2736
	v_mul_f32_e32 v96, v125, v118
	v_lshlrev_b32_e32 v123, 16, v123
	v_cvt_pk_bf16_f32 v96, v96, s0
	ds_write_b16 v27, v96 offset:5040
	v_mul_f32_e32 v96, v125, v123
	v_cvt_pk_bf16_f32 v96, v96, s0
	v_lshlrev_b32_e32 v118, 16, v114
	ds_write_b16 v27, v96 offset:7344
	v_sub_f32_e32 v96, v122, v118
	v_lshlrev_b32_e32 v114, 16, v116
	v_fma_f32 v116, v10, v96, v118
	v_sub_f32_e32 v96, v120, v115
	v_fma_f32 v120, v9, v96, v115
	v_sub_f32_e32 v96, v119, v114
; __device__ __forceinline__ float bf2f(bf16 b) { return __uint_as_float((unsigned)b << 16); }
; __device__ __forceinline__ bf16 f2bf(float f) { return (bf16)(pk_bf16(f, 0.f) & 0xffffu); }
; __device__ __forceinline__ float fexp(float x) { return __builtin_amdgcn_exp2f(x * 1.4426950408889634f); }
; __device__ __forceinline__ float flog(float x) { return __builtin_amdgcn_logf(x) * 0.6931471805599453f; }
; __device__ __forceinline__ float fsigmoid(float x) { return __builtin_amdgcn_rcpf(1.0f + fexp(-x)); }
; __device__ __forceinline__ void pc_phase(LAS unsigned char* lds, const bf16* Pp_, const bf16* LO, const float* mu, const float* w0, const float* a0, const float* k_k, const float* k_a, const float* r_k, ...
;     ...
;         for (int t = 0; t < 16; ++t) {
;             const float r0 = bf2f(sr_[t + 1]), k0 = bf2f(sk_[t + 1]), v0 = bf2f(sv_[t + 1]);
;             const float r = r0 + (r1 - r0) * mu_r, k = k0 + (k1 - k0) * mu_k, v = v0 + (v1 - v0) * mu_v; r1 = r0; k1 = k0; v1 = v0;
;             const float z = -(w0c + bf2f(slw[t])); const float sp = fmaxf(z, 0.f) + flog(1.0f + fexp(-fabsf(z))); const float w = -sp - 0.5f;
;             const float dec = fexp(-fexp(w)); const float a = fsigmoid(a0c + bf2f(sla[t]));
;             float kk = k * kkc; const float n2 = wsum_dpp(kk * kk); kk = kk / fmaxf(sqrtf(n2), 1e-12f);
;             const float kp = bf2f(f2bf(k * (1.0f + (a - 1.0f) * kac))), bb = bf2f(f2bf(kk * a)), rr = bf2f(f2bf(r)); kk = bf2f(f2bf(kk));
;             const float coef = wsum_dpp(rr * kp * rkc);
;             SV[(ib + t) * 64 + lane] = f2bf(v);
;             if (lane == 0) COEF[(size_t)(m0 + t) * 16 + h] = coef;
;             const float Pp = P; P *= dec; const float inv = 1.0f / P;
;             XKK[t * 72 + lane] = f2bf(kk * Pp); XR[t * 72 + lane] = f2bf(rr * P); XK[t * 72 + lane] = f2bf(kp * inv); XB[t * 72 + lane] = f2bf(bb * inv); }
	v_mul_f32_e32 v119, v14, v120
	v_fma_f32 v121, v12, v96, v114
	v_add_f32_e32 v96, 1.0, v113
	v_mul_f32_e32 v113, v119, v119
	v_rcp_f32_e32 v96, v96
	v_cvt_pk_bf16_f32 v116, v116, s0
	v_mov_b32_dpp v113, v113 quad_perm:[1,0,3,2] row_mask:0xf bank_mask:0xf bound_ctrl:1
	v_fmac_f32_e32 v113, v119, v119
	v_lshlrev_b32_e32 v116, 16, v116
	s_nop 0
	v_add_f32_dpp v113, v113, v113 quad_perm:[2,3,0,1] row_mask:0xf bank_mask:0xf bound_ctrl:1
	s_nop 1
	v_add_f32_dpp v113, v113, v113 row_ror:4 row_mask:0xf bank_mask:0xf bound_ctrl:1
	s_nop 1
	v_add_f32_dpp v113, v113, v113 row_ror:8 row_mask:0xf bank_mask:0xf bound_ctrl:1
	s_nop 0
	v_readlane_b32 s7, v113, 0
	v_readlane_b32 s8, v113, 16
	v_readlane_b32 s6, v113, 32
	v_readlane_b32 s9, v113, 48
	v_add_f32_e32 v113, -1.0, v96
	v_fma_f32 v113, v13, v113, 1.0
	v_mul_f32_e32 v113, v120, v113
	v_cvt_pk_bf16_f32 v113, v113, s0
	v_lshlrev_b32_e32 v113, 16, v113
	v_mul_f32_e32 v120, v116, v113
	v_mul_f32_e32 v122, v11, v120
	s_nop 1
	v_mov_b32_dpp v122, v122 quad_perm:[1,0,3,2] row_mask:0xf bank_mask:0xf bound_ctrl:1
	v_fmac_f32_e32 v122, v11, v120
	s_nop 1
	v_add_f32_dpp v120, v122, v122 quad_perm:[2,3,0,1] row_mask:0xf bank_mask:0xf bound_ctrl:1
	s_nop 1
	v_add_f32_dpp v120, v120, v120 row_ror:4 row_mask:0xf bank_mask:0xf bound_ctrl:1
	s_nop 1
	v_add_f32_dpp v120, v120, v120 row_ror:8 row_mask:0xf bank_mask:0xf bound_ctrl:1
	s_nop 0
	v_readlane_b32 s0, v120, 0
	v_readlane_b32 s15, v120, 16
	v_readlane_b32 s1, v120, 32
	v_readlane_b32 s17, v120, 48
	v_add_co_u32_e32 v120, vcc, 0x33600000, v6
	v_cvt_pk_bf16_f32 v122, v121, s0
	s_nop 0
	v_addc_co_u32_e32 v121, vcc, 0, v7, vcc
	global_store_short v[120:121], v122, off offset:512
	s_and_saveexec_b64 s[4:5], s[38:39]
	s_cbranch_execz .LBB0_291
	s_ashr_i32 s73, s72, 31
	s_lshl_b64 s[30:31], s[72:73], 6
	s_add_u32 s30, s2, s30
	v_mov_b32_e32 v120, s15
	v_mov_b32_e32 v121, s17
	s_addc_u32 s31, s14, s31
	v_pk_add_f32 v[120:121], s[0:1], v[120:121]
	s_nop 0
	v_add_f32_e32 v122, v120, v121
	v_mov_b64_e32 v[120:121], s[30:31]
	global_store_dword v[120:121], v122, off
.LBB0_291:
	s_or_b64 exec, exec, s[4:5]
	s_add_i32 s0, s11, s16
	s_cmpk_gt_i32 s0, 0x3fff
	s_cbranch_scc1 .Lpcpf_skip_4
	s_movk_i32 s0, 0x3400
	s_mov_b32 s1, 0
	v_lshl_add_u64 v[146:147], v[146:147], 0, s[0:1]
	s_movk_i32 s0, 0x1800
	v_lshl_add_u64 v[148:149], v[148:149], 0, s[0:1]
	global_load_ushort v129, v[146:147], off offset:-2048
	global_load_ushort v130, v[146:147], off
	global_load_ushort v131, v[146:147], off offset:2048
	global_load_ushort v127, v[148:149], off
	global_load_ushort v128, v[148:149], off offset:2048
.Lpcpf_skip_4:
	v_lshlrev_b32_e32 v112, 16, v112
	v_add_f32_e32 v112, v8, v112
	v_mul_f32_e64 v120, |v112|, s19
	v_exp_f32_e32 v120, v120
	v_mov_b32_e32 v121, s8
	v_mov_b32_e32 v122, s9
	v_add_f32_e32 v121, s7, v121
	v_add_f32_e32 v120, 1.0, v120
	v_log_f32_e32 v120, v120
	v_add_f32_e32 v122, s6, v122
	v_max_f32_e64 v112, -v112, 0
	v_add_f32_e32 v121, v121, v122
	v_fmac_f32_e32 v112, 0x3f317218, v120
	v_mul_f32_e32 v120, 0x4f800000, v121
	v_cmp_gt_f32_e32 vcc, s33, v121
	v_sub_f32_e32 v112, -0.5, v112
	v_mul_f32_e32 v112, 0x3fb8aa3b, v112
	v_cndmask_b32_e32 v120, v121, v120, vcc
	v_sqrt_f32_e32 v121, v120
	v_exp_f32_e32 v112, v112
	v_lshlrev_b32_e32 v108, 16, v108
	v_add_f32_e32 v108, v15, v108
	v_add_u32_e32 v122, -1, v121
	v_fma_f32 v123, -v122, v121, v120
	v_cmp_ge_f32_e64 s[56:57], 0, v123
	v_add_u32_e32 v123, 1, v121
	v_mul_f32_e32 v112, 0xbfb8aa3b, v112
	v_cndmask_b32_e64 v122, v121, v122, s[56:57]
	v_fma_f32 v121, -v123, v121, v120
	v_cmp_lt_f32_e64 s[56:57], 0, v121
	v_exp_f32_e32 v112, v112
	v_mul_f32_e32 v108, 0xbfb8aa3b, v108
	v_cndmask_b32_e64 v121, v122, v123, s[56:57]
	v_mul_f32_e32 v122, 0x37800000, v121
	v_cndmask_b32_e32 v121, v121, v122, vcc
	v_cmp_class_f32_e32 vcc, v120, v219
	v_exp_f32_e32 v108, v108
	v_lshlrev_b32_e32 v110, 16, v110
	v_cndmask_b32_e32 v120, v121, v120, vcc
	v_max_f32_e32 v120, 0x2b8cbccc, v120
	v_div_scale_f32 v121, s[0:1], v120, v120, v119
	v_rcp_f32_e32 v122, v121
	v_add_f32_e32 v108, 1.0, v108
	v_fma_f32 v123, -v121, v122, 1.0
	v_fmac_f32_e32 v122, v123, v122
	v_div_scale_f32 v123, vcc, v119, v120, v119
	v_mul_f32_e32 v124, v123, v122
	v_fma_f32 v125, -v121, v124, v123
	v_fmac_f32_e32 v124, v125, v122
	v_fma_f32 v121, -v121, v124, v123
	v_div_fmas_f32 v121, v121, v122, v124
	v_div_fixup_f32 v119, v121, v120, v119
	v_mul_f32_e32 v96, v96, v119
	v_cvt_pk_bf16_f32 v120, v96, s0
	v_mul_f32_e32 v96, v117, v112
	v_div_scale_f32 v112, s[0:1], v96, v96, 1.0
	v_rcp_f32_e32 v121, v112
	v_lshlrev_b32_e32 v120, 16, v120
	v_mul_f32_e32 v116, v96, v116
	v_cvt_pk_bf16_f32 v116, v116, s0
	v_fma_f32 v122, -v112, v121, 1.0
	v_fmac_f32_e32 v121, v122, v121
	v_div_scale_f32 v122, vcc, 1.0, v96, 1.0
	v_mul_f32_e32 v123, v122, v121
	v_fma_f32 v124, -v112, v123, v122
	v_fmac_f32_e32 v123, v124, v121
	v_fma_f32 v112, -v112, v123, v122
	v_div_fmas_f32 v112, v112, v121, v123
	v_div_fixup_f32 v112, v112, v96, 1.0
	v_mul_f32_e32 v113, v112, v113
	v_cvt_pk_bf16_f32 v113, v113, s0
	v_mul_f32_e32 v112, v112, v120
	ds_write_b16 v27, v113 offset:5184
	v_cvt_pk_bf16_f32 v112, v112, s0
	v_sub_f32_e32 v113, v115, v110
	ds_write_b16 v27, v112 offset:7488
	v_lshlrev_b32_e32 v112, 16, v109
	v_lshlrev_b32_e32 v109, 16, v111
	v_fma_f32 v115, v9, v113, v110
	v_sub_f32_e32 v113, v114, v109
	v_mul_f32_e32 v114, v14, v115
	ds_write_b16 v27, v116 offset:2880
	v_fma_f32 v116, v12, v113, v109
	v_rcp_f32_e32 v113, v108
	v_mul_f32_e32 v108, v114, v114
	v_sub_f32_e32 v111, v118, v112
	v_cvt_pk_bf16_f32 v119, v119, s0
	v_mov_b32_dpp v108, v108 quad_perm:[1,0,3,2] row_mask:0xf bank_mask:0xf bound_ctrl:1
; __device__ __forceinline__ float bf2f(bf16 b) { return __uint_as_float((unsigned)b << 16); }
; __device__ __forceinline__ bf16 f2bf(float f) { return (bf16)(pk_bf16(f, 0.f) & 0xffffu); }
; __device__ __forceinline__ float fexp(float x) { return __builtin_amdgcn_exp2f(x * 1.4426950408889634f); }
; __device__ __forceinline__ float flog(float x) { return __builtin_amdgcn_logf(x) * 0.6931471805599453f; }
; __device__ __forceinline__ float fsigmoid(float x) { return __builtin_amdgcn_rcpf(1.0f + fexp(-x)); }
; __device__ __forceinline__ void pc_phase(LAS unsigned char* lds, const bf16* Pp_, const bf16* LO, const float* mu, const float* w0, const float* a0, const float* k_k, const float* k_a, const float* r_k, ...
;     ...
;         for (int t = 0; t < 16; ++t) {
;             const float r0 = bf2f(sr_[t + 1]), k0 = bf2f(sk_[t + 1]), v0 = bf2f(sv_[t + 1]);
;             const float r = r0 + (r1 - r0) * mu_r, k = k0 + (k1 - k0) * mu_k, v = v0 + (v1 - v0) * mu_v; r1 = r0; k1 = k0; v1 = v0;
;             const float z = -(w0c + bf2f(slw[t])); const float sp = fmaxf(z, 0.f) + flog(1.0f + fexp(-fabsf(z))); const float w = -sp - 0.5f;
;             const float dec = fexp(-fexp(w)); const float a = fsigmoid(a0c + bf2f(sla[t]));
;             float kk = k * kkc; const float n2 = wsum_dpp(kk * kk); kk = kk / fmaxf(sqrtf(n2), 1e-12f);
;             const float kp = bf2f(f2bf(k * (1.0f + (a - 1.0f) * kac))), bb = bf2f(f2bf(kk * a)), rr = bf2f(f2bf(r)); kk = bf2f(f2bf(kk));
;             const float coef = wsum_dpp(rr * kp * rkc);
;             SV[(ib + t) * 64 + lane] = f2bf(v);
;             if (lane == 0) COEF[(size_t)(m0 + t) * 16 + h] = coef;
;             const float Pp = P; P *= dec; const float inv = 1.0f / P;
;             XKK[t * 72 + lane] = f2bf(kk * Pp); XR[t * 72 + lane] = f2bf(rr * P); XK[t * 72 + lane] = f2bf(kp * inv); XB[t * 72 + lane] = f2bf(bb * inv); }
	v_fmac_f32_e32 v108, v114, v114
	v_fma_f32 v111, v10, v111, v112
	v_lshlrev_b32_e32 v119, 16, v119
	v_add_f32_dpp v108, v108, v108 quad_perm:[2,3,0,1] row_mask:0xf bank_mask:0xf bound_ctrl:1
	v_cvt_pk_bf16_f32 v111, v111, s0
	v_mul_f32_e32 v117, v117, v119
	v_add_f32_dpp v108, v108, v108 row_ror:4 row_mask:0xf bank_mask:0xf bound_ctrl:1
	v_lshlrev_b32_e32 v111, 16, v111
	v_cvt_pk_bf16_f32 v117, v117, s0
	v_add_f32_dpp v108, v108, v108 row_ror:8 row_mask:0xf bank_mask:0xf bound_ctrl:1
	ds_write_b16 v27, v117 offset:576
	v_readlane_b32 s7, v108, 0
	v_readlane_b32 s8, v108, 16
	v_readlane_b32 s6, v108, 32
	v_readlane_b32 s9, v108, 48
	v_add_f32_e32 v108, -1.0, v113
	v_fma_f32 v108, v13, v108, 1.0
	v_mul_f32_e32 v108, v115, v108
	v_cvt_pk_bf16_f32 v108, v108, s0
	v_lshlrev_b32_e32 v108, 16, v108
	v_mul_f32_e32 v115, v111, v108
	v_mul_f32_e32 v117, v11, v115
	s_nop 1
	v_mov_b32_dpp v117, v117 quad_perm:[1,0,3,2] row_mask:0xf bank_mask:0xf bound_ctrl:1
	v_fmac_f32_e32 v117, v11, v115
	s_nop 1
	v_add_f32_dpp v115, v117, v117 quad_perm:[2,3,0,1] row_mask:0xf bank_mask:0xf bound_ctrl:1
	s_nop 1
	v_add_f32_dpp v115, v115, v115 row_ror:4 row_mask:0xf bank_mask:0xf bound_ctrl:1
	s_nop 1
	v_add_f32_dpp v115, v115, v115 row_ror:8 row_mask:0xf bank_mask:0xf bound_ctrl:1
	s_nop 0
	v_readlane_b32 s0, v115, 0
	v_readlane_b32 s15, v115, 16
	v_readlane_b32 s1, v115, 32
	v_readlane_b32 s17, v115, 48
	v_cvt_pk_bf16_f32 v115, v116, s0
	v_add_co_u32_e32 v116, vcc, 0x33600000, v6
	s_nop 1
	v_addc_co_u32_e32 v117, vcc, 0, v7, vcc
	global_store_short v[116:117], v115, off offset:640
	s_and_saveexec_b64 s[4:5], s[38:39]
	s_cbranch_execz .LBB0_293
	s_ashr_i32 s69, s68, 31
	s_lshl_b64 s[30:31], s[68:69], 6
	s_add_u32 s30, s2, s30
	v_mov_b32_e32 v116, s15
	v_mov_b32_e32 v117, s17
	s_addc_u32 s31, s14, s31
	v_pk_add_f32 v[116:117], s[0:1], v[116:117]
	s_nop 0
	v_add_f32_e32 v115, v116, v117
	v_mov_b64_e32 v[116:117], s[30:31]
	global_store_dword v[116:117], v115, off
.LBB0_293:
	s_or_b64 exec, exec, s[4:5]
	s_add_i32 s0, s11, s16
	s_cmpk_gt_i32 s0, 0x3fff
	s_cbranch_scc1 .Lpcpf_skip_5
	s_movk_i32 s0, 0x3400
	s_mov_b32 s1, 0
	v_lshl_add_u64 v[146:147], v[146:147], 0, s[0:1]
	s_movk_i32 s0, 0x1800
	v_lshl_add_u64 v[148:149], v[148:149], 0, s[0:1]
	global_load_ushort v124, v[146:147], off offset:-2048
	global_load_ushort v125, v[146:147], off
	global_load_ushort v126, v[146:147], off offset:2048
	global_load_ushort v122, v[148:149], off
	global_load_ushort v123, v[148:149], off offset:2048
.Lpcpf_skip_5:
	v_lshlrev_b32_e32 v107, 16, v107
	v_add_f32_e32 v107, v8, v107
	v_mul_f32_e64 v115, |v107|, s19
	v_exp_f32_e32 v115, v115
	v_mov_b32_e32 v116, s8
	v_mov_b32_e32 v117, s9
	v_add_f32_e32 v116, s7, v116
	v_add_f32_e32 v115, 1.0, v115
	v_log_f32_e32 v115, v115
	v_add_f32_e32 v117, s6, v117
	v_max_f32_e64 v107, -v107, 0
	v_add_f32_e32 v116, v116, v117
	v_fmac_f32_e32 v107, 0x3f317218, v115
	v_mul_f32_e32 v115, 0x4f800000, v116
	v_cmp_gt_f32_e32 vcc, s33, v116
	v_sub_f32_e32 v107, -0.5, v107
	v_mul_f32_e32 v107, 0x3fb8aa3b, v107
	v_cndmask_b32_e32 v115, v116, v115, vcc
	v_sqrt_f32_e32 v116, v115
	v_exp_f32_e32 v107, v107
	v_lshlrev_b32_e32 v103, 16, v103
	v_add_f32_e32 v103, v15, v103
	v_add_u32_e32 v117, -1, v116
	v_fma_f32 v118, -v117, v116, v115
	v_cmp_ge_f32_e64 s[56:57], 0, v118
	v_add_u32_e32 v118, 1, v116
	v_mul_f32_e32 v107, 0xbfb8aa3b, v107
	v_cndmask_b32_e64 v117, v116, v117, s[56:57]
	v_fma_f32 v116, -v118, v116, v115
	v_cmp_lt_f32_e64 s[56:57], 0, v116
	v_exp_f32_e32 v107, v107
	v_mul_f32_e32 v103, 0xbfb8aa3b, v103
	v_cndmask_b32_e64 v116, v117, v118, s[56:57]
	v_mul_f32_e32 v117, 0x37800000, v116
	v_cndmask_b32_e32 v116, v116, v117, vcc
	v_cmp_class_f32_e32 vcc, v115, v219
	v_mul_f32_e32 v107, v96, v107
	v_lshlrev_b32_e32 v105, 16, v105
	v_cndmask_b32_e32 v115, v116, v115, vcc
	v_max_f32_e32 v115, 0x2b8cbccc, v115
	v_div_scale_f32 v116, s[0:1], v115, v115, v114
	v_rcp_f32_e32 v117, v116
	v_exp_f32_e32 v103, v103
	v_fma_f32 v118, -v116, v117, 1.0
	v_fmac_f32_e32 v117, v118, v117
	v_div_scale_f32 v118, vcc, v114, v115, v114
	v_mul_f32_e32 v119, v118, v117
	v_fma_f32 v120, -v116, v119, v118
	v_fmac_f32_e32 v119, v120, v117
	v_fma_f32 v116, -v116, v119, v118
	v_div_fmas_f32 v116, v116, v117, v119
	v_div_fixup_f32 v114, v116, v115, v114
	v_mul_f32_e32 v113, v113, v114
	v_cvt_pk_bf16_f32 v113, v113, s0
	v_div_scale_f32 v115, s[0:1], v107, v107, 1.0
	v_rcp_f32_e32 v116, v115
	s_nop 0
	v_cvt_pk_bf16_f32 v114, v114, s0
	v_lshlrev_b32_e32 v114, 16, v114
	v_mul_f32_e32 v96, v96, v114
	v_fma_f32 v117, -v115, v116, 1.0
	v_fmac_f32_e32 v116, v117, v116
	v_div_scale_f32 v117, vcc, 1.0, v107, 1.0
	v_mul_f32_e32 v118, v117, v116
	v_fma_f32 v119, -v115, v118, v117
	v_fmac_f32_e32 v118, v119, v116
	v_fma_f32 v115, -v115, v118, v117
	v_cvt_pk_bf16_f32 v96, v96, s0
	v_div_fmas_f32 v115, v115, v116, v118
	ds_write_b16 v27, v96 offset:720
	v_mul_f32_e32 v96, v107, v111
	v_div_fixup_f32 v115, v115, v107, 1.0
	v_cvt_pk_bf16_f32 v96, v96, s0
	ds_write_b16 v27, v96 offset:3024
	v_mul_f32_e32 v96, v115, v108
	v_lshlrev_b32_e32 v113, 16, v113
	v_cvt_pk_bf16_f32 v96, v96, s0
	ds_write_b16 v27, v96 offset:5328
	v_mul_f32_e32 v96, v115, v113
	v_cvt_pk_bf16_f32 v96, v96, s0
	v_lshlrev_b32_e32 v108, 16, v104
	ds_write_b16 v27, v96 offset:7632
	v_sub_f32_e32 v96, v112, v108
	v_lshlrev_b32_e32 v104, 16, v106
	v_fma_f32 v106, v10, v96, v108
	v_sub_f32_e32 v96, v110, v105
	v_fma_f32 v110, v9, v96, v105
	v_sub_f32_e32 v96, v109, v104
	v_mul_f32_e32 v109, v14, v110
	v_fma_f32 v111, v12, v96, v104
	v_add_f32_e32 v96, 1.0, v103
	v_mul_f32_e32 v103, v109, v109
	v_rcp_f32_e32 v96, v96
	v_cvt_pk_bf16_f32 v106, v106, s0
; __device__ __forceinline__ float bf2f(bf16 b) { return __uint_as_float((unsigned)b << 16); }
; __device__ __forceinline__ bf16 f2bf(float f) { return (bf16)(pk_bf16(f, 0.f) & 0xffffu); }
; __device__ __forceinline__ float fexp(float x) { return __builtin_amdgcn_exp2f(x * 1.4426950408889634f); }
; __device__ __forceinline__ float flog(float x) { return __builtin_amdgcn_logf(x) * 0.6931471805599453f; }
; __device__ __forceinline__ float fsigmoid(float x) { return __builtin_amdgcn_rcpf(1.0f + fexp(-x)); }
; __device__ __forceinline__ void pc_phase(LAS unsigned char* lds, const bf16* Pp_, const bf16* LO, const float* mu, const float* w0, const float* a0, const float* k_k, const float* k_a, const float* r_k, ...
;     ...
;         for (int t = 0; t < 16; ++t) {
;             const float r0 = bf2f(sr_[t + 1]), k0 = bf2f(sk_[t + 1]), v0 = bf2f(sv_[t + 1]);
;             const float r = r0 + (r1 - r0) * mu_r, k = k0 + (k1 - k0) * mu_k, v = v0 + (v1 - v0) * mu_v; r1 = r0; k1 = k0; v1 = v0;
;             const float z = -(w0c + bf2f(slw[t])); const float sp = fmaxf(z, 0.f) + flog(1.0f + fexp(-fabsf(z))); const float w = -sp - 0.5f;
;             const float dec = fexp(-fexp(w)); const float a = fsigmoid(a0c + bf2f(sla[t]));
;             float kk = k * kkc; const float n2 = wsum_dpp(kk * kk); kk = kk / fmaxf(sqrtf(n2), 1e-12f);
;             const float kp = bf2f(f2bf(k * (1.0f + (a - 1.0f) * kac))), bb = bf2f(f2bf(kk * a)), rr = bf2f(f2bf(r)); kk = bf2f(f2bf(kk));
;             const float coef = wsum_dpp(rr * kp * rkc);
;             SV[(ib + t) * 64 + lane] = f2bf(v);
;             if (lane == 0) COEF[(size_t)(m0 + t) * 16 + h] = coef;
;             const float Pp = P; P *= dec; const float inv = 1.0f / P;
;             XKK[t * 72 + lane] = f2bf(kk * Pp); XR[t * 72 + lane] = f2bf(rr * P); XK[t * 72 + lane] = f2bf(kp * inv); XB[t * 72 + lane] = f2bf(bb * inv); }
	v_mov_b32_dpp v103, v103 quad_perm:[1,0,3,2] row_mask:0xf bank_mask:0xf bound_ctrl:1
	v_fmac_f32_e32 v103, v109, v109
	v_lshlrev_b32_e32 v106, 16, v106
	s_nop 0
	v_add_f32_dpp v103, v103, v103 quad_perm:[2,3,0,1] row_mask:0xf bank_mask:0xf bound_ctrl:1
	s_nop 1
	v_add_f32_dpp v103, v103, v103 row_ror:4 row_mask:0xf bank_mask:0xf bound_ctrl:1
	s_nop 1
	v_add_f32_dpp v103, v103, v103 row_ror:8 row_mask:0xf bank_mask:0xf bound_ctrl:1
	s_nop 0
	v_readlane_b32 s7, v103, 0
	v_readlane_b32 s8, v103, 16
	v_readlane_b32 s6, v103, 32
	v_readlane_b32 s9, v103, 48
	v_add_f32_e32 v103, -1.0, v96
	v_fma_f32 v103, v13, v103, 1.0
	v_mul_f32_e32 v103, v110, v103
	v_cvt_pk_bf16_f32 v103, v103, s0
	v_lshlrev_b32_e32 v103, 16, v103
	v_mul_f32_e32 v110, v106, v103
	v_mul_f32_e32 v112, v11, v110
	s_nop 1
	v_mov_b32_dpp v112, v112 quad_perm:[1,0,3,2] row_mask:0xf bank_mask:0xf bound_ctrl:1
	v_fmac_f32_e32 v112, v11, v110
	s_nop 1
	v_add_f32_dpp v110, v112, v112 quad_perm:[2,3,0,1] row_mask:0xf bank_mask:0xf bound_ctrl:1
	s_nop 1
	v_add_f32_dpp v110, v110, v110 row_ror:4 row_mask:0xf bank_mask:0xf bound_ctrl:1
	s_nop 1
	v_add_f32_dpp v110, v110, v110 row_ror:8 row_mask:0xf bank_mask:0xf bound_ctrl:1
	s_nop 0
	v_readlane_b32 s0, v110, 0
	v_readlane_b32 s15, v110, 16
	v_readlane_b32 s1, v110, 32
	v_readlane_b32 s17, v110, 48
	v_add_co_u32_e32 v110, vcc, 0x33600000, v6
	v_cvt_pk_bf16_f32 v112, v111, s0
	s_nop 0
	v_addc_co_u32_e32 v111, vcc, 0, v7, vcc
	global_store_short v[110:111], v112, off offset:768
	s_and_saveexec_b64 s[4:5], s[38:39]
	s_cbranch_execz .LBB0_295
	s_ashr_i32 s67, s66, 31
	s_lshl_b64 s[30:31], s[66:67], 6
	s_add_u32 s30, s2, s30
	v_mov_b32_e32 v110, s15
	v_mov_b32_e32 v111, s17
	s_addc_u32 s31, s14, s31
	v_pk_add_f32 v[110:111], s[0:1], v[110:111]
	s_nop 0
	v_add_f32_e32 v112, v110, v111
	v_mov_b64_e32 v[110:111], s[30:31]
	global_store_dword v[110:111], v112, off
.LBB0_295:
	s_or_b64 exec, exec, s[4:5]
	s_add_i32 s0, s11, s16
	s_cmpk_gt_i32 s0, 0x3fff
	s_cbranch_scc1 .Lpcpf_skip_6
	s_movk_i32 s0, 0x3400
	s_mov_b32 s1, 0
	v_lshl_add_u64 v[146:147], v[146:147], 0, s[0:1]
	s_movk_i32 s0, 0x1800
	v_lshl_add_u64 v[148:149], v[148:149], 0, s[0:1]
	global_load_ushort v119, v[146:147], off offset:-2048
	global_load_ushort v120, v[146:147], off
	global_load_ushort v121, v[146:147], off offset:2048
	global_load_ushort v117, v[148:149], off
	global_load_ushort v118, v[148:149], off offset:2048
.Lpcpf_skip_6:
	v_lshlrev_b32_e32 v102, 16, v102
	v_add_f32_e32 v102, v8, v102
	v_mul_f32_e64 v110, |v102|, s19
	v_exp_f32_e32 v110, v110
	v_mov_b32_e32 v111, s8
	v_mov_b32_e32 v112, s9
	v_add_f32_e32 v111, s7, v111
	v_add_f32_e32 v110, 1.0, v110
	v_log_f32_e32 v110, v110
	v_add_f32_e32 v112, s6, v112
	v_max_f32_e64 v102, -v102, 0
	v_add_f32_e32 v111, v111, v112
	v_fmac_f32_e32 v102, 0x3f317218, v110
	v_mul_f32_e32 v110, 0x4f800000, v111
	v_cmp_gt_f32_e32 vcc, s33, v111
	v_sub_f32_e32 v102, -0.5, v102
	v_mul_f32_e32 v102, 0x3fb8aa3b, v102
	v_cndmask_b32_e32 v110, v111, v110, vcc
	v_sqrt_f32_e32 v111, v110
	v_exp_f32_e32 v102, v102
	v_lshlrev_b32_e32 v98, 16, v98
	v_add_f32_e32 v98, v15, v98
	v_add_u32_e32 v112, -1, v111
	v_fma_f32 v113, -v112, v111, v110
	v_cmp_ge_f32_e64 s[56:57], 0, v113
	v_add_u32_e32 v113, 1, v111
	v_mul_f32_e32 v102, 0xbfb8aa3b, v102
	v_cndmask_b32_e64 v112, v111, v112, s[56:57]
	v_fma_f32 v111, -v113, v111, v110
	v_cmp_lt_f32_e64 s[56:57], 0, v111
	v_exp_f32_e32 v102, v102
	v_mul_f32_e32 v98, 0xbfb8aa3b, v98
	v_cndmask_b32_e64 v111, v112, v113, s[56:57]
	v_mul_f32_e32 v112, 0x37800000, v111
	v_cndmask_b32_e32 v111, v111, v112, vcc
	v_cmp_class_f32_e32 vcc, v110, v219
	v_exp_f32_e32 v98, v98
	v_lshlrev_b32_e32 v100, 16, v100
	v_cndmask_b32_e32 v110, v111, v110, vcc
	v_max_f32_e32 v110, 0x2b8cbccc, v110
	v_div_scale_f32 v111, s[0:1], v110, v110, v109
	v_rcp_f32_e32 v112, v111
	v_add_f32_e32 v98, 1.0, v98
	v_fma_f32 v113, -v111, v112, 1.0
	v_fmac_f32_e32 v112, v113, v112
	v_div_scale_f32 v113, vcc, v109, v110, v109
	v_mul_f32_e32 v114, v113, v112
	v_fma_f32 v115, -v111, v114, v113
	v_fmac_f32_e32 v114, v115, v112
	v_fma_f32 v111, -v111, v114, v113
	v_div_fmas_f32 v111, v111, v112, v114
	v_div_fixup_f32 v109, v111, v110, v109
	v_mul_f32_e32 v96, v96, v109
	v_cvt_pk_bf16_f32 v110, v96, s0
	v_mul_f32_e32 v96, v107, v102
	v_div_scale_f32 v102, s[0:1], v96, v96, 1.0
	v_rcp_f32_e32 v111, v102
	v_lshlrev_b32_e32 v110, 16, v110
	v_mul_f32_e32 v106, v96, v106
	v_cvt_pk_bf16_f32 v106, v106, s0
	v_fma_f32 v112, -v102, v111, 1.0
	v_fmac_f32_e32 v111, v112, v111
	v_div_scale_f32 v112, vcc, 1.0, v96, 1.0
	v_mul_f32_e32 v113, v112, v111
	v_fma_f32 v114, -v102, v113, v112
	v_fmac_f32_e32 v113, v114, v111
	v_fma_f32 v102, -v102, v113, v112
	v_div_fmas_f32 v102, v102, v111, v113
	v_div_fixup_f32 v102, v102, v96, 1.0
	v_mul_f32_e32 v103, v102, v103
	v_cvt_pk_bf16_f32 v103, v103, s0
	v_mul_f32_e32 v102, v102, v110
	ds_write_b16 v27, v103 offset:5472
	v_cvt_pk_bf16_f32 v102, v102, s0
	v_sub_f32_e32 v103, v105, v100
	ds_write_b16 v27, v102 offset:7776
	v_lshlrev_b32_e32 v102, 16, v99
	v_lshlrev_b32_e32 v99, 16, v101
	v_fma_f32 v105, v9, v103, v100
	v_sub_f32_e32 v103, v104, v99
	v_mul_f32_e32 v104, v14, v105
	ds_write_b16 v27, v106 offset:3168
	v_fma_f32 v106, v12, v103, v99
	v_rcp_f32_e32 v103, v98
	v_mul_f32_e32 v98, v104, v104
	v_sub_f32_e32 v101, v108, v102
	v_cvt_pk_bf16_f32 v109, v109, s0
	v_mov_b32_dpp v98, v98 quad_perm:[1,0,3,2] row_mask:0xf bank_mask:0xf bound_ctrl:1
	v_fmac_f32_e32 v98, v104, v104
	v_fma_f32 v101, v10, v101, v102
	v_lshlrev_b32_e32 v109, 16, v109
	v_add_f32_dpp v98, v98, v98 quad_perm:[2,3,0,1] row_mask:0xf bank_mask:0xf bound_ctrl:1
; __device__ __forceinline__ float bf2f(bf16 b) { return __uint_as_float((unsigned)b << 16); }
; __device__ __forceinline__ bf16 f2bf(float f) { return (bf16)(pk_bf16(f, 0.f) & 0xffffu); }
; __device__ __forceinline__ float fexp(float x) { return __builtin_amdgcn_exp2f(x * 1.4426950408889634f); }
; __device__ __forceinline__ float flog(float x) { return __builtin_amdgcn_logf(x) * 0.6931471805599453f; }
; __device__ __forceinline__ float fsigmoid(float x) { return __builtin_amdgcn_rcpf(1.0f + fexp(-x)); }
; __device__ __forceinline__ void pc_phase(LAS unsigned char* lds, const bf16* Pp_, const bf16* LO, const float* mu, const float* w0, const float* a0, const float* k_k, const float* k_a, const float* r_k, ...
;     ...
;         for (int t = 0; t < 16; ++t) {
;             const float r0 = bf2f(sr_[t + 1]), k0 = bf2f(sk_[t + 1]), v0 = bf2f(sv_[t + 1]);
;             const float r = r0 + (r1 - r0) * mu_r, k = k0 + (k1 - k0) * mu_k, v = v0 + (v1 - v0) * mu_v; r1 = r0; k1 = k0; v1 = v0;
;             const float z = -(w0c + bf2f(slw[t])); const float sp = fmaxf(z, 0.f) + flog(1.0f + fexp(-fabsf(z))); const float w = -sp - 0.5f;
;             const float dec = fexp(-fexp(w)); const float a = fsigmoid(a0c + bf2f(sla[t]));
;             float kk = k * kkc; const float n2 = wsum_dpp(kk * kk); kk = kk / fmaxf(sqrtf(n2), 1e-12f);
;             const float kp = bf2f(f2bf(k * (1.0f + (a - 1.0f) * kac))), bb = bf2f(f2bf(kk * a)), rr = bf2f(f2bf(r)); kk = bf2f(f2bf(kk));
;             const float coef = wsum_dpp(rr * kp * rkc);
;             SV[(ib + t) * 64 + lane] = f2bf(v);
;             if (lane == 0) COEF[(size_t)(m0 + t) * 16 + h] = coef;
;             const float Pp = P; P *= dec; const float inv = 1.0f / P;
;             XKK[t * 72 + lane] = f2bf(kk * Pp); XR[t * 72 + lane] = f2bf(rr * P); XK[t * 72 + lane] = f2bf(kp * inv); XB[t * 72 + lane] = f2bf(bb * inv); }
	v_cvt_pk_bf16_f32 v101, v101, s0
	v_mul_f32_e32 v107, v107, v109
	v_add_f32_dpp v98, v98, v98 row_ror:4 row_mask:0xf bank_mask:0xf bound_ctrl:1
	v_lshlrev_b32_e32 v101, 16, v101
	v_cvt_pk_bf16_f32 v107, v107, s0
	v_add_f32_dpp v98, v98, v98 row_ror:8 row_mask:0xf bank_mask:0xf bound_ctrl:1
	ds_write_b16 v27, v107 offset:864
	v_readlane_b32 s7, v98, 0
	v_readlane_b32 s8, v98, 16
	v_readlane_b32 s6, v98, 32
	v_readlane_b32 s9, v98, 48
	v_add_f32_e32 v98, -1.0, v103
	v_fma_f32 v98, v13, v98, 1.0
	v_mul_f32_e32 v98, v105, v98
	v_cvt_pk_bf16_f32 v98, v98, s0
	v_lshlrev_b32_e32 v98, 16, v98
	v_mul_f32_e32 v105, v101, v98
	v_mul_f32_e32 v107, v11, v105
	s_nop 1
	v_mov_b32_dpp v107, v107 quad_perm:[1,0,3,2] row_mask:0xf bank_mask:0xf bound_ctrl:1
	v_fmac_f32_e32 v107, v11, v105
	s_nop 1
	v_add_f32_dpp v105, v107, v107 quad_perm:[2,3,0,1] row_mask:0xf bank_mask:0xf bound_ctrl:1
	s_nop 1
	v_add_f32_dpp v105, v105, v105 row_ror:4 row_mask:0xf bank_mask:0xf bound_ctrl:1
	s_nop 1
	v_add_f32_dpp v105, v105, v105 row_ror:8 row_mask:0xf bank_mask:0xf bound_ctrl:1
	s_nop 0
	v_readlane_b32 s0, v105, 0
	v_readlane_b32 s15, v105, 16
	v_readlane_b32 s1, v105, 32
	v_readlane_b32 s17, v105, 48
	v_cvt_pk_bf16_f32 v105, v106, s0
	v_add_co_u32_e32 v106, vcc, 0x33600000, v6
	s_nop 1
	v_addc_co_u32_e32 v107, vcc, 0, v7, vcc
	global_store_short v[106:107], v105, off offset:896
	s_and_saveexec_b64 s[4:5], s[38:39]
	s_cbranch_execz .LBB0_297
	s_ashr_i32 s65, s64, 31
	s_lshl_b64 s[30:31], s[64:65], 6
	s_add_u32 s30, s2, s30
	v_mov_b32_e32 v106, s15
	v_mov_b32_e32 v107, s17
	s_addc_u32 s31, s14, s31
	v_pk_add_f32 v[106:107], s[0:1], v[106:107]
	s_nop 0
	v_add_f32_e32 v105, v106, v107
	v_mov_b64_e32 v[106:107], s[30:31]
	global_store_dword v[106:107], v105, off
.LBB0_297:
	s_or_b64 exec, exec, s[4:5]
	s_add_i32 s0, s11, s16
	s_cmpk_gt_i32 s0, 0x3fff
	s_cbranch_scc1 .Lpcpf_skip_7
	s_movk_i32 s0, 0x3400
	s_mov_b32 s1, 0
	v_lshl_add_u64 v[146:147], v[146:147], 0, s[0:1]
	s_movk_i32 s0, 0x1800
	v_lshl_add_u64 v[148:149], v[148:149], 0, s[0:1]
	global_load_ushort v114, v[146:147], off offset:-2048
	global_load_ushort v115, v[146:147], off
	global_load_ushort v116, v[146:147], off offset:2048
	global_load_ushort v112, v[148:149], off
	global_load_ushort v113, v[148:149], off offset:2048
.Lpcpf_skip_7:
	v_lshlrev_b32_e32 v95, 16, v95
	v_add_f32_e32 v95, v8, v95
	v_mul_f32_e64 v105, |v95|, s19
	v_exp_f32_e32 v105, v105
	v_mov_b32_e32 v106, s8
	v_mov_b32_e32 v107, s9
	v_add_f32_e32 v106, s7, v106
	v_add_f32_e32 v105, 1.0, v105
	v_log_f32_e32 v105, v105
	v_add_f32_e32 v107, s6, v107
	v_max_f32_e64 v95, -v95, 0
	v_add_f32_e32 v106, v106, v107
	v_fmac_f32_e32 v95, 0x3f317218, v105
	v_mul_f32_e32 v105, 0x4f800000, v106
	v_cmp_gt_f32_e32 vcc, s33, v106
	v_sub_f32_e32 v95, -0.5, v95
	v_mul_f32_e32 v95, 0x3fb8aa3b, v95
	v_cndmask_b32_e32 v105, v106, v105, vcc
	v_sqrt_f32_e32 v106, v105
	v_exp_f32_e32 v95, v95
	v_lshlrev_b32_e32 v91, 16, v91
	v_add_f32_e32 v91, v15, v91
	v_add_u32_e32 v107, -1, v106
	v_fma_f32 v108, -v107, v106, v105
	v_cmp_ge_f32_e64 s[56:57], 0, v108
	v_add_u32_e32 v108, 1, v106
	v_mul_f32_e32 v95, 0xbfb8aa3b, v95
	v_cndmask_b32_e64 v107, v106, v107, s[56:57]
	v_fma_f32 v106, -v108, v106, v105
	v_cmp_lt_f32_e64 s[56:57], 0, v106
	v_exp_f32_e32 v95, v95
	v_mul_f32_e32 v91, 0xbfb8aa3b, v91
	v_cndmask_b32_e64 v106, v107, v108, s[56:57]
	v_mul_f32_e32 v107, 0x37800000, v106
	v_cndmask_b32_e32 v106, v106, v107, vcc
	v_cmp_class_f32_e32 vcc, v105, v219
	v_mul_f32_e32 v95, v96, v95
	v_exp_f32_e32 v91, v91
	v_cndmask_b32_e32 v105, v106, v105, vcc
	v_max_f32_e32 v105, 0x2b8cbccc, v105
	v_div_scale_f32 v106, s[0:1], v105, v105, v104
	v_rcp_f32_e32 v107, v106
	v_lshlrev_b32_e32 v93, 16, v93
	v_add_f32_e32 v91, 1.0, v91
	v_fma_f32 v108, -v106, v107, 1.0
	v_fmac_f32_e32 v107, v108, v107
	v_div_scale_f32 v108, vcc, v104, v105, v104
	v_mul_f32_e32 v109, v108, v107
	v_fma_f32 v110, -v106, v109, v108
	v_fmac_f32_e32 v109, v110, v107
	v_fma_f32 v106, -v106, v109, v108
	v_div_fmas_f32 v106, v106, v107, v109
	v_div_fixup_f32 v104, v106, v105, v104
	v_mul_f32_e32 v103, v103, v104
	v_cvt_pk_bf16_f32 v103, v103, s0
	v_div_scale_f32 v105, s[0:1], v95, v95, 1.0
	v_rcp_f32_e32 v106, v105
	s_nop 0
	v_cvt_pk_bf16_f32 v104, v104, s0
	v_lshlrev_b32_e32 v104, 16, v104
	v_mul_f32_e32 v96, v96, v104
	v_fma_f32 v107, -v105, v106, 1.0
	v_fmac_f32_e32 v106, v107, v106
	v_div_scale_f32 v107, vcc, 1.0, v95, 1.0
	v_mul_f32_e32 v108, v107, v106
	v_fma_f32 v109, -v105, v108, v107
	v_fmac_f32_e32 v108, v109, v106
	v_fma_f32 v105, -v105, v108, v107
	v_cvt_pk_bf16_f32 v96, v96, s0
	v_div_fmas_f32 v105, v105, v106, v108
	ds_write_b16 v27, v96 offset:1008
	v_mul_f32_e32 v96, v95, v101
	v_div_fixup_f32 v105, v105, v95, 1.0
	v_cvt_pk_bf16_f32 v96, v96, s0
	ds_write_b16 v27, v96 offset:3312
	v_mul_f32_e32 v96, v105, v98
	v_lshlrev_b32_e32 v103, 16, v103
	v_cvt_pk_bf16_f32 v96, v96, s0
	ds_write_b16 v27, v96 offset:5616
	v_mul_f32_e32 v96, v105, v103
	v_cvt_pk_bf16_f32 v96, v96, s0
	v_sub_f32_e32 v98, v100, v93
	ds_write_b16 v27, v96 offset:7920
	v_lshlrev_b32_e32 v96, 16, v92
	v_lshlrev_b32_e32 v92, 16, v94
	v_fma_f32 v100, v9, v98, v93
	v_sub_f32_e32 v98, v99, v92
	v_mul_f32_e32 v99, v14, v100
	v_fma_f32 v101, v12, v98, v92
	v_rcp_f32_e32 v98, v91
	v_mul_f32_e32 v91, v99, v99
	v_sub_f32_e32 v94, v102, v96
	v_fma_f32 v94, v10, v94, v96
	v_mov_b32_dpp v91, v91 quad_perm:[1,0,3,2] row_mask:0xf bank_mask:0xf bound_ctrl:1
	v_fmac_f32_e32 v91, v99, v99
	v_cvt_pk_bf16_f32 v94, v94, s0
	v_lshlrev_b32_e32 v94, 16, v94
	v_add_f32_dpp v91, v91, v91 quad_perm:[2,3,0,1] row_mask:0xf bank_mask:0xf bound_ctrl:1
	s_nop 1
	v_add_f32_dpp v91, v91, v91 row_ror:4 row_mask:0xf bank_mask:0xf bound_ctrl:1
	s_nop 1
	v_add_f32_dpp v91, v91, v91 row_ror:8 row_mask:0xf bank_mask:0xf bound_ctrl:1
	s_nop 0
	v_readlane_b32 s7, v91, 0
	v_readlane_b32 s8, v91, 16
	v_readlane_b32 s6, v91, 32
	v_readlane_b32 s9, v91, 48
	v_add_f32_e32 v91, -1.0, v98
	v_fma_f32 v91, v13, v91, 1.0
	v_mul_f32_e32 v91, v100, v91
	v_cvt_pk_bf16_f32 v91, v91, s0
	v_lshlrev_b32_e32 v91, 16, v91
	v_mul_f32_e32 v100, v94, v91
	v_mul_f32_e32 v102, v11, v100
	s_nop 1
	v_mov_b32_dpp v102, v102 quad_perm:[1,0,3,2] row_mask:0xf bank_mask:0xf bound_ctrl:1
	v_fmac_f32_e32 v102, v11, v100
	s_nop 1
	v_add_f32_dpp v100, v102, v102 quad_perm:[2,3,0,1] row_mask:0xf bank_mask:0xf bound_ctrl:1
	s_nop 1
	v_add_f32_dpp v100, v100, v100 row_ror:4 row_mask:0xf bank_mask:0xf bound_ctrl:1
	s_nop 1
	v_add_f32_dpp v100, v100, v100 row_ror:8 row_mask:0xf bank_mask:0xf bound_ctrl:1
	s_nop 0
	v_readlane_b32 s0, v100, 0
	v_readlane_b32 s15, v100, 16
	v_readlane_b32 s1, v100, 32
	v_readlane_b32 s17, v100, 48
	v_add_co_u32_e32 v100, vcc, 0x33600000, v6
	v_cvt_pk_bf16_f32 v102, v101, s0
	s_nop 0
	v_addc_co_u32_e32 v101, vcc, 0, v7, vcc
	global_store_short v[100:101], v102, off offset:1024
	s_and_saveexec_b64 s[4:5], s[38:39]
	s_cbranch_execz .LBB0_299
; __device__ __forceinline__ float bf2f(bf16 b) { return __uint_as_float((unsigned)b << 16); }
; __device__ __forceinline__ bf16 f2bf(float f) { return (bf16)(pk_bf16(f, 0.f) & 0xffffu); }
; __device__ __forceinline__ float fexp(float x) { return __builtin_amdgcn_exp2f(x * 1.4426950408889634f); }
; __device__ __forceinline__ float flog(float x) { return __builtin_amdgcn_logf(x) * 0.6931471805599453f; }
; __device__ __forceinline__ float fsigmoid(float x) { return __builtin_amdgcn_rcpf(1.0f + fexp(-x)); }
; __device__ __forceinline__ void pc_phase(LAS unsigned char* lds, const bf16* Pp_, const bf16* LO, const float* mu, const float* w0, const float* a0, const float* k_k, const float* k_a, const float* r_k, ...
;     ...
;         for (int t = 0; t < 16; ++t) {
;             const float r0 = bf2f(sr_[t + 1]), k0 = bf2f(sk_[t + 1]), v0 = bf2f(sv_[t + 1]);
;             const float r = r0 + (r1 - r0) * mu_r, k = k0 + (k1 - k0) * mu_k, v = v0 + (v1 - v0) * mu_v; r1 = r0; k1 = k0; v1 = v0;
;             const float z = -(w0c + bf2f(slw[t])); const float sp = fmaxf(z, 0.f) + flog(1.0f + fexp(-fabsf(z))); const float w = -sp - 0.5f;
;             const float dec = fexp(-fexp(w)); const float a = fsigmoid(a0c + bf2f(sla[t]));
;             float kk = k * kkc; const float n2 = wsum_dpp(kk * kk); kk = kk / fmaxf(sqrtf(n2), 1e-12f);
;             const float kp = bf2f(f2bf(k * (1.0f + (a - 1.0f) * kac))), bb = bf2f(f2bf(kk * a)), rr = bf2f(f2bf(r)); kk = bf2f(f2bf(kk));
;             const float coef = wsum_dpp(rr * kp * rkc);
;             SV[(ib + t) * 64 + lane] = f2bf(v);
;             if (lane == 0) COEF[(size_t)(m0 + t) * 16 + h] = coef;
;             const float Pp = P; P *= dec; const float inv = 1.0f / P;
;             XKK[t * 72 + lane] = f2bf(kk * Pp); XR[t * 72 + lane] = f2bf(rr * P); XK[t * 72 + lane] = f2bf(kp * inv); XB[t * 72 + lane] = f2bf(bb * inv); }
	s_ashr_i32 s63, s62, 31
	s_lshl_b64 s[30:31], s[62:63], 6
	s_add_u32 s30, s2, s30
	v_mov_b32_e32 v100, s15
	v_mov_b32_e32 v101, s17
	s_addc_u32 s31, s14, s31
	v_pk_add_f32 v[100:101], s[0:1], v[100:101]
	v_readlane_b32 s63, v254, 44
	v_add_f32_e32 v102, v100, v101
	v_mov_b64_e32 v[100:101], s[30:31]
	global_store_dword v[100:101], v102, off
.LBB0_299:
	s_or_b64 exec, exec, s[4:5]
	s_add_i32 s0, s11, s16
	s_cmpk_gt_i32 s0, 0x3fff
	s_cbranch_scc1 .Lpcpf_skip_8
	s_movk_i32 s0, 0x3400
	s_mov_b32 s1, 0
	v_lshl_add_u64 v[146:147], v[146:147], 0, s[0:1]
	s_movk_i32 s0, 0x1800
	v_lshl_add_u64 v[148:149], v[148:149], 0, s[0:1]
	global_load_ushort v109, v[146:147], off offset:-2048
	global_load_ushort v110, v[146:147], off
	global_load_ushort v111, v[146:147], off offset:2048
	global_load_ushort v107, v[148:149], off
	global_load_ushort v108, v[148:149], off offset:2048
.Lpcpf_skip_8:
	v_lshlrev_b32_e32 v90, 16, v90
	v_add_f32_e32 v90, v8, v90
	v_mul_f32_e64 v100, |v90|, s19
	v_exp_f32_e32 v100, v100
	v_mov_b32_e32 v101, s8
	v_mov_b32_e32 v102, s9
	v_add_f32_e32 v101, s7, v101
	v_add_f32_e32 v100, 1.0, v100
	v_log_f32_e32 v100, v100
	v_add_f32_e32 v102, s6, v102
	v_max_f32_e64 v90, -v90, 0
	v_add_f32_e32 v101, v101, v102
	v_fmac_f32_e32 v90, 0x3f317218, v100
	v_mul_f32_e32 v100, 0x4f800000, v101
	v_cmp_gt_f32_e32 vcc, s33, v101
	v_sub_f32_e32 v90, -0.5, v90
	v_mul_f32_e32 v90, 0x3fb8aa3b, v90
	v_cndmask_b32_e32 v100, v101, v100, vcc
	v_sqrt_f32_e32 v101, v100
	v_exp_f32_e32 v90, v90
	v_lshlrev_b32_e32 v86, 16, v86
	v_add_f32_e32 v86, v15, v86
	v_add_u32_e32 v102, -1, v101
	v_fma_f32 v103, -v102, v101, v100
	v_cmp_ge_f32_e64 s[56:57], 0, v103
	v_add_u32_e32 v103, 1, v101
	v_mul_f32_e32 v90, 0xbfb8aa3b, v90
	v_cndmask_b32_e64 v102, v101, v102, s[56:57]
	v_fma_f32 v101, -v103, v101, v100
	v_cmp_lt_f32_e64 s[56:57], 0, v101
	v_exp_f32_e32 v90, v90
	v_mul_f32_e32 v86, 0xbfb8aa3b, v86
	v_cndmask_b32_e64 v101, v102, v103, s[56:57]
	v_mul_f32_e32 v102, 0x37800000, v101
	v_cndmask_b32_e32 v101, v101, v102, vcc
	v_cmp_class_f32_e32 vcc, v100, v219
	v_mul_f32_e32 v90, v95, v90
	v_exp_f32_e32 v86, v86
	v_cndmask_b32_e32 v100, v101, v100, vcc
	v_max_f32_e32 v100, 0x2b8cbccc, v100
	v_div_scale_f32 v101, s[0:1], v100, v100, v99
	v_rcp_f32_e32 v102, v101
	v_mul_f32_e32 v94, v90, v94
	v_lshlrev_b32_e32 v88, 16, v88
	v_sub_f32_e32 v93, v93, v88
	v_fma_f32 v103, -v101, v102, 1.0
	v_fmac_f32_e32 v102, v103, v102
	v_div_scale_f32 v103, vcc, v99, v100, v99
	v_mul_f32_e32 v104, v103, v102
	v_fma_f32 v105, -v101, v104, v103
	v_fmac_f32_e32 v104, v105, v102
	v_fma_f32 v101, -v101, v104, v103
	v_div_fmas_f32 v101, v101, v102, v104
	v_div_fixup_f32 v99, v101, v100, v99
	v_mul_f32_e32 v98, v98, v99
	v_cvt_pk_bf16_f32 v98, v98, s0
	v_div_scale_f32 v100, s[0:1], v90, v90, 1.0
	v_rcp_f32_e32 v101, v100
	v_lshlrev_b32_e32 v98, 16, v98
	v_cvt_pk_bf16_f32 v99, v99, s0
	v_lshlrev_b32_e32 v99, 16, v99
	v_fma_f32 v102, -v100, v101, 1.0
	v_fmac_f32_e32 v101, v102, v101
	v_div_scale_f32 v102, vcc, 1.0, v90, 1.0
	v_mul_f32_e32 v103, v102, v101
	v_fma_f32 v104, -v100, v103, v102
	v_fmac_f32_e32 v103, v104, v101
	v_fma_f32 v100, -v100, v103, v102
	v_div_fmas_f32 v100, v100, v101, v103
	v_div_fixup_f32 v100, v100, v90, 1.0
	v_mul_f32_e32 v91, v100, v91
	v_cvt_pk_bf16_f32 v91, v91, s0
	ds_write_b16 v27, v91 offset:5760
	v_mul_f32_e32 v91, v100, v98
	v_cvt_pk_bf16_f32 v94, v94, s0
	v_cvt_pk_bf16_f32 v91, v91, s0
	v_mul_f32_e32 v95, v95, v99
	ds_write_b16 v27, v94 offset:3456
	ds_write_b16 v27, v91 offset:8064
	v_lshlrev_b32_e32 v91, 16, v87
	v_lshlrev_b32_e32 v87, 16, v89
	v_fma_f32 v94, v9, v93, v88
	v_cvt_pk_bf16_f32 v95, v95, s0
	v_sub_f32_e32 v92, v92, v87
	v_add_f32_e32 v86, 1.0, v86
	v_mul_f32_e32 v93, v14, v94
	ds_write_b16 v27, v95 offset:1152
	v_fma_f32 v95, v12, v92, v87
	v_rcp_f32_e32 v92, v86
	v_mul_f32_e32 v86, v93, v93
	v_sub_f32_e32 v89, v96, v91
	v_fma_f32 v89, v10, v89, v91
	v_mov_b32_dpp v86, v86 quad_perm:[1,0,3,2] row_mask:0xf bank_mask:0xf bound_ctrl:1
	v_fmac_f32_e32 v86, v93, v93
	v_cvt_pk_bf16_f32 v89, v89, s0
	v_lshlrev_b32_e32 v89, 16, v89
	v_add_f32_dpp v86, v86, v86 quad_perm:[2,3,0,1] row_mask:0xf bank_mask:0xf bound_ctrl:1
	s_nop 1
	v_add_f32_dpp v86, v86, v86 row_ror:4 row_mask:0xf bank_mask:0xf bound_ctrl:1
	s_nop 1
	v_add_f32_dpp v86, v86, v86 row_ror:8 row_mask:0xf bank_mask:0xf bound_ctrl:1
	s_nop 0
	v_readlane_b32 s7, v86, 0
	v_readlane_b32 s8, v86, 16
	v_readlane_b32 s6, v86, 32
	v_readlane_b32 s9, v86, 48
	v_add_f32_e32 v86, -1.0, v92
	v_fma_f32 v86, v13, v86, 1.0
	v_mul_f32_e32 v86, v94, v86
	v_cvt_pk_bf16_f32 v86, v86, s0
	v_lshlrev_b32_e32 v86, 16, v86
	v_mul_f32_e32 v94, v89, v86
	v_mul_f32_e32 v96, v11, v94
	s_nop 1
	v_mov_b32_dpp v96, v96 quad_perm:[1,0,3,2] row_mask:0xf bank_mask:0xf bound_ctrl:1
	v_fmac_f32_e32 v96, v11, v94
	s_nop 1
	v_add_f32_dpp v94, v96, v96 quad_perm:[2,3,0,1] row_mask:0xf bank_mask:0xf bound_ctrl:1
	s_nop 1
	v_add_f32_dpp v94, v94, v94 row_ror:4 row_mask:0xf bank_mask:0xf bound_ctrl:1
	s_nop 1
	v_add_f32_dpp v94, v94, v94 row_ror:8 row_mask:0xf bank_mask:0xf bound_ctrl:1
	s_nop 0
	v_readlane_b32 s0, v94, 0
	v_readlane_b32 s15, v94, 16
	v_readlane_b32 s1, v94, 32
	v_readlane_b32 s17, v94, 48
	v_add_co_u32_e32 v94, vcc, 0x33600000, v6
	v_cvt_pk_bf16_f32 v96, v95, s0
	s_nop 0
	v_addc_co_u32_e32 v95, vcc, 0, v7, vcc
	global_store_short v[94:95], v96, off offset:1152
	s_and_saveexec_b64 s[4:5], s[38:39]
	s_cbranch_execz .LBB0_301
	s_ashr_i32 s37, s36, 31
	s_lshl_b64 s[30:31], s[36:37], 6
	s_add_u32 s30, s2, s30
	v_mov_b32_e32 v94, s15
	v_mov_b32_e32 v95, s17
	s_addc_u32 s31, s14, s31
	v_pk_add_f32 v[94:95], s[0:1], v[94:95]
	s_nop 0
	v_add_f32_e32 v96, v94, v95
	v_mov_b64_e32 v[94:95], s[30:31]
	global_store_dword v[94:95], v96, off
; __device__ __forceinline__ float bf2f(bf16 b) { return __uint_as_float((unsigned)b << 16); }
; __device__ __forceinline__ bf16 f2bf(float f) { return (bf16)(pk_bf16(f, 0.f) & 0xffffu); }
; __device__ __forceinline__ float fexp(float x) { return __builtin_amdgcn_exp2f(x * 1.4426950408889634f); }
; __device__ __forceinline__ float flog(float x) { return __builtin_amdgcn_logf(x) * 0.6931471805599453f; }
; __device__ __forceinline__ float fsigmoid(float x) { return __builtin_amdgcn_rcpf(1.0f + fexp(-x)); }
; __device__ __forceinline__ void pc_phase(LAS unsigned char* lds, const bf16* Pp_, const bf16* LO, const float* mu, const float* w0, const float* a0, const float* k_k, const float* k_a, const float* r_k, ...
;     ...
;         for (int t = 0; t < 16; ++t) {
;             const float r0 = bf2f(sr_[t + 1]), k0 = bf2f(sk_[t + 1]), v0 = bf2f(sv_[t + 1]);
;             const float r = r0 + (r1 - r0) * mu_r, k = k0 + (k1 - k0) * mu_k, v = v0 + (v1 - v0) * mu_v; r1 = r0; k1 = k0; v1 = v0;
;             const float z = -(w0c + bf2f(slw[t])); const float sp = fmaxf(z, 0.f) + flog(1.0f + fexp(-fabsf(z))); const float w = -sp - 0.5f;
;             const float dec = fexp(-fexp(w)); const float a = fsigmoid(a0c + bf2f(sla[t]));
;             float kk = k * kkc; const float n2 = wsum_dpp(kk * kk); kk = kk / fmaxf(sqrtf(n2), 1e-12f);
;             const float kp = bf2f(f2bf(k * (1.0f + (a - 1.0f) * kac))), bb = bf2f(f2bf(kk * a)), rr = bf2f(f2bf(r)); kk = bf2f(f2bf(kk));
;             const float coef = wsum_dpp(rr * kp * rkc);
;             SV[(ib + t) * 64 + lane] = f2bf(v);
;             if (lane == 0) COEF[(size_t)(m0 + t) * 16 + h] = coef;
;             const float Pp = P; P *= dec; const float inv = 1.0f / P;
;             XKK[t * 72 + lane] = f2bf(kk * Pp); XR[t * 72 + lane] = f2bf(rr * P); XK[t * 72 + lane] = f2bf(kp * inv); XB[t * 72 + lane] = f2bf(bb * inv); }
.LBB0_301:
	s_or_b64 exec, exec, s[4:5]
	s_add_i32 s0, s11, s16
	s_cmpk_gt_i32 s0, 0x3fff
	s_cbranch_scc1 .Lpcpf_skip_9
	s_movk_i32 s0, 0x3400
	s_mov_b32 s1, 0
	v_lshl_add_u64 v[146:147], v[146:147], 0, s[0:1]
	s_movk_i32 s0, 0x1800
	v_lshl_add_u64 v[148:149], v[148:149], 0, s[0:1]
	global_load_ushort v104, v[146:147], off offset:-2048
	global_load_ushort v105, v[146:147], off
	global_load_ushort v106, v[146:147], off offset:2048
	global_load_ushort v102, v[148:149], off
	global_load_ushort v103, v[148:149], off offset:2048
.Lpcpf_skip_9:
	v_lshlrev_b32_e32 v85, 16, v85
	v_add_f32_e32 v85, v8, v85
	v_mul_f32_e64 v94, |v85|, s19
	v_exp_f32_e32 v94, v94
	v_mov_b32_e32 v95, s8
	v_mov_b32_e32 v96, s9
	v_add_f32_e32 v95, s7, v95
	v_add_f32_e32 v94, 1.0, v94
	v_log_f32_e32 v94, v94
	v_add_f32_e32 v96, s6, v96
	v_max_f32_e64 v85, -v85, 0
	v_add_f32_e32 v95, v95, v96
	v_fmac_f32_e32 v85, 0x3f317218, v94
	v_mul_f32_e32 v94, 0x4f800000, v95
	v_cmp_gt_f32_e32 vcc, s33, v95
	v_sub_f32_e32 v85, -0.5, v85
	v_mul_f32_e32 v85, 0x3fb8aa3b, v85
	v_cndmask_b32_e32 v94, v95, v94, vcc
	v_sqrt_f32_e32 v95, v94
	v_exp_f32_e32 v85, v85
	v_lshlrev_b32_e32 v81, 16, v81
	v_add_f32_e32 v81, v15, v81
	v_add_u32_e32 v96, -1, v95
	v_fma_f32 v98, -v96, v95, v94
	v_cmp_ge_f32_e64 s[56:57], 0, v98
	v_add_u32_e32 v98, 1, v95
	v_mul_f32_e32 v85, 0xbfb8aa3b, v85
	v_cndmask_b32_e64 v96, v95, v96, s[56:57]
	v_fma_f32 v95, -v98, v95, v94
	v_cmp_lt_f32_e64 s[56:57], 0, v95
	v_exp_f32_e32 v85, v85
	v_mul_f32_e32 v81, 0xbfb8aa3b, v81
	v_cndmask_b32_e64 v95, v96, v98, s[56:57]
	v_mul_f32_e32 v96, 0x37800000, v95
	v_cndmask_b32_e32 v95, v95, v96, vcc
	v_cmp_class_f32_e32 vcc, v94, v219
	v_mul_f32_e32 v85, v90, v85
	v_exp_f32_e32 v81, v81
	v_cndmask_b32_e32 v94, v95, v94, vcc
	v_max_f32_e32 v94, 0x2b8cbccc, v94
	v_div_scale_f32 v95, s[0:1], v94, v94, v93
	v_rcp_f32_e32 v96, v95
	v_mul_f32_e32 v89, v85, v89
	v_lshlrev_b32_e32 v83, 16, v83
	v_sub_f32_e32 v88, v88, v83
	v_fma_f32 v98, -v95, v96, 1.0
	v_fmac_f32_e32 v96, v98, v96
	v_div_scale_f32 v98, vcc, v93, v94, v93
	v_mul_f32_e32 v99, v98, v96
	v_fma_f32 v100, -v95, v99, v98
	v_fmac_f32_e32 v99, v100, v96
	v_fma_f32 v95, -v95, v99, v98
	v_div_fmas_f32 v95, v95, v96, v99
	v_div_fixup_f32 v93, v95, v94, v93
	v_mul_f32_e32 v92, v92, v93
	v_cvt_pk_bf16_f32 v92, v92, s0
	v_div_scale_f32 v94, s[0:1], v85, v85, 1.0
	v_rcp_f32_e32 v95, v94
	v_lshlrev_b32_e32 v92, 16, v92
	v_cvt_pk_bf16_f32 v93, v93, s0
	v_lshlrev_b32_e32 v93, 16, v93
	v_fma_f32 v96, -v94, v95, 1.0
	v_fmac_f32_e32 v95, v96, v95
	v_div_scale_f32 v96, vcc, 1.0, v85, 1.0
	v_mul_f32_e32 v98, v96, v95
	v_fma_f32 v99, -v94, v98, v96
	v_fmac_f32_e32 v98, v99, v95
	v_fma_f32 v94, -v94, v98, v96
	v_div_fmas_f32 v94, v94, v95, v98
	v_div_fixup_f32 v94, v94, v85, 1.0
	v_mul_f32_e32 v86, v94, v86
	v_cvt_pk_bf16_f32 v86, v86, s0
	ds_write_b16 v27, v86 offset:5904
	v_mul_f32_e32 v86, v94, v92
	v_cvt_pk_bf16_f32 v89, v89, s0
	v_cvt_pk_bf16_f32 v86, v86, s0
	v_mul_f32_e32 v90, v90, v93
	ds_write_b16 v27, v89 offset:3600
	ds_write_b16 v27, v86 offset:8208
	v_lshlrev_b32_e32 v86, 16, v82
	v_lshlrev_b32_e32 v82, 16, v84
	v_fma_f32 v89, v9, v88, v83
	v_cvt_pk_bf16_f32 v90, v90, s0
	v_sub_f32_e32 v87, v87, v82
	v_add_f32_e32 v81, 1.0, v81
	v_mul_f32_e32 v88, v14, v89
	ds_write_b16 v27, v90 offset:1296
	v_fma_f32 v90, v12, v87, v82
	v_rcp_f32_e32 v87, v81
	v_mul_f32_e32 v81, v88, v88
	v_sub_f32_e32 v84, v91, v86
	v_fma_f32 v84, v10, v84, v86
	v_mov_b32_dpp v81, v81 quad_perm:[1,0,3,2] row_mask:0xf bank_mask:0xf bound_ctrl:1
	v_fmac_f32_e32 v81, v88, v88
	v_cvt_pk_bf16_f32 v84, v84, s0
	v_lshlrev_b32_e32 v84, 16, v84
	v_add_f32_dpp v81, v81, v81 quad_perm:[2,3,0,1] row_mask:0xf bank_mask:0xf bound_ctrl:1
	s_nop 1
	v_add_f32_dpp v81, v81, v81 row_ror:4 row_mask:0xf bank_mask:0xf bound_ctrl:1
	s_nop 1
	v_add_f32_dpp v81, v81, v81 row_ror:8 row_mask:0xf bank_mask:0xf bound_ctrl:1
	s_nop 0
	v_readlane_b32 s7, v81, 0
	v_readlane_b32 s8, v81, 16
	v_readlane_b32 s6, v81, 32
	v_readlane_b32 s9, v81, 48
	v_add_f32_e32 v81, -1.0, v87
	v_fma_f32 v81, v13, v81, 1.0
	v_mul_f32_e32 v81, v89, v81
	v_cvt_pk_bf16_f32 v81, v81, s0
	v_lshlrev_b32_e32 v81, 16, v81
	v_mul_f32_e32 v89, v84, v81
	v_mul_f32_e32 v91, v11, v89
	s_nop 1
	v_mov_b32_dpp v91, v91 quad_perm:[1,0,3,2] row_mask:0xf bank_mask:0xf bound_ctrl:1
	v_fmac_f32_e32 v91, v11, v89
	s_nop 1
	v_add_f32_dpp v89, v91, v91 quad_perm:[2,3,0,1] row_mask:0xf bank_mask:0xf bound_ctrl:1
	s_nop 1
	v_add_f32_dpp v89, v89, v89 row_ror:4 row_mask:0xf bank_mask:0xf bound_ctrl:1
	s_nop 1
	v_add_f32_dpp v89, v89, v89 row_ror:8 row_mask:0xf bank_mask:0xf bound_ctrl:1
	s_nop 0
	v_readlane_b32 s0, v89, 0
	v_readlane_b32 s15, v89, 16
	v_readlane_b32 s1, v89, 32
	v_readlane_b32 s17, v89, 48
	v_cvt_pk_bf16_f32 v89, v90, s0
	v_add_co_u32_e32 v90, vcc, 0x33600000, v6
	s_nop 1
	v_addc_co_u32_e32 v91, vcc, 0, v7, vcc
	global_store_short v[90:91], v89, off offset:1280
	s_and_saveexec_b64 s[4:5], s[38:39]
	s_cbranch_execz .LBB0_303
	s_ashr_i32 s85, s84, 31
	s_lshl_b64 s[30:31], s[84:85], 6
	s_add_u32 s30, s2, s30
	v_mov_b32_e32 v90, s15
	v_mov_b32_e32 v91, s17
	s_addc_u32 s31, s14, s31
	v_pk_add_f32 v[90:91], s[0:1], v[90:91]
	s_nop 0
	v_add_f32_e32 v89, v90, v91
	v_mov_b64_e32 v[90:91], s[30:31]
	global_store_dword v[90:91], v89, off
.LBB0_303:
	s_or_b64 exec, exec, s[4:5]
	s_add_i32 s0, s11, s16
	s_cmpk_gt_i32 s0, 0x3fff
	s_cbranch_scc1 .Lpcpf_skip_10
	s_movk_i32 s0, 0x3400
	s_mov_b32 s1, 0
	v_lshl_add_u64 v[146:147], v[146:147], 0, s[0:1]
	s_movk_i32 s0, 0x1800
	v_lshl_add_u64 v[148:149], v[148:149], 0, s[0:1]
	global_load_ushort v99, v[146:147], off offset:-2048
	global_load_ushort v100, v[146:147], off
	global_load_ushort v101, v[146:147], off offset:2048
	global_load_ushort v95, v[148:149], off
	global_load_ushort v98, v[148:149], off offset:2048
; __device__ __forceinline__ float bf2f(bf16 b) { return __uint_as_float((unsigned)b << 16); }
; __device__ __forceinline__ bf16 f2bf(float f) { return (bf16)(pk_bf16(f, 0.f) & 0xffffu); }
; __device__ __forceinline__ float fexp(float x) { return __builtin_amdgcn_exp2f(x * 1.4426950408889634f); }
; __device__ __forceinline__ float flog(float x) { return __builtin_amdgcn_logf(x) * 0.6931471805599453f; }
; __device__ __forceinline__ float fsigmoid(float x) { return __builtin_amdgcn_rcpf(1.0f + fexp(-x)); }
; __device__ __forceinline__ void pc_phase(LAS unsigned char* lds, const bf16* Pp_, const bf16* LO, const float* mu, const float* w0, const float* a0, const float* k_k, const float* k_a, const float* r_k, ...
;     ...
;         for (int t = 0; t < 16; ++t) {
;             const float r0 = bf2f(sr_[t + 1]), k0 = bf2f(sk_[t + 1]), v0 = bf2f(sv_[t + 1]);
;             const float r = r0 + (r1 - r0) * mu_r, k = k0 + (k1 - k0) * mu_k, v = v0 + (v1 - v0) * mu_v; r1 = r0; k1 = k0; v1 = v0;
;             const float z = -(w0c + bf2f(slw[t])); const float sp = fmaxf(z, 0.f) + flog(1.0f + fexp(-fabsf(z))); const float w = -sp - 0.5f;
;             const float dec = fexp(-fexp(w)); const float a = fsigmoid(a0c + bf2f(sla[t]));
;             float kk = k * kkc; const float n2 = wsum_dpp(kk * kk); kk = kk / fmaxf(sqrtf(n2), 1e-12f);
;             const float kp = bf2f(f2bf(k * (1.0f + (a - 1.0f) * kac))), bb = bf2f(f2bf(kk * a)), rr = bf2f(f2bf(r)); kk = bf2f(f2bf(kk));
;             const float coef = wsum_dpp(rr * kp * rkc);
;             SV[(ib + t) * 64 + lane] = f2bf(v);
;             if (lane == 0) COEF[(size_t)(m0 + t) * 16 + h] = coef;
;             const float Pp = P; P *= dec; const float inv = 1.0f / P;
;             XKK[t * 72 + lane] = f2bf(kk * Pp); XR[t * 72 + lane] = f2bf(rr * P); XK[t * 72 + lane] = f2bf(kp * inv); XB[t * 72 + lane] = f2bf(bb * inv); }
.Lpcpf_skip_10:
	v_lshlrev_b32_e32 v80, 16, v80
	v_add_f32_e32 v80, v8, v80
	v_mul_f32_e64 v89, |v80|, s19
	v_exp_f32_e32 v89, v89
	v_mov_b32_e32 v90, s8
	v_mov_b32_e32 v91, s9
	v_add_f32_e32 v90, s7, v90
	v_add_f32_e32 v89, 1.0, v89
	v_log_f32_e32 v89, v89
	v_add_f32_e32 v91, s6, v91
	v_max_f32_e64 v80, -v80, 0
	v_add_f32_e32 v90, v90, v91
	v_fmac_f32_e32 v80, 0x3f317218, v89
	v_mul_f32_e32 v89, 0x4f800000, v90
	v_cmp_gt_f32_e32 vcc, s33, v90
	v_sub_f32_e32 v80, -0.5, v80
	v_mul_f32_e32 v80, 0x3fb8aa3b, v80
	v_cndmask_b32_e32 v89, v90, v89, vcc
	v_sqrt_f32_e32 v90, v89
	v_exp_f32_e32 v80, v80
	v_lshlrev_b32_e32 v76, 16, v76
	v_add_f32_e32 v76, v15, v76
	v_add_u32_e32 v91, -1, v90
	v_fma_f32 v92, -v91, v90, v89
	v_cmp_ge_f32_e64 s[56:57], 0, v92
	v_add_u32_e32 v92, 1, v90
	v_mul_f32_e32 v80, 0xbfb8aa3b, v80
	v_cndmask_b32_e64 v91, v90, v91, s[56:57]
	v_fma_f32 v90, -v92, v90, v89
	v_cmp_lt_f32_e64 s[56:57], 0, v90
	v_exp_f32_e32 v80, v80
	v_mul_f32_e32 v76, 0xbfb8aa3b, v76
	v_cndmask_b32_e64 v90, v91, v92, s[56:57]
	v_mul_f32_e32 v91, 0x37800000, v90
	v_cndmask_b32_e32 v90, v90, v91, vcc
	v_cmp_class_f32_e32 vcc, v89, v219
	v_mul_f32_e32 v80, v85, v80
	v_exp_f32_e32 v76, v76
	v_cndmask_b32_e32 v89, v90, v89, vcc
	v_max_f32_e32 v89, 0x2b8cbccc, v89
	v_div_scale_f32 v90, s[0:1], v89, v89, v88
	v_rcp_f32_e32 v91, v90
	v_mul_f32_e32 v84, v80, v84
	v_lshlrev_b32_e32 v78, 16, v78
	v_sub_f32_e32 v83, v83, v78
	v_fma_f32 v92, -v90, v91, 1.0
	v_fmac_f32_e32 v91, v92, v91
	v_div_scale_f32 v92, vcc, v88, v89, v88
	v_mul_f32_e32 v93, v92, v91
	v_fma_f32 v94, -v90, v93, v92
	v_fmac_f32_e32 v93, v94, v91
	v_fma_f32 v90, -v90, v93, v92
	v_div_fmas_f32 v90, v90, v91, v93
	v_div_fixup_f32 v88, v90, v89, v88
	v_mul_f32_e32 v87, v87, v88
	v_cvt_pk_bf16_f32 v87, v87, s0
	v_div_scale_f32 v89, s[0:1], v80, v80, 1.0
	v_rcp_f32_e32 v90, v89
	v_lshlrev_b32_e32 v87, 16, v87
	v_cvt_pk_bf16_f32 v88, v88, s0
	v_lshlrev_b32_e32 v88, 16, v88
	v_fma_f32 v91, -v89, v90, 1.0
	v_fmac_f32_e32 v90, v91, v90
	v_div_scale_f32 v91, vcc, 1.0, v80, 1.0
	v_mul_f32_e32 v92, v91, v90
	v_fma_f32 v93, -v89, v92, v91
	v_fmac_f32_e32 v92, v93, v90
	v_fma_f32 v89, -v89, v92, v91
	v_div_fmas_f32 v89, v89, v90, v92
	v_div_fixup_f32 v89, v89, v80, 1.0
	v_mul_f32_e32 v81, v89, v81
	v_cvt_pk_bf16_f32 v81, v81, s0
	ds_write_b16 v27, v81 offset:6048
	v_mul_f32_e32 v81, v89, v87
	v_cvt_pk_bf16_f32 v84, v84, s0
	v_cvt_pk_bf16_f32 v81, v81, s0
	v_mul_f32_e32 v85, v85, v88
	ds_write_b16 v27, v84 offset:3744
	ds_write_b16 v27, v81 offset:8352
	v_lshlrev_b32_e32 v81, 16, v77
	v_lshlrev_b32_e32 v77, 16, v79
	v_fma_f32 v84, v9, v83, v78
	v_cvt_pk_bf16_f32 v85, v85, s0
	v_sub_f32_e32 v82, v82, v77
	v_add_f32_e32 v76, 1.0, v76
	v_mul_f32_e32 v83, v14, v84
	ds_write_b16 v27, v85 offset:1440
	v_fma_f32 v85, v12, v82, v77
	v_rcp_f32_e32 v82, v76
	v_mul_f32_e32 v76, v83, v83
	v_sub_f32_e32 v79, v86, v81
	v_fma_f32 v79, v10, v79, v81
	v_mov_b32_dpp v76, v76 quad_perm:[1,0,3,2] row_mask:0xf bank_mask:0xf bound_ctrl:1
	v_fmac_f32_e32 v76, v83, v83
	v_cvt_pk_bf16_f32 v79, v79, s0
	v_lshlrev_b32_e32 v79, 16, v79
	v_add_f32_dpp v76, v76, v76 quad_perm:[2,3,0,1] row_mask:0xf bank_mask:0xf bound_ctrl:1
	s_nop 1
	v_add_f32_dpp v76, v76, v76 row_ror:4 row_mask:0xf bank_mask:0xf bound_ctrl:1
	s_nop 1
	v_add_f32_dpp v76, v76, v76 row_ror:8 row_mask:0xf bank_mask:0xf bound_ctrl:1
	s_nop 0
	v_readlane_b32 s7, v76, 0
	v_readlane_b32 s8, v76, 16
	v_readlane_b32 s6, v76, 32
	v_readlane_b32 s9, v76, 48
	v_add_f32_e32 v76, -1.0, v82
	v_fma_f32 v76, v13, v76, 1.0
	v_mul_f32_e32 v76, v84, v76
	v_cvt_pk_bf16_f32 v76, v76, s0
	v_lshlrev_b32_e32 v76, 16, v76
	v_mul_f32_e32 v84, v79, v76
	v_mul_f32_e32 v86, v11, v84
	s_nop 1
	v_mov_b32_dpp v86, v86 quad_perm:[1,0,3,2] row_mask:0xf bank_mask:0xf bound_ctrl:1
	v_fmac_f32_e32 v86, v11, v84
	s_nop 1
	v_add_f32_dpp v84, v86, v86 quad_perm:[2,3,0,1] row_mask:0xf bank_mask:0xf bound_ctrl:1
	s_nop 1
	v_add_f32_dpp v84, v84, v84 row_ror:4 row_mask:0xf bank_mask:0xf bound_ctrl:1
	s_nop 1
	v_add_f32_dpp v84, v84, v84 row_ror:8 row_mask:0xf bank_mask:0xf bound_ctrl:1
	s_nop 0
	v_readlane_b32 s0, v84, 0
	v_readlane_b32 s15, v84, 16
	v_readlane_b32 s1, v84, 32
	v_readlane_b32 s17, v84, 48
	v_add_co_u32_e32 v84, vcc, 0x33600000, v6
	v_cvt_pk_bf16_f32 v86, v85, s0
	s_nop 0
	v_addc_co_u32_e32 v85, vcc, 0, v7, vcc
	global_store_short v[84:85], v86, off offset:1408
	s_and_saveexec_b64 s[4:5], s[38:39]
	s_cbranch_execz .LBB0_305
	s_ashr_i32 s83, s82, 31
	s_lshl_b64 s[30:31], s[82:83], 6
	s_add_u32 s30, s2, s30
	v_mov_b32_e32 v84, s15
	v_mov_b32_e32 v85, s17
	s_addc_u32 s31, s14, s31
	v_pk_add_f32 v[84:85], s[0:1], v[84:85]
	s_nop 0
	v_add_f32_e32 v86, v84, v85
	v_mov_b64_e32 v[84:85], s[30:31]
	global_store_dword v[84:85], v86, off
.LBB0_305:
	s_or_b64 exec, exec, s[4:5]
	s_add_i32 s0, s11, s16
	s_cmpk_gt_i32 s0, 0x3fff
	s_cbranch_scc1 .Lpcpf_skip_11
	s_movk_i32 s0, 0x3400
	s_mov_b32 s1, 0
	v_lshl_add_u64 v[146:147], v[146:147], 0, s[0:1]
	s_movk_i32 s0, 0x1800
	v_lshl_add_u64 v[148:149], v[148:149], 0, s[0:1]
	global_load_ushort v92, v[146:147], off offset:-2048
	global_load_ushort v93, v[146:147], off
	global_load_ushort v94, v[146:147], off offset:2048
	global_load_ushort v90, v[148:149], off
	global_load_ushort v91, v[148:149], off offset:2048
; __device__ __forceinline__ float bf2f(bf16 b) { return __uint_as_float((unsigned)b << 16); }
; __device__ __forceinline__ bf16 f2bf(float f) { return (bf16)(pk_bf16(f, 0.f) & 0xffffu); }
; __device__ __forceinline__ float fexp(float x) { return __builtin_amdgcn_exp2f(x * 1.4426950408889634f); }
; __device__ __forceinline__ float flog(float x) { return __builtin_amdgcn_logf(x) * 0.6931471805599453f; }
; __device__ __forceinline__ float fsigmoid(float x) { return __builtin_amdgcn_rcpf(1.0f + fexp(-x)); }
; __device__ __forceinline__ void pc_phase(LAS unsigned char* lds, const bf16* Pp_, const bf16* LO, const float* mu, const float* w0, const float* a0, const float* k_k, const float* k_a, const float* r_k, ...
;     ...
;         for (int t = 0; t < 16; ++t) {
;             const float r0 = bf2f(sr_[t + 1]), k0 = bf2f(sk_[t + 1]), v0 = bf2f(sv_[t + 1]);
;             const float r = r0 + (r1 - r0) * mu_r, k = k0 + (k1 - k0) * mu_k, v = v0 + (v1 - v0) * mu_v; r1 = r0; k1 = k0; v1 = v0;
;             const float z = -(w0c + bf2f(slw[t])); const float sp = fmaxf(z, 0.f) + flog(1.0f + fexp(-fabsf(z))); const float w = -sp - 0.5f;
;             const float dec = fexp(-fexp(w)); const float a = fsigmoid(a0c + bf2f(sla[t]));
;             float kk = k * kkc; const float n2 = wsum_dpp(kk * kk); kk = kk / fmaxf(sqrtf(n2), 1e-12f);
;             const float kp = bf2f(f2bf(k * (1.0f + (a - 1.0f) * kac))), bb = bf2f(f2bf(kk * a)), rr = bf2f(f2bf(r)); kk = bf2f(f2bf(kk));
;             const float coef = wsum_dpp(rr * kp * rkc);
;             SV[(ib + t) * 64 + lane] = f2bf(v);
;             if (lane == 0) COEF[(size_t)(m0 + t) * 16 + h] = coef;
;             const float Pp = P; P *= dec; const float inv = 1.0f / P;
;             XKK[t * 72 + lane] = f2bf(kk * Pp); XR[t * 72 + lane] = f2bf(rr * P); XK[t * 72 + lane] = f2bf(kp * inv); XB[t * 72 + lane] = f2bf(bb * inv); }
.Lpcpf_skip_11:
	v_lshlrev_b32_e32 v75, 16, v75
	v_add_f32_e32 v75, v8, v75
	v_mul_f32_e64 v84, |v75|, s19
	v_exp_f32_e32 v84, v84
	v_mov_b32_e32 v85, s8
	v_mov_b32_e32 v86, s9
	v_add_f32_e32 v85, s7, v85
	v_add_f32_e32 v84, 1.0, v84
	v_log_f32_e32 v84, v84
	v_add_f32_e32 v86, s6, v86
	v_max_f32_e64 v75, -v75, 0
	v_add_f32_e32 v85, v85, v86
	v_fmac_f32_e32 v75, 0x3f317218, v84
	v_mul_f32_e32 v84, 0x4f800000, v85
	v_cmp_gt_f32_e32 vcc, s33, v85
	v_sub_f32_e32 v75, -0.5, v75
	v_mul_f32_e32 v75, 0x3fb8aa3b, v75
	v_cndmask_b32_e32 v84, v85, v84, vcc
	v_sqrt_f32_e32 v85, v84
	v_exp_f32_e32 v75, v75
	v_lshlrev_b32_e32 v71, 16, v71
	v_add_f32_e32 v71, v15, v71
	v_add_u32_e32 v86, -1, v85
	v_fma_f32 v87, -v86, v85, v84
	v_cmp_ge_f32_e64 s[56:57], 0, v87
	v_add_u32_e32 v87, 1, v85
	v_mul_f32_e32 v75, 0xbfb8aa3b, v75
	v_cndmask_b32_e64 v86, v85, v86, s[56:57]
	v_fma_f32 v85, -v87, v85, v84
	v_cmp_lt_f32_e64 s[56:57], 0, v85
	v_exp_f32_e32 v75, v75
	v_mul_f32_e32 v71, 0xbfb8aa3b, v71
	v_cndmask_b32_e64 v85, v86, v87, s[56:57]
	v_mul_f32_e32 v86, 0x37800000, v85
	v_cndmask_b32_e32 v85, v85, v86, vcc
	v_cmp_class_f32_e32 vcc, v84, v219
	v_mul_f32_e32 v75, v80, v75
	v_exp_f32_e32 v71, v71
	v_cndmask_b32_e32 v84, v85, v84, vcc
	v_max_f32_e32 v84, 0x2b8cbccc, v84
	v_div_scale_f32 v85, s[0:1], v84, v84, v83
	v_rcp_f32_e32 v86, v85
	v_mul_f32_e32 v79, v75, v79
	v_lshlrev_b32_e32 v73, 16, v73
	v_sub_f32_e32 v78, v78, v73
	v_fma_f32 v87, -v85, v86, 1.0
	v_fmac_f32_e32 v86, v87, v86
	v_div_scale_f32 v87, vcc, v83, v84, v83
	v_mul_f32_e32 v88, v87, v86
	v_fma_f32 v89, -v85, v88, v87
	v_fmac_f32_e32 v88, v89, v86
	v_fma_f32 v85, -v85, v88, v87
	v_div_fmas_f32 v85, v85, v86, v88
	v_div_fixup_f32 v83, v85, v84, v83
	v_mul_f32_e32 v82, v82, v83
	v_cvt_pk_bf16_f32 v82, v82, s0
	v_div_scale_f32 v84, s[0:1], v75, v75, 1.0
	v_rcp_f32_e32 v85, v84
	v_lshlrev_b32_e32 v82, 16, v82
	v_cvt_pk_bf16_f32 v83, v83, s0
	v_lshlrev_b32_e32 v83, 16, v83
	v_fma_f32 v86, -v84, v85, 1.0
	v_fmac_f32_e32 v85, v86, v85
	v_div_scale_f32 v86, vcc, 1.0, v75, 1.0
	v_mul_f32_e32 v87, v86, v85
	v_fma_f32 v88, -v84, v87, v86
	v_fmac_f32_e32 v87, v88, v85
	v_fma_f32 v84, -v84, v87, v86
	v_div_fmas_f32 v84, v84, v85, v87
	v_div_fixup_f32 v84, v84, v75, 1.0
	v_mul_f32_e32 v76, v84, v76
	v_cvt_pk_bf16_f32 v76, v76, s0
	ds_write_b16 v27, v76 offset:6192
	v_mul_f32_e32 v76, v84, v82
	v_cvt_pk_bf16_f32 v79, v79, s0
	v_cvt_pk_bf16_f32 v76, v76, s0
	v_mul_f32_e32 v80, v80, v83
	ds_write_b16 v27, v79 offset:3888
	ds_write_b16 v27, v76 offset:8496
	v_lshlrev_b32_e32 v76, 16, v72
	v_lshlrev_b32_e32 v72, 16, v74
	v_fma_f32 v79, v9, v78, v73
	v_cvt_pk_bf16_f32 v80, v80, s0
	v_sub_f32_e32 v77, v77, v72
	v_add_f32_e32 v71, 1.0, v71
	v_mul_f32_e32 v78, v14, v79
	ds_write_b16 v27, v80 offset:1584
	v_fma_f32 v80, v12, v77, v72
	v_rcp_f32_e32 v77, v71
	v_mul_f32_e32 v71, v78, v78
	v_sub_f32_e32 v74, v81, v76
	v_fma_f32 v74, v10, v74, v76
	v_mov_b32_dpp v71, v71 quad_perm:[1,0,3,2] row_mask:0xf bank_mask:0xf bound_ctrl:1
	v_fmac_f32_e32 v71, v78, v78
	v_cvt_pk_bf16_f32 v74, v74, s0
	v_lshlrev_b32_e32 v74, 16, v74
	v_add_f32_dpp v71, v71, v71 quad_perm:[2,3,0,1] row_mask:0xf bank_mask:0xf bound_ctrl:1
	s_nop 1
	v_add_f32_dpp v71, v71, v71 row_ror:4 row_mask:0xf bank_mask:0xf bound_ctrl:1
	s_nop 1
	v_add_f32_dpp v71, v71, v71 row_ror:8 row_mask:0xf bank_mask:0xf bound_ctrl:1
	s_nop 0
	v_readlane_b32 s7, v71, 0
	v_readlane_b32 s8, v71, 16
	v_readlane_b32 s6, v71, 32
	v_readlane_b32 s9, v71, 48
	v_add_f32_e32 v71, -1.0, v77
	v_fma_f32 v71, v13, v71, 1.0
	v_mul_f32_e32 v71, v79, v71
	v_cvt_pk_bf16_f32 v71, v71, s0
	v_lshlrev_b32_e32 v71, 16, v71
	v_mul_f32_e32 v79, v74, v71
	v_mul_f32_e32 v81, v11, v79
	s_nop 1
	v_mov_b32_dpp v81, v81 quad_perm:[1,0,3,2] row_mask:0xf bank_mask:0xf bound_ctrl:1
	v_fmac_f32_e32 v81, v11, v79
	s_nop 1
	v_add_f32_dpp v79, v81, v81 quad_perm:[2,3,0,1] row_mask:0xf bank_mask:0xf bound_ctrl:1
	s_nop 1
	v_add_f32_dpp v79, v79, v79 row_ror:4 row_mask:0xf bank_mask:0xf bound_ctrl:1
	s_nop 1
	v_add_f32_dpp v79, v79, v79 row_ror:8 row_mask:0xf bank_mask:0xf bound_ctrl:1
	s_nop 0
	v_readlane_b32 s0, v79, 0
	v_readlane_b32 s15, v79, 16
	v_readlane_b32 s1, v79, 32
	v_readlane_b32 s17, v79, 48
	v_cvt_pk_bf16_f32 v79, v80, s0
	v_add_co_u32_e32 v80, vcc, 0x33600000, v6
	s_nop 1
	v_addc_co_u32_e32 v81, vcc, 0, v7, vcc
	global_store_short v[80:81], v79, off offset:1536
	s_and_saveexec_b64 s[4:5], s[38:39]
	s_cbranch_execz .LBB0_307
	s_ashr_i32 s81, s80, 31
	s_lshl_b64 s[30:31], s[80:81], 6
	s_add_u32 s30, s2, s30
	v_mov_b32_e32 v80, s15
	v_mov_b32_e32 v81, s17
	s_addc_u32 s31, s14, s31
	v_pk_add_f32 v[80:81], s[0:1], v[80:81]
	s_nop 0
	v_add_f32_e32 v79, v80, v81
	v_mov_b64_e32 v[80:81], s[30:31]
	global_store_dword v[80:81], v79, off
.LBB0_307:
	s_or_b64 exec, exec, s[4:5]
	s_add_i32 s0, s11, s16
	s_cmpk_gt_i32 s0, 0x3fff
	s_cbranch_scc1 .Lpcpf_skip_12
	s_movk_i32 s0, 0x3400
	s_mov_b32 s1, 0
	v_lshl_add_u64 v[146:147], v[146:147], 0, s[0:1]
	s_movk_i32 s0, 0x1800
	v_lshl_add_u64 v[148:149], v[148:149], 0, s[0:1]
	global_load_ushort v164, v[146:147], off offset:-2048
	global_load_ushort v165, v[146:147], off
	global_load_ushort v166, v[146:147], off offset:2048
	global_load_ushort v167, v[148:149], off
	global_load_ushort v168, v[148:149], off offset:2048
	s_movk_i32 s0, 0x3400
	s_mov_b32 s1, 0
	v_lshl_add_u64 v[146:147], v[146:147], 0, s[0:1]
	s_movk_i32 s0, 0x1800
	v_lshl_add_u64 v[148:149], v[148:149], 0, s[0:1]
	global_load_ushort v169, v[146:147], off offset:-2048
	global_load_ushort v170, v[146:147], off
	global_load_ushort v171, v[146:147], off offset:2048
	global_load_ushort v172, v[148:149], off
	global_load_ushort v173, v[148:149], off offset:2048
; __device__ __forceinline__ float bf2f(bf16 b) { return __uint_as_float((unsigned)b << 16); }
; __device__ __forceinline__ bf16 f2bf(float f) { return (bf16)(pk_bf16(f, 0.f) & 0xffffu); }
; __device__ __forceinline__ float fexp(float x) { return __builtin_amdgcn_exp2f(x * 1.4426950408889634f); }
; __device__ __forceinline__ float flog(float x) { return __builtin_amdgcn_logf(x) * 0.6931471805599453f; }
; __device__ __forceinline__ float fsigmoid(float x) { return __builtin_amdgcn_rcpf(1.0f + fexp(-x)); }
; __device__ __forceinline__ void pc_phase(LAS unsigned char* lds, const bf16* Pp_, const bf16* LO, const float* mu, const float* w0, const float* a0, const float* k_k, const float* k_a, const float* r_k, ...
;     ...
;         for (int t = 0; t < 16; ++t) {
;             const float r0 = bf2f(sr_[t + 1]), k0 = bf2f(sk_[t + 1]), v0 = bf2f(sv_[t + 1]);
;             const float r = r0 + (r1 - r0) * mu_r, k = k0 + (k1 - k0) * mu_k, v = v0 + (v1 - v0) * mu_v; r1 = r0; k1 = k0; v1 = v0;
;             const float z = -(w0c + bf2f(slw[t])); const float sp = fmaxf(z, 0.f) + flog(1.0f + fexp(-fabsf(z))); const float w = -sp - 0.5f;
;             const float dec = fexp(-fexp(w)); const float a = fsigmoid(a0c + bf2f(sla[t]));
;             float kk = k * kkc; const float n2 = wsum_dpp(kk * kk); kk = kk / fmaxf(sqrtf(n2), 1e-12f);
;             const float kp = bf2f(f2bf(k * (1.0f + (a - 1.0f) * kac))), bb = bf2f(f2bf(kk * a)), rr = bf2f(f2bf(r)); kk = bf2f(f2bf(kk));
;             const float coef = wsum_dpp(rr * kp * rkc);
;             SV[(ib + t) * 64 + lane] = f2bf(v);
;             if (lane == 0) COEF[(size_t)(m0 + t) * 16 + h] = coef;
;             const float Pp = P; P *= dec; const float inv = 1.0f / P;
;             XKK[t * 72 + lane] = f2bf(kk * Pp); XR[t * 72 + lane] = f2bf(rr * P); XK[t * 72 + lane] = f2bf(kp * inv); XB[t * 72 + lane] = f2bf(bb * inv); }
.Lpcpf_skip_12:
	v_lshlrev_b32_e32 v70, 16, v70
	v_add_f32_e32 v70, v8, v70
	v_mul_f32_e64 v79, |v70|, s19
	v_exp_f32_e32 v79, v79
	v_mov_b32_e32 v80, s8
	v_mov_b32_e32 v81, s9
	v_add_f32_e32 v80, s7, v80
	v_add_f32_e32 v79, 1.0, v79
	v_log_f32_e32 v79, v79
	v_add_f32_e32 v81, s6, v81
	v_max_f32_e64 v70, -v70, 0
	v_add_f32_e32 v80, v80, v81
	v_fmac_f32_e32 v70, 0x3f317218, v79
	v_mul_f32_e32 v79, 0x4f800000, v80
	v_cmp_gt_f32_e32 vcc, s33, v80
	v_sub_f32_e32 v70, -0.5, v70
	v_mul_f32_e32 v70, 0x3fb8aa3b, v70
	v_cndmask_b32_e32 v79, v80, v79, vcc
	v_sqrt_f32_e32 v80, v79
	v_exp_f32_e32 v70, v70
	v_lshlrev_b32_e32 v69, 16, v69
	v_add_f32_e32 v69, v15, v69
	v_add_u32_e32 v81, -1, v80
	v_fma_f32 v82, -v81, v80, v79
	v_cmp_ge_f32_e64 s[56:57], 0, v82
	v_add_u32_e32 v82, 1, v80
	v_mul_f32_e32 v70, 0xbfb8aa3b, v70
	v_cndmask_b32_e64 v81, v80, v81, s[56:57]
	v_fma_f32 v80, -v82, v80, v79
	v_cmp_lt_f32_e64 s[56:57], 0, v80
	v_exp_f32_e32 v70, v70
	v_mul_f32_e32 v69, 0xbfb8aa3b, v69
	v_cndmask_b32_e64 v80, v81, v82, s[56:57]
	v_mul_f32_e32 v81, 0x37800000, v80
	v_cndmask_b32_e32 v80, v80, v81, vcc
	v_cmp_class_f32_e32 vcc, v79, v219
	v_mul_f32_e32 v70, v75, v70
	v_mul_f32_e32 v74, v70, v74
	v_cndmask_b32_e32 v79, v80, v79, vcc
	v_max_f32_e32 v79, 0x2b8cbccc, v79
	v_div_scale_f32 v80, s[0:1], v79, v79, v78
	v_rcp_f32_e32 v81, v80
	v_exp_f32_e32 v69, v69
	v_lshlrev_b32_e32 v67, 16, v67
	v_fma_f32 v82, -v80, v81, 1.0
	v_fmac_f32_e32 v81, v82, v81
	v_div_scale_f32 v82, vcc, v78, v79, v78
	v_mul_f32_e32 v83, v82, v81
	v_fma_f32 v84, -v80, v83, v82
	v_fmac_f32_e32 v83, v84, v81
	v_fma_f32 v80, -v80, v83, v82
	v_div_fmas_f32 v80, v80, v81, v83
	v_div_fixup_f32 v78, v80, v79, v78
	v_mul_f32_e32 v77, v77, v78
	v_cvt_pk_bf16_f32 v77, v77, s0
	v_div_scale_f32 v79, s[0:1], v70, v70, 1.0
	v_rcp_f32_e32 v80, v79
	v_lshlrev_b32_e32 v77, 16, v77
	v_cvt_pk_bf16_f32 v78, v78, s0
	v_cvt_pk_bf16_f32 v74, v74, s0
	v_fma_f32 v81, -v79, v80, 1.0
	v_fmac_f32_e32 v80, v81, v80
	v_div_scale_f32 v81, vcc, 1.0, v70, 1.0
	v_mul_f32_e32 v82, v81, v80
	v_fma_f32 v83, -v79, v82, v81
	v_fmac_f32_e32 v82, v83, v80
	v_fma_f32 v79, -v79, v82, v81
	v_div_fmas_f32 v79, v79, v80, v82
	v_div_fixup_f32 v79, v79, v70, 1.0
	v_mul_f32_e32 v71, v79, v71
	v_cvt_pk_bf16_f32 v71, v71, s0
	ds_write_b16 v27, v71 offset:6336
	v_mul_f32_e32 v71, v79, v77
	v_cvt_pk_bf16_f32 v71, v71, s0
	ds_write_b16 v27, v71 offset:8640
	v_lshlrev_b32_e32 v71, 16, v66
	v_lshlrev_b32_e32 v66, 16, v68
	v_sub_f32_e32 v68, v76, v71
	v_lshlrev_b32_e32 v78, 16, v78
	ds_write_b16 v27, v74 offset:4032
	v_fma_f32 v74, v10, v68, v71
	v_sub_f32_e32 v68, v73, v67
	v_mul_f32_e32 v75, v75, v78
	v_fma_f32 v68, v9, v68, v67
	v_cvt_pk_bf16_f32 v75, v75, s0
	v_sub_f32_e32 v72, v72, v66
	v_add_f32_e32 v69, 1.0, v69
	v_mul_f32_e32 v73, v14, v68
	ds_write_b16 v27, v75 offset:1728
	v_fma_f32 v75, v12, v72, v66
	v_rcp_f32_e32 v72, v69
	v_mul_f32_e32 v69, v73, v73
	s_nop 1
	v_mov_b32_dpp v69, v69 quad_perm:[1,0,3,2] row_mask:0xf bank_mask:0xf bound_ctrl:1
	v_fmac_f32_e32 v69, v73, v73
	s_nop 1
	v_add_f32_dpp v69, v69, v69 quad_perm:[2,3,0,1] row_mask:0xf bank_mask:0xf bound_ctrl:1
	s_nop 1
	v_add_f32_dpp v69, v69, v69 row_ror:4 row_mask:0xf bank_mask:0xf bound_ctrl:1
	s_nop 1
	v_add_f32_dpp v69, v69, v69 row_ror:8 row_mask:0xf bank_mask:0xf bound_ctrl:1
	s_nop 0
	v_readlane_b32 s7, v69, 0
	v_readlane_b32 s8, v69, 16
	v_readlane_b32 s6, v69, 32
	v_readlane_b32 s9, v69, 48
	v_add_f32_e32 v69, -1.0, v72
	v_fma_f32 v69, v13, v69, 1.0
	v_mul_f32_e32 v68, v68, v69
	v_cvt_pk_bf16_f32 v68, v68, s0
	v_cvt_pk_bf16_f32 v69, v74, s0
	v_lshlrev_b32_e32 v68, 16, v68
	v_lshlrev_b32_e32 v69, 16, v69
	v_mul_f32_e32 v74, v69, v68
	v_mul_f32_e32 v76, v11, v74
	s_nop 1
	v_mov_b32_dpp v76, v76 quad_perm:[1,0,3,2] row_mask:0xf bank_mask:0xf bound_ctrl:1
	v_fmac_f32_e32 v76, v11, v74
	s_nop 1
	v_add_f32_dpp v74, v76, v76 quad_perm:[2,3,0,1] row_mask:0xf bank_mask:0xf bound_ctrl:1
	s_nop 1
	v_add_f32_dpp v74, v74, v74 row_ror:4 row_mask:0xf bank_mask:0xf bound_ctrl:1
	s_nop 1
	v_add_f32_dpp v74, v74, v74 row_ror:8 row_mask:0xf bank_mask:0xf bound_ctrl:1
	s_nop 0
	v_readlane_b32 s0, v74, 0
	v_readlane_b32 s15, v74, 16
	v_readlane_b32 s1, v74, 32
	v_readlane_b32 s17, v74, 48
	v_add_co_u32_e32 v74, vcc, 0x33600000, v6
	v_cvt_pk_bf16_f32 v76, v75, s0
	s_nop 0
	v_addc_co_u32_e32 v75, vcc, 0, v7, vcc
	global_store_short v[74:75], v76, off offset:1664
	s_and_saveexec_b64 s[4:5], s[38:39]
	s_cbranch_execz .LBB0_309
	s_mov_b32 s34, s79
	s_ashr_i32 s79, s78, 31
	s_lshl_b64 s[30:31], s[78:79], 6
	s_add_u32 s30, s2, s30
	v_mov_b32_e32 v74, s15
	v_mov_b32_e32 v75, s17
	s_addc_u32 s31, s14, s31
	v_pk_add_f32 v[74:75], s[0:1], v[74:75]
	s_mov_b32 s79, s34
	v_add_f32_e32 v76, v74, v75
	v_mov_b64_e32 v[74:75], s[30:31]
	global_store_dword v[74:75], v76, off
.LBB0_309:
	s_or_b64 exec, exec, s[4:5]
	s_add_i32 s0, s11, s16
	s_cmpk_gt_i32 s0, 0x3fff
	s_cbranch_scc1 .Lpcpf_skip_13
	s_movk_i32 s0, 0x3400
	s_mov_b32 s1, 0
	v_lshl_add_u64 v[146:147], v[146:147], 0, s[0:1]
	s_movk_i32 s0, 0x1800
	v_lshl_add_u64 v[148:149], v[148:149], 0, s[0:1]
	global_load_ushort v174, v[146:147], off offset:-2048
	global_load_ushort v175, v[146:147], off
	global_load_ushort v176, v[146:147], off offset:2048
	global_load_ushort v177, v[148:149], off
	global_load_ushort v178, v[148:149], off offset:2048
	s_movk_i32 s0, 0x3400
	s_mov_b32 s1, 0
	v_lshl_add_u64 v[146:147], v[146:147], 0, s[0:1]
	s_movk_i32 s0, 0x1800
	v_lshl_add_u64 v[148:149], v[148:149], 0, s[0:1]
	global_load_ushort v179, v[146:147], off offset:-2048
	global_load_ushort v180, v[146:147], off
	global_load_ushort v181, v[146:147], off offset:2048
	global_load_ushort v182, v[148:149], off
	global_load_ushort v183, v[148:149], off offset:2048
; __device__ __forceinline__ float bf2f(bf16 b) { return __uint_as_float((unsigned)b << 16); }
; __device__ __forceinline__ bf16 f2bf(float f) { return (bf16)(pk_bf16(f, 0.f) & 0xffffu); }
; __device__ __forceinline__ float fexp(float x) { return __builtin_amdgcn_exp2f(x * 1.4426950408889634f); }
; __device__ __forceinline__ float flog(float x) { return __builtin_amdgcn_logf(x) * 0.6931471805599453f; }
; __device__ __forceinline__ float fsigmoid(float x) { return __builtin_amdgcn_rcpf(1.0f + fexp(-x)); }
; __device__ __forceinline__ void pc_phase(LAS unsigned char* lds, const bf16* Pp_, const bf16* LO, const float* mu, const float* w0, const float* a0, const float* k_k, const float* k_a, const float* r_k, ...
;     ...
;         for (int t = 0; t < 16; ++t) {
;             const float r0 = bf2f(sr_[t + 1]), k0 = bf2f(sk_[t + 1]), v0 = bf2f(sv_[t + 1]);
;             const float r = r0 + (r1 - r0) * mu_r, k = k0 + (k1 - k0) * mu_k, v = v0 + (v1 - v0) * mu_v; r1 = r0; k1 = k0; v1 = v0;
;             const float z = -(w0c + bf2f(slw[t])); const float sp = fmaxf(z, 0.f) + flog(1.0f + fexp(-fabsf(z))); const float w = -sp - 0.5f;
;             const float dec = fexp(-fexp(w)); const float a = fsigmoid(a0c + bf2f(sla[t]));
;             float kk = k * kkc; const float n2 = wsum_dpp(kk * kk); kk = kk / fmaxf(sqrtf(n2), 1e-12f);
;             const float kp = bf2f(f2bf(k * (1.0f + (a - 1.0f) * kac))), bb = bf2f(f2bf(kk * a)), rr = bf2f(f2bf(r)); kk = bf2f(f2bf(kk));
;             const float coef = wsum_dpp(rr * kp * rkc);
;             SV[(ib + t) * 64 + lane] = f2bf(v);
;             if (lane == 0) COEF[(size_t)(m0 + t) * 16 + h] = coef;
;             const float Pp = P; P *= dec; const float inv = 1.0f / P;
;             XKK[t * 72 + lane] = f2bf(kk * Pp); XR[t * 72 + lane] = f2bf(rr * P); XK[t * 72 + lane] = f2bf(kp * inv); XB[t * 72 + lane] = f2bf(bb * inv); }
.Lpcpf_skip_13:
	v_lshlrev_b32_e32 v65, 16, v65
	v_add_f32_e32 v65, v8, v65
	v_mul_f32_e64 v74, |v65|, s19
	v_exp_f32_e32 v74, v74
	v_mov_b32_e32 v75, s8
	v_mov_b32_e32 v76, s9
	v_add_f32_e32 v75, s7, v75
	v_add_f32_e32 v74, 1.0, v74
	v_log_f32_e32 v74, v74
	v_add_f32_e32 v76, s6, v76
	v_max_f32_e64 v65, -v65, 0
	v_add_f32_e32 v75, v75, v76
	v_fmac_f32_e32 v65, 0x3f317218, v74
	v_mul_f32_e32 v74, 0x4f800000, v75
	v_cmp_gt_f32_e32 vcc, s33, v75
	v_sub_f32_e32 v65, -0.5, v65
	v_mul_f32_e32 v65, 0x3fb8aa3b, v65
	v_cndmask_b32_e32 v74, v75, v74, vcc
	v_sqrt_f32_e32 v75, v74
	v_exp_f32_e32 v65, v65
	v_lshlrev_b32_e32 v61, 16, v61
	v_add_f32_e32 v61, v15, v61
	v_add_u32_e32 v76, -1, v75
	v_fma_f32 v77, -v76, v75, v74
	v_cmp_ge_f32_e64 s[56:57], 0, v77
	v_add_u32_e32 v77, 1, v75
	v_mul_f32_e32 v65, 0xbfb8aa3b, v65
	v_cndmask_b32_e64 v76, v75, v76, s[56:57]
	v_fma_f32 v75, -v77, v75, v74
	v_cmp_lt_f32_e64 s[56:57], 0, v75
	v_exp_f32_e32 v65, v65
	v_mul_f32_e32 v61, 0xbfb8aa3b, v61
	v_cndmask_b32_e64 v75, v76, v77, s[56:57]
	v_mul_f32_e32 v76, 0x37800000, v75
	v_cndmask_b32_e32 v75, v75, v76, vcc
	v_cmp_class_f32_e32 vcc, v74, v219
	v_mul_f32_e32 v65, v70, v65
	v_exp_f32_e32 v61, v61
	v_cndmask_b32_e32 v74, v75, v74, vcc
	v_max_f32_e32 v74, 0x2b8cbccc, v74
	v_div_scale_f32 v75, s[0:1], v74, v74, v73
	v_rcp_f32_e32 v76, v75
	v_mul_f32_e32 v69, v65, v69
	v_lshlrev_b32_e32 v63, 16, v63
	v_sub_f32_e32 v67, v67, v63
	v_fma_f32 v77, -v75, v76, 1.0
	v_fmac_f32_e32 v76, v77, v76
	v_div_scale_f32 v77, vcc, v73, v74, v73
	v_mul_f32_e32 v78, v77, v76
	v_fma_f32 v79, -v75, v78, v77
	v_fmac_f32_e32 v78, v79, v76
	v_fma_f32 v75, -v75, v78, v77
	v_div_fmas_f32 v75, v75, v76, v78
	v_div_fixup_f32 v73, v75, v74, v73
	v_mul_f32_e32 v72, v72, v73
	v_cvt_pk_bf16_f32 v72, v72, s0
	v_div_scale_f32 v74, s[0:1], v65, v65, 1.0
	v_rcp_f32_e32 v75, v74
	v_lshlrev_b32_e32 v72, 16, v72
	v_cvt_pk_bf16_f32 v73, v73, s0
	v_lshlrev_b32_e32 v73, 16, v73
	v_fma_f32 v76, -v74, v75, 1.0
	v_fmac_f32_e32 v75, v76, v75
	v_div_scale_f32 v76, vcc, 1.0, v65, 1.0
	v_mul_f32_e32 v77, v76, v75
	v_fma_f32 v78, -v74, v77, v76
	v_fmac_f32_e32 v77, v78, v75
	v_fma_f32 v74, -v74, v77, v76
	v_div_fmas_f32 v74, v74, v75, v77
	v_div_fixup_f32 v74, v74, v65, 1.0
	v_mul_f32_e32 v68, v74, v68
	v_cvt_pk_bf16_f32 v68, v68, s0
	ds_write_b16 v27, v68 offset:6480
	v_mul_f32_e32 v68, v74, v72
	v_cvt_pk_bf16_f32 v69, v69, s0
	v_cvt_pk_bf16_f32 v68, v68, s0
	v_mul_f32_e32 v70, v70, v73
	ds_write_b16 v27, v69 offset:4176
	ds_write_b16 v27, v68 offset:8784
	v_lshlrev_b32_e32 v68, 16, v62
	v_lshlrev_b32_e32 v62, 16, v64
	v_fma_f32 v69, v9, v67, v63
	v_cvt_pk_bf16_f32 v70, v70, s0
	v_sub_f32_e32 v66, v66, v62
	v_add_f32_e32 v61, 1.0, v61
	v_mul_f32_e32 v67, v14, v69
	ds_write_b16 v27, v70 offset:1872
	v_fma_f32 v70, v12, v66, v62
	v_rcp_f32_e32 v66, v61
	v_mul_f32_e32 v61, v67, v67
	v_sub_f32_e32 v64, v71, v68
	v_fma_f32 v64, v10, v64, v68
	v_mov_b32_dpp v61, v61 quad_perm:[1,0,3,2] row_mask:0xf bank_mask:0xf bound_ctrl:1
	v_fmac_f32_e32 v61, v67, v67
	v_cvt_pk_bf16_f32 v64, v64, s0
	v_lshlrev_b32_e32 v64, 16, v64
	v_add_f32_dpp v61, v61, v61 quad_perm:[2,3,0,1] row_mask:0xf bank_mask:0xf bound_ctrl:1
	s_nop 1
	v_add_f32_dpp v61, v61, v61 row_ror:4 row_mask:0xf bank_mask:0xf bound_ctrl:1
	s_nop 1
	v_add_f32_dpp v61, v61, v61 row_ror:8 row_mask:0xf bank_mask:0xf bound_ctrl:1
	s_nop 0
	v_readlane_b32 s7, v61, 0
	v_readlane_b32 s8, v61, 16
	v_readlane_b32 s6, v61, 32
	v_readlane_b32 s9, v61, 48
	v_add_f32_e32 v61, -1.0, v66
	v_fma_f32 v61, v13, v61, 1.0
	v_mul_f32_e32 v61, v69, v61
	v_cvt_pk_bf16_f32 v61, v61, s0
	v_lshlrev_b32_e32 v61, 16, v61
	v_mul_f32_e32 v69, v64, v61
	v_mul_f32_e32 v71, v11, v69
	s_nop 1
	v_mov_b32_dpp v71, v71 quad_perm:[1,0,3,2] row_mask:0xf bank_mask:0xf bound_ctrl:1
	v_fmac_f32_e32 v71, v11, v69
	s_nop 1
	v_add_f32_dpp v69, v71, v71 quad_perm:[2,3,0,1] row_mask:0xf bank_mask:0xf bound_ctrl:1
	s_nop 1
	v_add_f32_dpp v69, v69, v69 row_ror:4 row_mask:0xf bank_mask:0xf bound_ctrl:1
	s_nop 1
	v_add_f32_dpp v69, v69, v69 row_ror:8 row_mask:0xf bank_mask:0xf bound_ctrl:1
	s_nop 0
	v_readlane_b32 s0, v69, 0
	v_readlane_b32 s15, v69, 16
	v_readlane_b32 s1, v69, 32
	v_readlane_b32 s17, v69, 48
	v_cvt_pk_bf16_f32 v69, v70, s0
	v_add_co_u32_e32 v70, vcc, 0x33600000, v6
	s_nop 1
	v_addc_co_u32_e32 v71, vcc, 0, v7, vcc
	global_store_short v[70:71], v69, off offset:1792
	s_and_saveexec_b64 s[4:5], s[38:39]
	s_cbranch_execz .LBB0_311
	s_ashr_i32 s77, s76, 31
	s_lshl_b64 s[30:31], s[76:77], 6
	s_add_u32 s30, s2, s30
	v_mov_b32_e32 v70, s15
	v_mov_b32_e32 v71, s17
	s_addc_u32 s31, s14, s31
	v_pk_add_f32 v[70:71], s[0:1], v[70:71]
	v_readlane_b32 s77, v254, 56
	v_add_f32_e32 v69, v70, v71
	v_mov_b64_e32 v[70:71], s[30:31]
	global_store_dword v[70:71], v69, off
; __device__ __forceinline__ float bf2f(bf16 b) { return __uint_as_float((unsigned)b << 16); }
; __device__ __forceinline__ bf16 f2bf(float f) { return (bf16)(pk_bf16(f, 0.f) & 0xffffu); }
; __device__ __forceinline__ float fexp(float x) { return __builtin_amdgcn_exp2f(x * 1.4426950408889634f); }
; __device__ __forceinline__ float flog(float x) { return __builtin_amdgcn_logf(x) * 0.6931471805599453f; }
; __device__ __forceinline__ float fsigmoid(float x) { return __builtin_amdgcn_rcpf(1.0f + fexp(-x)); }
; __device__ __forceinline__ void pc_phase(LAS unsigned char* lds, const bf16* Pp_, const bf16* LO, const float* mu, const float* w0, const float* a0, const float* k_k, const float* k_a, const float* r_k, ...
;     ...
;         for (int t = 0; t < 16; ++t) {
;             const float r0 = bf2f(sr_[t + 1]), k0 = bf2f(sk_[t + 1]), v0 = bf2f(sv_[t + 1]);
;             const float r = r0 + (r1 - r0) * mu_r, k = k0 + (k1 - k0) * mu_k, v = v0 + (v1 - v0) * mu_v; r1 = r0; k1 = k0; v1 = v0;
;             const float z = -(w0c + bf2f(slw[t])); const float sp = fmaxf(z, 0.f) + flog(1.0f + fexp(-fabsf(z))); const float w = -sp - 0.5f;
;             const float dec = fexp(-fexp(w)); const float a = fsigmoid(a0c + bf2f(sla[t]));
;             float kk = k * kkc; const float n2 = wsum_dpp(kk * kk); kk = kk / fmaxf(sqrtf(n2), 1e-12f);
;             const float kp = bf2f(f2bf(k * (1.0f + (a - 1.0f) * kac))), bb = bf2f(f2bf(kk * a)), rr = bf2f(f2bf(r)); kk = bf2f(f2bf(kk));
;             const float coef = wsum_dpp(rr * kp * rkc);
;             SV[(ib + t) * 64 + lane] = f2bf(v);
;             if (lane == 0) COEF[(size_t)(m0 + t) * 16 + h] = coef;
;             const float Pp = P; P *= dec; const float inv = 1.0f / P;
;             XKK[t * 72 + lane] = f2bf(kk * Pp); XR[t * 72 + lane] = f2bf(rr * P); XK[t * 72 + lane] = f2bf(kp * inv); XB[t * 72 + lane] = f2bf(bb * inv); }
.LBB0_311:
	s_or_b64 exec, exec, s[4:5]
	s_add_i32 s0, s11, s16
	s_cmpk_gt_i32 s0, 0x3fff
	s_cbranch_scc1 .Lpcpf_skip_14
	s_movk_i32 s0, 0x3400
	s_mov_b32 s1, 0
	v_lshl_add_u64 v[146:147], v[146:147], 0, s[0:1]
	s_movk_i32 s0, 0x1800
	v_lshl_add_u64 v[148:149], v[148:149], 0, s[0:1]
	global_load_ushort v184, v[146:147], off offset:-2048
	global_load_ushort v187, v[146:147], off
	global_load_ushort v188, v[146:147], off offset:2048
	global_load_ushort v189, v[148:149], off
	global_load_ushort v190, v[148:149], off offset:2048
	s_movk_i32 s0, 0x3400
	s_mov_b32 s1, 0
	v_lshl_add_u64 v[146:147], v[146:147], 0, s[0:1]
	s_movk_i32 s0, 0x1800
	v_lshl_add_u64 v[148:149], v[148:149], 0, s[0:1]
	global_load_ushort v191, v[146:147], off offset:-2048
	global_load_ushort v192, v[146:147], off
	global_load_ushort v193, v[146:147], off offset:2048
	global_load_ushort v202, v[148:149], off
	global_load_ushort v203, v[148:149], off offset:2048
.Lpcpf_skip_14:
	v_lshlrev_b32_e32 v21, 16, v21
	v_add_f32_e32 v21, v8, v21
	v_mul_f32_e64 v69, |v21|, s19
	v_exp_f32_e32 v69, v69
	v_mov_b32_e32 v70, s8
	v_mov_b32_e32 v71, s9
	v_add_f32_e32 v70, s7, v70
	v_add_f32_e32 v69, 1.0, v69
	v_log_f32_e32 v69, v69
	v_add_f32_e32 v71, s6, v71
	v_max_f32_e64 v21, -v21, 0
	v_add_f32_e32 v70, v70, v71
	v_fmac_f32_e32 v21, 0x3f317218, v69
	v_mul_f32_e32 v69, 0x4f800000, v70
	v_cmp_gt_f32_e32 vcc, s33, v70
	v_sub_f32_e32 v21, -0.5, v21
	v_mul_f32_e32 v21, 0x3fb8aa3b, v21
	v_cndmask_b32_e32 v69, v70, v69, vcc
	v_sqrt_f32_e32 v70, v69
	v_exp_f32_e32 v21, v21
	v_lshlrev_b32_e32 v17, 16, v17
	v_add_f32_e32 v15, v15, v17
	v_add_u32_e32 v71, -1, v70
	v_fma_f32 v72, -v71, v70, v69
	v_cmp_ge_f32_e64 s[56:57], 0, v72
	v_add_u32_e32 v72, 1, v70
	v_mul_f32_e32 v21, 0xbfb8aa3b, v21
	v_cndmask_b32_e64 v71, v70, v71, s[56:57]
	v_fma_f32 v70, -v72, v70, v69
	v_cmp_lt_f32_e64 s[56:57], 0, v70
	v_exp_f32_e32 v21, v21
	v_mul_f32_e32 v15, 0xbfb8aa3b, v15
	v_cndmask_b32_e64 v70, v71, v72, s[56:57]
	v_mul_f32_e32 v71, 0x37800000, v70
	v_cndmask_b32_e32 v70, v70, v71, vcc
	v_cmp_class_f32_e32 vcc, v69, v219
	v_mul_f32_e32 v21, v65, v21
	v_lshlrev_b32_e32 v18, 16, v18
	v_cndmask_b32_e32 v69, v70, v69, vcc
	v_max_f32_e32 v69, 0x2b8cbccc, v69
	v_div_scale_f32 v70, s[0:1], v69, v69, v67
	v_rcp_f32_e32 v71, v70
	v_exp_f32_e32 v15, v15
	v_lshlrev_b32_e32 v19, 16, v19
	v_lshlrev_b32_e32 v20, 16, v20
	v_fma_f32 v72, -v70, v71, 1.0
	v_fmac_f32_e32 v71, v72, v71
	v_div_scale_f32 v72, vcc, v67, v69, v67
	v_mul_f32_e32 v73, v72, v71
	v_fma_f32 v74, -v70, v73, v72
	v_fmac_f32_e32 v73, v74, v71
	v_fma_f32 v70, -v70, v73, v72
	v_div_fmas_f32 v70, v70, v71, v73
	v_div_fixup_f32 v67, v70, v69, v67
	v_mul_f32_e32 v66, v66, v67
	v_cvt_pk_bf16_f32 v66, v66, s0
	v_div_scale_f32 v69, s[0:1], v21, v21, 1.0
	v_rcp_f32_e32 v70, v69
	v_lshlrev_b32_e32 v66, 16, v66
	v_cvt_pk_bf16_f32 v67, v67, s0
	v_lshlrev_b32_e32 v67, 16, v67
	v_fma_f32 v71, -v69, v70, 1.0
	v_fmac_f32_e32 v70, v71, v70
	v_div_scale_f32 v71, vcc, 1.0, v21, 1.0
	v_mul_f32_e32 v72, v71, v70
	v_fma_f32 v73, -v69, v72, v71
	v_fmac_f32_e32 v72, v73, v70
	v_fma_f32 v69, -v69, v72, v71
	v_div_fmas_f32 v69, v69, v70, v72
	v_div_fixup_f32 v69, v69, v21, 1.0
	v_mul_f32_e32 v61, v69, v61
	v_cvt_pk_bf16_f32 v61, v61, s0
	ds_write_b16 v27, v61 offset:6624
	v_mul_f32_e32 v61, v69, v66
	v_cvt_pk_bf16_f32 v61, v61, s0
	ds_write_b16 v27, v61 offset:8928
	v_sub_f32_e32 v61, v68, v18
	v_fmac_f32_e32 v18, v10, v61
	v_sub_f32_e32 v10, v63, v19
	v_fmac_f32_e32 v19, v9, v10
	v_sub_f32_e32 v9, v62, v20
	v_fmac_f32_e32 v20, v12, v9
	v_add_f32_e32 v9, 1.0, v15
	v_mul_f32_e32 v14, v14, v19
	v_rcp_f32_e32 v12, v9
	v_mul_f32_e32 v9, v14, v14
	v_cvt_pk_bf16_f32 v10, v18, s0
	v_lshlrev_b32_e32 v10, 16, v10
	v_mov_b32_dpp v9, v9 quad_perm:[1,0,3,2] row_mask:0xf bank_mask:0xf bound_ctrl:1
	v_fmac_f32_e32 v9, v14, v14
	v_mul_f32_e32 v65, v65, v67
	v_mul_f32_e32 v64, v21, v64
	v_add_f32_dpp v9, v9, v9 quad_perm:[2,3,0,1] row_mask:0xf bank_mask:0xf bound_ctrl:1
	v_cvt_pk_bf16_f32 v65, v65, s0
	v_cvt_pk_bf16_f32 v64, v64, s0
	v_add_f32_dpp v9, v9, v9 row_ror:4 row_mask:0xf bank_mask:0xf bound_ctrl:1
	v_add_co_u32_e32 v6, vcc, 0x33600000, v6
	s_nop 0
	v_add_f32_dpp v9, v9, v9 row_ror:8 row_mask:0xf bank_mask:0xf bound_ctrl:1
	v_addc_co_u32_e32 v7, vcc, 0, v7, vcc
	v_readlane_b32 s7, v9, 0
	v_readlane_b32 s9, v9, 16
	v_readlane_b32 s6, v9, 32
	v_readlane_b32 s8, v9, 48
	v_add_f32_e32 v9, -1.0, v12
	v_fma_f32 v9, v13, v9, 1.0
	v_mul_f32_e32 v9, v19, v9
	v_cvt_pk_bf16_f32 v9, v9, s0
	v_lshlrev_b32_e32 v9, 16, v9
	v_mul_f32_e32 v13, v10, v9
	v_mul_f32_e32 v15, v11, v13
	ds_write_b16 v27, v65 offset:2016
	ds_write_b16 v27, v64 offset:4320
	v_mov_b32_dpp v15, v15 quad_perm:[1,0,3,2] row_mask:0xf bank_mask:0xf bound_ctrl:1
	v_fmac_f32_e32 v15, v11, v13
	s_nop 1
	v_add_f32_dpp v11, v15, v15 quad_perm:[2,3,0,1] row_mask:0xf bank_mask:0xf bound_ctrl:1
	s_nop 1
	v_add_f32_dpp v11, v11, v11 row_ror:4 row_mask:0xf bank_mask:0xf bound_ctrl:1
	s_nop 1
	v_add_f32_dpp v11, v11, v11 row_ror:8 row_mask:0xf bank_mask:0xf bound_ctrl:1
	s_nop 0
	v_readlane_b32 s0, v11, 0
	v_readlane_b32 s15, v11, 16
	v_readlane_b32 s1, v11, 32
	v_readlane_b32 s17, v11, 48
	v_cvt_pk_bf16_f32 v11, v20, s0
	global_store_short v[6:7], v11, off offset:1920
	s_and_saveexec_b64 s[4:5], s[38:39]
	s_cbranch_execz .LBB0_280
	s_mov_b32 s34, s75
	s_ashr_i32 s75, s74, 31
	s_lshl_b64 s[30:31], s[74:75], 6
	s_add_u32 s30, s2, s30
	v_mov_b32_e32 v6, s15
	v_mov_b32_e32 v7, s17
	s_addc_u32 s31, s14, s31
	v_pk_add_f32 v[6:7], s[0:1], v[6:7]
	s_mov_b32 s75, s34
	v_add_f32_e32 v11, v6, v7
	v_mov_b64_e32 v[6:7], s[30:31]
	global_store_dword v[6:7], v11, off
	s_branch .LBB0_280
